# 6 GEMM loops (FFN-in x4, AB-in, HG-in): accumulator zeroing removed, first K-iteration peeled with C=0 on the first MFMA into each accumulator
# speedup vs baseline: 1.0102x; 1.0055x over previous
; #define PG8_STAGE(bufoff, gbase, voff) do { _Pragma("unroll") for (int _i = 0; _i < 2; ++_i) \
;         __builtin_amdgcn_global_load_lds((const unsigned*)((const char*)(gbase) + (voff)[_i]), (PG8_LAS unsigned*)(lds + (bufoff) + ldsw + _i * 8192), 16, 0, 0); } while (0)
; #define PG8_LDA(dst, b, h) do { _Pragma("unroll") for (int m = 0; m < 4; ++m) _Pragma("unroll") for (int k = 0; k < 2; ++k) dst[m][k] = *(const PG8_LAS bf16x8*)(lds + PG8_SA(b, h) + aoff + m * 2048 + k * 1024); } while (0)
; #define PG8_LDB(dst, b, h) do { _Pragma("unroll") for (int n = 0; n < 2; ++n) _Pragma("unroll") for (int k = 0; k < 2; ++k) dst[n][k] = *(const PG8_LAS bf16x8*)(lds + PG8_SB(b, h) + boff + n * 2048 + k * 1024); } while (0)
; #define PG8_MMA(ai, bj, At, Bt) do { __builtin_amdgcn_s_setprio(1); _Pragma("unroll") for (int m = 0; m < 4; ++m) _Pragma("unroll") for (int n = 0; n < 2; ++n) _Pragma("unroll") for (int k = 0; k < 2; ++k) \
;         acc[ai][bj][m][n] = __builtin_amdgcn_mfma_f32_16x16x32_bf16(Bt[n][k], At[m][k], acc[ai][bj][m][n], 0, 0, 0); __builtin_amdgcn_s_setprio(0); } while (0)
; #define PG8_WAIT_V(n) asm volatile("s_waitcnt vmcnt(" #n ")" ::: "memory")
; #define PG8_WAIT_L(n) asm volatile("s_waitcnt lgkmcnt(" #n ")" ::: "memory")
; #define PG8_BAR __builtin_amdgcn_s_barrier()
; template <class Epi, class Sched, bool ALIGN_EPI = false, bool SP2 = false>
; __device__ __forceinline__ void gemm_phase(PG8_LAS unsigned char* lds, const Gemm g, const Sched& S, const Epi& E) {
;     ...
;     f32x4 acc[2][2][4][2];
; #pragma unroll
;     for (int a = 0; a < 2; ++a)
; #pragma unroll
;         for (int b = 0; b < 2; ++b)
; #pragma unroll
;             for (int m = 0; m < 4; ++m)
; #pragma unroll
;                 for (int n = 0; n < 2; ++n) acc[a][b][m][n] = (f32x4){0.f, 0.f, 0.f, 0.f};
;     ...
;             if constexpr (SP2) {
;             PG8_LDB(B0, 0, 0); PG8_LDB(B1, 0, 1); PG8_SCHED; PG8_LDA(At, 0, 0); PG8_STAGE(PG8_SA(1, 1), a1 + hstepA, voffA);
;             PG8_WAIT_V(8); PG8_WAIT_L(0); PG8_BAR; PG8_MMA(0, 0, At, B0); PG8_MMA(0, 1, At, B1); PG8_BAR; PG8_SCHED;
;             PG8_LDA(At, 0, 1); PG8_STAGE(PG8_SB(0, 0), b2, voffB); PG8_STAGE(PG8_SB(0, 1), b2 + hstepB, voffB); PG8_STAGE(PG8_SA(0, 0), a2, voffA);
;             PG8_WAIT_V(8); PG8_WAIT_L(0); PG8_BAR; PG8_MMA(1, 0, At, B0); PG8_MMA(1, 1, At, B1); PG8_BAR; PG8_SCHED;
.LBB0_299:
	s_ashr_i32 s43, s42, 31
	s_lshl_b64 s[4:5], s[42:43], 20
	v_readlane_b32 s12, v254, 41
	v_readlane_b32 s13, v254, 42
	s_add_u32 s46, s12, s4
	s_addc_u32 s47, s13, s5
	s_and_b64 s[4:5], s[34:35], exec
	s_cselect_b32 s4, s47, s51
	s_cselect_b32 s5, s46, s50
	s_ashr_i32 s41, s40, 31
	s_lshl_b64 s[12:13], s[40:41], 20
	v_readlane_b32 s14, v253, 24
	s_add_u32 s48, s14, s12
	v_readlane_b32 s12, v253, 25
	s_addc_u32 s49, s12, s13
	s_and_b64 s[12:13], s[34:35], exec
	s_cselect_b32 s12, s49, s57
	s_cselect_b32 s13, s48, s56
	s_add_u32 s50, s50, 0x80080
	s_addc_u32 s51, s51, 0
	s_add_u32 s41, s56, 0x100
	s_addc_u32 s43, s57, 0
	s_mov_b32 s61, -2
	ds_read_b128 v[156:159], v152
	ds_read_b128 v[160:163], v152 offset:1024
	ds_read_b128 v[164:167], v152 offset:2048
	ds_read_b128 v[168:171], v152 offset:3072
	ds_read_b128 v[172:175], v153
	ds_read_b128 v[176:179], v153 offset:1024
	ds_read_b128 v[180:183], v153 offset:2048
	ds_read_b128 v[186:189], v153 offset:3072
	s_add_u32 s56, s50, 0xfff80080
	s_addc_u32 s57, s51, -1
	s_cmp_eq_u32 s61, 28
	s_cselect_b32 s59, s4, s57
	s_cselect_b32 s58, s5, s56
	s_cselect_b32 s57, s12, s43
	s_cselect_b32 s56, s13, s41
	v_lshl_add_u64 v[222:223], s[50:51], 0, v[142:143]
	s_add_i32 m0, s6, 0xc000
	ds_read_b128 v[190:193], v154
	ds_read_b128 v[194:197], v154 offset:1024
	ds_read_b128 v[198:201], v154 offset:2048
	ds_read_b128 v[202:205], v154 offset:3072
	ds_read_b128 v[206:209], v154 offset:4096
	ds_read_b128 v[210:213], v154 offset:5120
	ds_read_b128 v[214:217], v154 offset:6144
	ds_read_b128 v[218:221], v154 offset:7168
	global_load_lds_dwordx4 v[222:223], off
	v_lshl_add_u64 v[222:223], s[50:51], 0, v[144:145]
	s_add_i32 m0, s6, 0xe000
	s_nop 0
	global_load_lds_dwordx4 v[222:223], off
	s_waitcnt vmcnt(8)
	s_waitcnt lgkmcnt(0)
	s_setprio 1
	s_barrier
	v_mfma_f32_16x16x32_bf16 v[124:127], v[156:159], v[190:193], 0
	v_mfma_f32_16x16x32_bf16 v[120:123], v[164:167], v[190:193], 0
	v_mfma_f32_16x16x32_bf16 v[108:111], v[156:159], v[198:201], 0
	v_mfma_f32_16x16x32_bf16 v[104:107], v[164:167], v[198:201], 0
	v_mfma_f32_16x16x32_bf16 v[92:95], v[156:159], v[206:209], 0
	v_mfma_f32_16x16x32_bf16 v[88:91], v[164:167], v[206:209], 0
	v_mfma_f32_16x16x32_bf16 v[76:79], v[156:159], v[214:217], 0
	v_mfma_f32_16x16x32_bf16 v[72:75], v[164:167], v[214:217], 0
	v_mfma_f32_16x16x32_bf16 v[124:127], v[160:163], v[194:197], v[124:127]
	v_mfma_f32_16x16x32_bf16 v[120:123], v[168:171], v[194:197], v[120:123]
	v_mfma_f32_16x16x32_bf16 v[108:111], v[160:163], v[202:205], v[108:111]
	v_mfma_f32_16x16x32_bf16 v[104:107], v[168:171], v[202:205], v[104:107]
	v_mfma_f32_16x16x32_bf16 v[92:95], v[160:163], v[210:213], v[92:95]
	v_mfma_f32_16x16x32_bf16 v[88:91], v[168:171], v[210:213], v[88:91]
	v_mfma_f32_16x16x32_bf16 v[76:79], v[160:163], v[218:221], v[76:79]
	v_mfma_f32_16x16x32_bf16 v[72:75], v[168:171], v[218:221], v[72:75]
	s_setprio 0
	s_setprio 1
	v_mfma_f32_16x16x32_bf16 v[116:119], v[172:175], v[190:193], 0
	v_mfma_f32_16x16x32_bf16 v[112:115], v[180:183], v[190:193], 0
	v_mfma_f32_16x16x32_bf16 v[100:103], v[172:175], v[198:201], 0
	v_mfma_f32_16x16x32_bf16 v[96:99], v[180:183], v[198:201], 0
	v_mfma_f32_16x16x32_bf16 v[84:87], v[172:175], v[206:209], 0
	v_mfma_f32_16x16x32_bf16 v[80:83], v[180:183], v[206:209], 0
	v_mfma_f32_16x16x32_bf16 v[68:71], v[172:175], v[214:217], 0
	v_mfma_f32_16x16x32_bf16 v[64:67], v[180:183], v[214:217], 0
	v_mfma_f32_16x16x32_bf16 v[116:119], v[176:179], v[194:197], v[116:119]
	v_mfma_f32_16x16x32_bf16 v[112:115], v[186:189], v[194:197], v[112:115]
	v_mfma_f32_16x16x32_bf16 v[100:103], v[176:179], v[202:205], v[100:103]
	v_mfma_f32_16x16x32_bf16 v[96:99], v[186:189], v[202:205], v[96:99]
	v_mfma_f32_16x16x32_bf16 v[84:87], v[176:179], v[210:213], v[84:87]
	v_mfma_f32_16x16x32_bf16 v[80:83], v[186:189], v[210:213], v[80:83]
	v_mfma_f32_16x16x32_bf16 v[68:71], v[176:179], v[218:221], v[68:71]
	v_mfma_f32_16x16x32_bf16 v[64:67], v[186:189], v[218:221], v[64:67]
	s_barrier
	s_setprio 0
	s_add_i32 s62, s53, s3
	v_lshl_add_u64 v[222:223], s[56:57], 0, v[130:131]
	s_mov_b32 m0, s62
	ds_read_b128 v[190:193], v154 offset:16384
	ds_read_b128 v[194:197], v154 offset:17408
	ds_read_b128 v[198:201], v154 offset:18432
	ds_read_b128 v[202:205], v154 offset:19456
	ds_read_b128 v[206:209], v154 offset:20480
	ds_read_b128 v[210:213], v154 offset:21504
	ds_read_b128 v[214:217], v154 offset:22528
	ds_read_b128 v[218:221], v154 offset:23552
	global_load_lds_dwordx4 v[222:223], off
	s_add_i32 m0, s62, 0x2000
	s_add_u32 s62, s56, 0x80000
	v_lshl_add_u64 v[224:225], s[56:57], 0, v[134:135]
	s_addc_u32 s63, s57, 0
	s_add_i32 s64, s55, s3
	global_load_lds_dwordx4 v[224:225], off
	v_lshl_add_u64 v[226:227], s[62:63], 0, v[130:131]
	s_mov_b32 m0, s64
	v_lshl_add_u64 v[228:229], s[58:59], 0, v[132:133]
	global_load_lds_dwordx4 v[226:227], off
	v_lshl_add_u64 v[226:227], s[62:63], 0, v[134:135]
	s_add_i32 m0, s64, 0x2000
	s_nop 0
	global_load_lds_dwordx4 v[226:227], off
	v_lshl_add_u64 v[226:227], s[58:59], 0, v[128:129]
	s_mov_b32 m0, s6
	s_nop 0
	global_load_lds_dwordx4 v[226:227], off
	s_mov_b32 m0, s7
	s_nop 0
	global_load_lds_dwordx4 v[228:229], off
	s_waitcnt vmcnt(8)
	s_waitcnt lgkmcnt(0)
	s_setprio 1
	s_barrier
; #define PG8_STAGE(bufoff, gbase, voff) do { _Pragma("unroll") for (int _i = 0; _i < 2; ++_i) \
;         __builtin_amdgcn_global_load_lds((const unsigned*)((const char*)(gbase) + (voff)[_i]), (PG8_LAS unsigned*)(lds + (bufoff) + ldsw + _i * 8192), 16, 0, 0); } while (0)
; #define PG8_LDA(dst, b, h) do { _Pragma("unroll") for (int m = 0; m < 4; ++m) _Pragma("unroll") for (int k = 0; k < 2; ++k) dst[m][k] = *(const PG8_LAS bf16x8*)(lds + PG8_SA(b, h) + aoff + m * 2048 + k * 1024); } while (0)
; #define PG8_LDB(dst, b, h) do { _Pragma("unroll") for (int n = 0; n < 2; ++n) _Pragma("unroll") for (int k = 0; k < 2; ++k) dst[n][k] = *(const PG8_LAS bf16x8*)(lds + PG8_SB(b, h) + boff + n * 2048 + k * 1024); } while (0)
; #define PG8_MMA(ai, bj, At, Bt) do { __builtin_amdgcn_s_setprio(1); _Pragma("unroll") for (int m = 0; m < 4; ++m) _Pragma("unroll") for (int n = 0; n < 2; ++n) _Pragma("unroll") for (int k = 0; k < 2; ++k) \
;         acc[ai][bj][m][n] = __builtin_amdgcn_mfma_f32_16x16x32_bf16(Bt[n][k], At[m][k], acc[ai][bj][m][n], 0, 0, 0); __builtin_amdgcn_s_setprio(0); } while (0)
; #define PG8_WAIT_V(n) asm volatile("s_waitcnt vmcnt(" #n ")" ::: "memory")
; #define PG8_WAIT_L(n) asm volatile("s_waitcnt lgkmcnt(" #n ")" ::: "memory")
; #define PG8_BAR __builtin_amdgcn_s_barrier()
; #define PG8_SCHED __builtin_amdgcn_sched_barrier(0)
; template <class Epi, class Sched, bool ALIGN_EPI = false, bool SP2 = false>
; __device__ __forceinline__ void gemm_phase(PG8_LAS unsigned char* lds, const Gemm g, const Sched& S, const Epi& E) {
;     ...
;             if constexpr (SP2) {
;             PG8_LDB(B0, 0, 0); PG8_LDB(B1, 0, 1); PG8_SCHED; PG8_LDA(At, 0, 0); PG8_STAGE(PG8_SA(1, 1), a1 + hstepA, voffA);
;             PG8_WAIT_V(8); PG8_WAIT_L(0); PG8_BAR; PG8_MMA(0, 0, At, B0); PG8_MMA(0, 1, At, B1); PG8_BAR; PG8_SCHED;
;             PG8_LDA(At, 0, 1); PG8_STAGE(PG8_SB(0, 0), b2, voffB); PG8_STAGE(PG8_SB(0, 1), b2 + hstepB, voffB); PG8_STAGE(PG8_SA(0, 0), a2, voffA);
;             PG8_WAIT_V(8); PG8_WAIT_L(0); PG8_BAR; PG8_MMA(1, 0, At, B0); PG8_MMA(1, 1, At, B1); PG8_BAR; PG8_SCHED;
;             PG8_LDB(B0, 1, 0); PG8_LDB(B1, 1, 1); PG8_SCHED; PG8_LDA(At, 1, 0); PG8_STAGE(PG8_SA(0, 1), a2 + hstepA, voffA);
;             PG8_WAIT_V(8); PG8_WAIT_L(0); PG8_BAR; PG8_MMA(0, 0, At, B0); PG8_MMA(0, 1, At, B1); PG8_BAR; PG8_SCHED;
	v_mfma_f32_16x16x32_bf16 v[60:63], v[156:159], v[190:193], 0
	v_mfma_f32_16x16x32_bf16 v[56:59], v[164:167], v[190:193], 0
	v_mfma_f32_16x16x32_bf16 v[44:47], v[156:159], v[198:201], 0
	v_mfma_f32_16x16x32_bf16 v[40:43], v[164:167], v[198:201], 0
	v_mfma_f32_16x16x32_bf16 v[28:31], v[156:159], v[206:209], 0
	v_mfma_f32_16x16x32_bf16 v[24:27], v[164:167], v[206:209], 0
	v_mfma_f32_16x16x32_bf16 v[12:15], v[156:159], v[214:217], 0
	v_mfma_f32_16x16x32_bf16 v[8:11], v[164:167], v[214:217], 0
	v_mfma_f32_16x16x32_bf16 v[60:63], v[160:163], v[194:197], v[60:63]
	v_mfma_f32_16x16x32_bf16 v[56:59], v[168:171], v[194:197], v[56:59]
	v_mfma_f32_16x16x32_bf16 v[44:47], v[160:163], v[202:205], v[44:47]
	v_mfma_f32_16x16x32_bf16 v[40:43], v[168:171], v[202:205], v[40:43]
	v_mfma_f32_16x16x32_bf16 v[28:31], v[160:163], v[210:213], v[28:31]
	v_mfma_f32_16x16x32_bf16 v[24:27], v[168:171], v[210:213], v[24:27]
	v_mfma_f32_16x16x32_bf16 v[12:15], v[160:163], v[218:221], v[12:15]
	v_mfma_f32_16x16x32_bf16 v[8:11], v[168:171], v[218:221], v[8:11]
	s_setprio 0
	s_setprio 1
	v_mfma_f32_16x16x32_bf16 v[52:55], v[172:175], v[190:193], 0
	v_mfma_f32_16x16x32_bf16 v[48:51], v[180:183], v[190:193], 0
	v_mfma_f32_16x16x32_bf16 v[36:39], v[172:175], v[198:201], 0
	v_mfma_f32_16x16x32_bf16 v[32:35], v[180:183], v[198:201], 0
	v_mfma_f32_16x16x32_bf16 v[20:23], v[172:175], v[206:209], 0
	v_mfma_f32_16x16x32_bf16 v[16:19], v[180:183], v[206:209], 0
	v_mfma_f32_16x16x32_bf16 v[4:7], v[172:175], v[214:217], 0
	v_mfma_f32_16x16x32_bf16 v[0:3], v[180:183], v[214:217], 0
	v_mfma_f32_16x16x32_bf16 v[52:55], v[176:179], v[194:197], v[52:55]
	v_mfma_f32_16x16x32_bf16 v[48:51], v[186:189], v[194:197], v[48:51]
	v_mfma_f32_16x16x32_bf16 v[36:39], v[176:179], v[202:205], v[36:39]
	v_mfma_f32_16x16x32_bf16 v[32:35], v[186:189], v[202:205], v[32:35]
	v_mfma_f32_16x16x32_bf16 v[20:23], v[176:179], v[210:213], v[20:23]
	v_mfma_f32_16x16x32_bf16 v[16:19], v[186:189], v[210:213], v[16:19]
	v_mfma_f32_16x16x32_bf16 v[4:7], v[176:179], v[218:221], v[4:7]
	v_mfma_f32_16x16x32_bf16 v[0:3], v[186:189], v[218:221], v[0:3]
	s_barrier
	s_setprio 0
	s_add_i32 s62, 0, 0x18000
	v_add_u32_e32 v155, s62, v150
	s_add_i32 s63, 0, 0x1c000
	ds_read_b128 v[156:159], v155
	ds_read_b128 v[160:163], v155 offset:1024
	ds_read_b128 v[164:167], v155 offset:2048
	ds_read_b128 v[168:171], v155 offset:3072
	v_add_u32_e32 v155, s63, v150
	ds_read_b128 v[172:175], v155
	ds_read_b128 v[176:179], v155 offset:1024
	ds_read_b128 v[180:183], v155 offset:2048
	ds_read_b128 v[186:189], v155 offset:3072
	s_add_u32 s58, s58, 0x80000
	s_addc_u32 s59, s59, 0
	s_mov_b32 m0, s8
	v_lshl_add_u64 v[230:231], s[58:59], 0, v[128:129]
	ds_read_b128 v[190:193], v154 offset:32768
	ds_read_b128 v[194:197], v154 offset:33792
	ds_read_b128 v[198:201], v154 offset:34816
	ds_read_b128 v[202:205], v154 offset:35840
	ds_read_b128 v[206:209], v154 offset:36864
	ds_read_b128 v[210:213], v154 offset:37888
	ds_read_b128 v[214:217], v154 offset:38912
	ds_read_b128 v[218:221], v154 offset:39936
	global_load_lds_dwordx4 v[230:231], off
	v_lshl_add_u64 v[230:231], s[58:59], 0, v[132:133]
	s_mov_b32 m0, s9
	s_nop 0
	global_load_lds_dwordx4 v[230:231], off
	s_waitcnt vmcnt(8)
	s_waitcnt lgkmcnt(0)
	s_setprio 1
	s_barrier
	v_mfma_f32_16x16x32_bf16 v[124:127], v[156:159], v[190:193], v[124:127]
	v_mfma_f32_16x16x32_bf16 v[120:123], v[164:167], v[190:193], v[120:123]
	v_mfma_f32_16x16x32_bf16 v[108:111], v[156:159], v[198:201], v[108:111]
	v_mfma_f32_16x16x32_bf16 v[104:107], v[164:167], v[198:201], v[104:107]
	v_mfma_f32_16x16x32_bf16 v[92:95], v[156:159], v[206:209], v[92:95]
	v_mfma_f32_16x16x32_bf16 v[88:91], v[164:167], v[206:209], v[88:91]
	v_mfma_f32_16x16x32_bf16 v[76:79], v[156:159], v[214:217], v[76:79]
	v_mfma_f32_16x16x32_bf16 v[72:75], v[164:167], v[214:217], v[72:75]
	v_mfma_f32_16x16x32_bf16 v[124:127], v[160:163], v[194:197], v[124:127]
	v_mfma_f32_16x16x32_bf16 v[120:123], v[168:171], v[194:197], v[120:123]
	v_mfma_f32_16x16x32_bf16 v[108:111], v[160:163], v[202:205], v[108:111]
	v_mfma_f32_16x16x32_bf16 v[104:107], v[168:171], v[202:205], v[104:107]
	v_mfma_f32_16x16x32_bf16 v[92:95], v[160:163], v[210:213], v[92:95]
	v_mfma_f32_16x16x32_bf16 v[88:91], v[168:171], v[210:213], v[88:91]
	v_mfma_f32_16x16x32_bf16 v[76:79], v[160:163], v[218:221], v[76:79]
	v_mfma_f32_16x16x32_bf16 v[72:75], v[168:171], v[218:221], v[72:75]
	s_setprio 0
	s_setprio 1
	v_mfma_f32_16x16x32_bf16 v[116:119], v[172:175], v[190:193], v[116:119]
	v_mfma_f32_16x16x32_bf16 v[112:115], v[180:183], v[190:193], v[112:115]
	v_mfma_f32_16x16x32_bf16 v[100:103], v[172:175], v[198:201], v[100:103]
	v_mfma_f32_16x16x32_bf16 v[96:99], v[180:183], v[198:201], v[96:99]
	v_mfma_f32_16x16x32_bf16 v[84:87], v[172:175], v[206:209], v[84:87]
	v_mfma_f32_16x16x32_bf16 v[80:83], v[180:183], v[206:209], v[80:83]
	v_mfma_f32_16x16x32_bf16 v[68:71], v[172:175], v[214:217], v[68:71]
	v_mfma_f32_16x16x32_bf16 v[64:67], v[180:183], v[214:217], v[64:67]
	v_mfma_f32_16x16x32_bf16 v[116:119], v[176:179], v[194:197], v[116:119]
	v_mfma_f32_16x16x32_bf16 v[112:115], v[186:189], v[194:197], v[112:115]
	v_mfma_f32_16x16x32_bf16 v[100:103], v[176:179], v[202:205], v[100:103]
	v_mfma_f32_16x16x32_bf16 v[96:99], v[186:189], v[202:205], v[96:99]
	v_mfma_f32_16x16x32_bf16 v[84:87], v[176:179], v[210:213], v[84:87]
	v_mfma_f32_16x16x32_bf16 v[80:83], v[186:189], v[210:213], v[80:83]
	v_mfma_f32_16x16x32_bf16 v[68:71], v[176:179], v[218:221], v[68:71]
	v_mfma_f32_16x16x32_bf16 v[64:67], v[186:189], v[218:221], v[64:67]
	s_barrier
; #define PG8_STAGE(bufoff, gbase, voff) do { _Pragma("unroll") for (int _i = 0; _i < 2; ++_i) \
;         __builtin_amdgcn_global_load_lds((const unsigned*)((const char*)(gbase) + (voff)[_i]), (PG8_LAS unsigned*)(lds + (bufoff) + ldsw + _i * 8192), 16, 0, 0); } while (0)
; #define PG8_LDA(dst, b, h) do { _Pragma("unroll") for (int m = 0; m < 4; ++m) _Pragma("unroll") for (int k = 0; k < 2; ++k) dst[m][k] = *(const PG8_LAS bf16x8*)(lds + PG8_SA(b, h) + aoff + m * 2048 + k * 1024); } while (0)
; #define PG8_LDB(dst, b, h) do { _Pragma("unroll") for (int n = 0; n < 2; ++n) _Pragma("unroll") for (int k = 0; k < 2; ++k) dst[n][k] = *(const PG8_LAS bf16x8*)(lds + PG8_SB(b, h) + boff + n * 2048 + k * 1024); } while (0)
; #define PG8_MMA(ai, bj, At, Bt) do { __builtin_amdgcn_s_setprio(1); _Pragma("unroll") for (int m = 0; m < 4; ++m) _Pragma("unroll") for (int n = 0; n < 2; ++n) _Pragma("unroll") for (int k = 0; k < 2; ++k) \
;         acc[ai][bj][m][n] = __builtin_amdgcn_mfma_f32_16x16x32_bf16(Bt[n][k], At[m][k], acc[ai][bj][m][n], 0, 0, 0); __builtin_amdgcn_s_setprio(0); } while (0)
; template <class Epi, class Sched, bool ALIGN_EPI = false, bool SP2 = false>
; __device__ __forceinline__ void gemm_phase(PG8_LAS unsigned char* lds, const Gemm g, const Sched& S, const Epi& E) {
;     ...
;         for (int t = 0; t < nt; t += 2) {
;             const bool last = (t == nt - 2);
;             const char* a1 = cA + (size_t)(t + 1) * kstA;
;             const char* a2 = last ? nA : cA + (size_t)(t + 2) * kstA; const char* b2 = last ? nB : cB + (size_t)(t + 2) * kstep;
;             const char* a3 = a2 + kstA; const char* b3 = b2 + kstep;
;             if (last && has_next) S.a_ready(nxt);
;             if constexpr (SP2) {
;             PG8_LDB(B0, 0, 0); PG8_LDB(B1, 0, 1); PG8_SCHED; PG8_LDA(At, 0, 0); PG8_STAGE(PG8_SA(1, 1), a1 + hstepA, voffA);
;     ...
;             PG8_LDB(B0, 1, 0); PG8_LDB(B1, 1, 1); PG8_SCHED; PG8_LDA(At, 1, 0); PG8_STAGE(PG8_SA(0, 1), a2 + hstepA, voffA);
;             PG8_WAIT_V(8); PG8_WAIT_L(0); PG8_BAR; PG8_MMA(0, 0, At, B0); PG8_MMA(0, 1, At, B1); PG8_BAR; PG8_SCHED;
;             PG8_LDA(At, 1, 1); PG8_STAGE(PG8_SB(1, 0), b3, voffB); PG8_STAGE(PG8_SB(1, 1), b3 + hstepB, voffB); PG8_STAGE(PG8_SA(1, 0), a3, voffA);
;             PG8_WAIT_V(8); PG8_WAIT_L(0); PG8_BAR; PG8_MMA(1, 0, At, B0); PG8_MMA(1, 1, At, B1); PG8_BAR; PG8_SCHED;
	s_setprio 0
	s_add_i32 s58, s62, s3
	v_lshl_add_u64 v[222:223], v[222:223], 0, s[36:37]
	s_mov_b32 m0, s58
	ds_read_b128 v[190:193], v154 offset:49152
	ds_read_b128 v[194:197], v154 offset:50176
	ds_read_b128 v[198:201], v154 offset:51200
	ds_read_b128 v[202:205], v154 offset:52224
	ds_read_b128 v[206:209], v154 offset:53248
	ds_read_b128 v[210:213], v154 offset:54272
	ds_read_b128 v[214:217], v154 offset:55296
	ds_read_b128 v[218:221], v154 offset:56320
	global_load_lds_dwordx4 v[222:223], off
	s_add_i32 m0, s58, 0x2000
	s_add_u32 s56, s56, 0x80080
	v_lshl_add_u64 v[222:223], v[224:225], 0, s[36:37]
	s_addc_u32 s57, s57, 0
	s_add_i32 s58, s63, s3
	global_load_lds_dwordx4 v[222:223], off
	v_lshl_add_u64 v[222:223], s[56:57], 0, v[130:131]
	s_mov_b32 m0, s58
	s_nop 0
	global_load_lds_dwordx4 v[222:223], off
	v_lshl_add_u64 v[222:223], s[56:57], 0, v[134:135]
	s_add_i32 m0, s58, 0x2000
	s_nop 0
	global_load_lds_dwordx4 v[222:223], off
	v_lshl_add_u64 v[222:223], v[226:227], 0, s[36:37]
	s_mov_b32 m0, s44
	s_nop 0
	global_load_lds_dwordx4 v[222:223], off
	v_lshl_add_u64 v[222:223], v[228:229], 0, s[36:37]
	s_mov_b32 m0, s45
	s_nop 0
	global_load_lds_dwordx4 v[222:223], off
	s_waitcnt vmcnt(8)
	s_waitcnt lgkmcnt(0)
	s_setprio 1
	s_barrier
	v_mfma_f32_16x16x32_bf16 v[60:63], v[156:159], v[190:193], v[60:63]
	v_mfma_f32_16x16x32_bf16 v[56:59], v[164:167], v[190:193], v[56:59]
	v_mfma_f32_16x16x32_bf16 v[44:47], v[156:159], v[198:201], v[44:47]
	v_mfma_f32_16x16x32_bf16 v[40:43], v[164:167], v[198:201], v[40:43]
	v_mfma_f32_16x16x32_bf16 v[28:31], v[156:159], v[206:209], v[28:31]
	v_mfma_f32_16x16x32_bf16 v[24:27], v[164:167], v[206:209], v[24:27]
	v_mfma_f32_16x16x32_bf16 v[12:15], v[156:159], v[214:217], v[12:15]
	v_mfma_f32_16x16x32_bf16 v[8:11], v[164:167], v[214:217], v[8:11]
	v_mfma_f32_16x16x32_bf16 v[60:63], v[160:163], v[194:197], v[60:63]
	v_mfma_f32_16x16x32_bf16 v[56:59], v[168:171], v[194:197], v[56:59]
	v_mfma_f32_16x16x32_bf16 v[44:47], v[160:163], v[202:205], v[44:47]
	v_mfma_f32_16x16x32_bf16 v[40:43], v[168:171], v[202:205], v[40:43]
	v_mfma_f32_16x16x32_bf16 v[28:31], v[160:163], v[210:213], v[28:31]
	v_mfma_f32_16x16x32_bf16 v[24:27], v[168:171], v[210:213], v[24:27]
	v_mfma_f32_16x16x32_bf16 v[12:15], v[160:163], v[218:221], v[12:15]
	v_mfma_f32_16x16x32_bf16 v[8:11], v[168:171], v[218:221], v[8:11]
	s_setprio 0
	s_setprio 1
	v_mfma_f32_16x16x32_bf16 v[52:55], v[172:175], v[190:193], v[52:55]
	v_mfma_f32_16x16x32_bf16 v[48:51], v[180:183], v[190:193], v[48:51]
	v_mfma_f32_16x16x32_bf16 v[36:39], v[172:175], v[198:201], v[36:39]
	v_mfma_f32_16x16x32_bf16 v[32:35], v[180:183], v[198:201], v[32:35]
	v_mfma_f32_16x16x32_bf16 v[20:23], v[172:175], v[206:209], v[20:23]
	v_mfma_f32_16x16x32_bf16 v[16:19], v[180:183], v[206:209], v[16:19]
	v_mfma_f32_16x16x32_bf16 v[4:7], v[172:175], v[214:217], v[4:7]
	v_mfma_f32_16x16x32_bf16 v[0:3], v[180:183], v[214:217], v[0:3]
	v_mfma_f32_16x16x32_bf16 v[52:55], v[176:179], v[194:197], v[52:55]
	v_mfma_f32_16x16x32_bf16 v[48:51], v[186:189], v[194:197], v[48:51]
	v_mfma_f32_16x16x32_bf16 v[36:39], v[176:179], v[202:205], v[36:39]
	v_mfma_f32_16x16x32_bf16 v[32:35], v[186:189], v[202:205], v[32:35]
	v_mfma_f32_16x16x32_bf16 v[20:23], v[176:179], v[210:213], v[20:23]
	v_mfma_f32_16x16x32_bf16 v[16:19], v[186:189], v[210:213], v[16:19]
	v_mfma_f32_16x16x32_bf16 v[4:7], v[176:179], v[218:221], v[4:7]
	v_mfma_f32_16x16x32_bf16 v[0:3], v[186:189], v[218:221], v[0:3]
	s_barrier
	s_setprio 0
	s_add_i32 s61, s61, 2
	s_add_u32 s50, s50, 0x100
	s_addc_u32 s51, s51, 0
	s_add_u32 s41, s41, 0x100
	s_addc_u32 s43, s43, 0
	s_cmp_gt_u32 s61, 29
	s_cbranch_scc1 .Lmy_peel_0_exit
.LBB0_300:
	ds_read_b128 v[156:159], v152
	ds_read_b128 v[160:163], v152 offset:1024
	ds_read_b128 v[164:167], v152 offset:2048
	ds_read_b128 v[168:171], v152 offset:3072
	ds_read_b128 v[172:175], v153
	ds_read_b128 v[176:179], v153 offset:1024
	ds_read_b128 v[180:183], v153 offset:2048
	ds_read_b128 v[186:189], v153 offset:3072
	s_add_u32 s56, s50, 0xfff80080
	s_addc_u32 s57, s51, -1
	s_cmp_eq_u32 s61, 28
	s_cselect_b32 s59, s4, s57
	s_cselect_b32 s58, s5, s56
	s_cselect_b32 s57, s12, s43
	s_cselect_b32 s56, s13, s41
	v_lshl_add_u64 v[222:223], s[50:51], 0, v[142:143]
	s_add_i32 m0, s6, 0xc000
	ds_read_b128 v[190:193], v154
	ds_read_b128 v[194:197], v154 offset:1024
	ds_read_b128 v[198:201], v154 offset:2048
	ds_read_b128 v[202:205], v154 offset:3072
	ds_read_b128 v[206:209], v154 offset:4096
	ds_read_b128 v[210:213], v154 offset:5120
	ds_read_b128 v[214:217], v154 offset:6144
	ds_read_b128 v[218:221], v154 offset:7168
	global_load_lds_dwordx4 v[222:223], off
	v_lshl_add_u64 v[222:223], s[50:51], 0, v[144:145]
	s_add_i32 m0, s6, 0xe000
	s_nop 0
	global_load_lds_dwordx4 v[222:223], off
	s_waitcnt vmcnt(8)
	s_waitcnt lgkmcnt(0)
	s_setprio 1
	s_barrier
; #define PG8_STAGE(bufoff, gbase, voff) do { _Pragma("unroll") for (int _i = 0; _i < 2; ++_i) \
;         __builtin_amdgcn_global_load_lds((const unsigned*)((const char*)(gbase) + (voff)[_i]), (PG8_LAS unsigned*)(lds + (bufoff) + ldsw + _i * 8192), 16, 0, 0); } while (0)
; #define PG8_LDA(dst, b, h) do { _Pragma("unroll") for (int m = 0; m < 4; ++m) _Pragma("unroll") for (int k = 0; k < 2; ++k) dst[m][k] = *(const PG8_LAS bf16x8*)(lds + PG8_SA(b, h) + aoff + m * 2048 + k * 1024); } while (0)
; #define PG8_LDB(dst, b, h) do { _Pragma("unroll") for (int n = 0; n < 2; ++n) _Pragma("unroll") for (int k = 0; k < 2; ++k) dst[n][k] = *(const PG8_LAS bf16x8*)(lds + PG8_SB(b, h) + boff + n * 2048 + k * 1024); } while (0)
; #define PG8_MMA(ai, bj, At, Bt) do { __builtin_amdgcn_s_setprio(1); _Pragma("unroll") for (int m = 0; m < 4; ++m) _Pragma("unroll") for (int n = 0; n < 2; ++n) _Pragma("unroll") for (int k = 0; k < 2; ++k) \
;         acc[ai][bj][m][n] = __builtin_amdgcn_mfma_f32_16x16x32_bf16(Bt[n][k], At[m][k], acc[ai][bj][m][n], 0, 0, 0); __builtin_amdgcn_s_setprio(0); } while (0)
; #define PG8_WAIT_V(n) asm volatile("s_waitcnt vmcnt(" #n ")" ::: "memory")
; #define PG8_WAIT_L(n) asm volatile("s_waitcnt lgkmcnt(" #n ")" ::: "memory")
; #define PG8_BAR __builtin_amdgcn_s_barrier()
; #define PG8_SCHED __builtin_amdgcn_sched_barrier(0)
; template <class Epi, class Sched, bool ALIGN_EPI = false, bool SP2 = false>
; __device__ __forceinline__ void gemm_phase(PG8_LAS unsigned char* lds, const Gemm g, const Sched& S, const Epi& E) {
;     ...
;             PG8_LDB(B0, 0, 0); PG8_LDB(B1, 0, 1); PG8_SCHED; PG8_LDA(At, 0, 0); PG8_STAGE(PG8_SA(1, 1), a1 + hstepA, voffA);
;             PG8_WAIT_V(8); PG8_WAIT_L(0); PG8_BAR; PG8_MMA(0, 0, At, B0); PG8_MMA(0, 1, At, B1); PG8_BAR; PG8_SCHED;
;             PG8_LDA(At, 0, 1); PG8_STAGE(PG8_SB(0, 0), b2, voffB); PG8_STAGE(PG8_SB(0, 1), b2 + hstepB, voffB); PG8_STAGE(PG8_SA(0, 0), a2, voffA);
;             PG8_WAIT_V(8); PG8_WAIT_L(0); PG8_BAR; PG8_MMA(1, 0, At, B0); PG8_MMA(1, 1, At, B1); PG8_BAR; PG8_SCHED;
;             PG8_LDB(B0, 1, 0); PG8_LDB(B1, 1, 1); PG8_SCHED; PG8_LDA(At, 1, 0); PG8_STAGE(PG8_SA(0, 1), a2 + hstepA, voffA);
	v_mfma_f32_16x16x32_bf16 v[124:127], v[156:159], v[190:193], v[124:127]
	v_mfma_f32_16x16x32_bf16 v[120:123], v[164:167], v[190:193], v[120:123]
	v_mfma_f32_16x16x32_bf16 v[108:111], v[156:159], v[198:201], v[108:111]
	v_mfma_f32_16x16x32_bf16 v[104:107], v[164:167], v[198:201], v[104:107]
	v_mfma_f32_16x16x32_bf16 v[92:95], v[156:159], v[206:209], v[92:95]
	v_mfma_f32_16x16x32_bf16 v[88:91], v[164:167], v[206:209], v[88:91]
	v_mfma_f32_16x16x32_bf16 v[76:79], v[156:159], v[214:217], v[76:79]
	v_mfma_f32_16x16x32_bf16 v[72:75], v[164:167], v[214:217], v[72:75]
	v_mfma_f32_16x16x32_bf16 v[124:127], v[160:163], v[194:197], v[124:127]
	v_mfma_f32_16x16x32_bf16 v[120:123], v[168:171], v[194:197], v[120:123]
	v_mfma_f32_16x16x32_bf16 v[108:111], v[160:163], v[202:205], v[108:111]
	v_mfma_f32_16x16x32_bf16 v[104:107], v[168:171], v[202:205], v[104:107]
	v_mfma_f32_16x16x32_bf16 v[92:95], v[160:163], v[210:213], v[92:95]
	v_mfma_f32_16x16x32_bf16 v[88:91], v[168:171], v[210:213], v[88:91]
	v_mfma_f32_16x16x32_bf16 v[76:79], v[160:163], v[218:221], v[76:79]
	v_mfma_f32_16x16x32_bf16 v[72:75], v[168:171], v[218:221], v[72:75]
	s_setprio 0
	s_setprio 1
	v_mfma_f32_16x16x32_bf16 v[116:119], v[172:175], v[190:193], v[116:119]
	v_mfma_f32_16x16x32_bf16 v[112:115], v[180:183], v[190:193], v[112:115]
	v_mfma_f32_16x16x32_bf16 v[100:103], v[172:175], v[198:201], v[100:103]
	v_mfma_f32_16x16x32_bf16 v[96:99], v[180:183], v[198:201], v[96:99]
	v_mfma_f32_16x16x32_bf16 v[84:87], v[172:175], v[206:209], v[84:87]
	v_mfma_f32_16x16x32_bf16 v[80:83], v[180:183], v[206:209], v[80:83]
	v_mfma_f32_16x16x32_bf16 v[68:71], v[172:175], v[214:217], v[68:71]
	v_mfma_f32_16x16x32_bf16 v[64:67], v[180:183], v[214:217], v[64:67]
	v_mfma_f32_16x16x32_bf16 v[116:119], v[176:179], v[194:197], v[116:119]
	v_mfma_f32_16x16x32_bf16 v[112:115], v[186:189], v[194:197], v[112:115]
	v_mfma_f32_16x16x32_bf16 v[100:103], v[176:179], v[202:205], v[100:103]
	v_mfma_f32_16x16x32_bf16 v[96:99], v[186:189], v[202:205], v[96:99]
	v_mfma_f32_16x16x32_bf16 v[84:87], v[176:179], v[210:213], v[84:87]
	v_mfma_f32_16x16x32_bf16 v[80:83], v[186:189], v[210:213], v[80:83]
	v_mfma_f32_16x16x32_bf16 v[68:71], v[176:179], v[218:221], v[68:71]
	v_mfma_f32_16x16x32_bf16 v[64:67], v[186:189], v[218:221], v[64:67]
	s_barrier
	s_setprio 0
	s_add_i32 s62, s53, s3
	v_lshl_add_u64 v[222:223], s[56:57], 0, v[130:131]
	s_mov_b32 m0, s62
	ds_read_b128 v[190:193], v154 offset:16384
	ds_read_b128 v[194:197], v154 offset:17408
	ds_read_b128 v[198:201], v154 offset:18432
	ds_read_b128 v[202:205], v154 offset:19456
	ds_read_b128 v[206:209], v154 offset:20480
	ds_read_b128 v[210:213], v154 offset:21504
	ds_read_b128 v[214:217], v154 offset:22528
	ds_read_b128 v[218:221], v154 offset:23552
	global_load_lds_dwordx4 v[222:223], off
	s_add_i32 m0, s62, 0x2000
	s_add_u32 s62, s56, 0x80000
	v_lshl_add_u64 v[224:225], s[56:57], 0, v[134:135]
	s_addc_u32 s63, s57, 0
	s_add_i32 s64, s55, s3
	global_load_lds_dwordx4 v[224:225], off
	v_lshl_add_u64 v[226:227], s[62:63], 0, v[130:131]
	s_mov_b32 m0, s64
	v_lshl_add_u64 v[228:229], s[58:59], 0, v[132:133]
	global_load_lds_dwordx4 v[226:227], off
	v_lshl_add_u64 v[226:227], s[62:63], 0, v[134:135]
	s_add_i32 m0, s64, 0x2000
	s_nop 0
	global_load_lds_dwordx4 v[226:227], off
	v_lshl_add_u64 v[226:227], s[58:59], 0, v[128:129]
	s_mov_b32 m0, s6
	s_nop 0
	global_load_lds_dwordx4 v[226:227], off
	s_mov_b32 m0, s7
	s_nop 0
	global_load_lds_dwordx4 v[228:229], off
	s_waitcnt vmcnt(8)
	s_waitcnt lgkmcnt(0)
	s_setprio 1
	s_barrier
	v_mfma_f32_16x16x32_bf16 v[60:63], v[156:159], v[190:193], v[60:63]
	v_mfma_f32_16x16x32_bf16 v[56:59], v[164:167], v[190:193], v[56:59]
	v_mfma_f32_16x16x32_bf16 v[44:47], v[156:159], v[198:201], v[44:47]
	v_mfma_f32_16x16x32_bf16 v[40:43], v[164:167], v[198:201], v[40:43]
	v_mfma_f32_16x16x32_bf16 v[28:31], v[156:159], v[206:209], v[28:31]
	v_mfma_f32_16x16x32_bf16 v[24:27], v[164:167], v[206:209], v[24:27]
	v_mfma_f32_16x16x32_bf16 v[12:15], v[156:159], v[214:217], v[12:15]
	v_mfma_f32_16x16x32_bf16 v[8:11], v[164:167], v[214:217], v[8:11]
	v_mfma_f32_16x16x32_bf16 v[60:63], v[160:163], v[194:197], v[60:63]
	v_mfma_f32_16x16x32_bf16 v[56:59], v[168:171], v[194:197], v[56:59]
	v_mfma_f32_16x16x32_bf16 v[44:47], v[160:163], v[202:205], v[44:47]
	v_mfma_f32_16x16x32_bf16 v[40:43], v[168:171], v[202:205], v[40:43]
	v_mfma_f32_16x16x32_bf16 v[28:31], v[160:163], v[210:213], v[28:31]
	v_mfma_f32_16x16x32_bf16 v[24:27], v[168:171], v[210:213], v[24:27]
	v_mfma_f32_16x16x32_bf16 v[12:15], v[160:163], v[218:221], v[12:15]
	v_mfma_f32_16x16x32_bf16 v[8:11], v[168:171], v[218:221], v[8:11]
	s_setprio 0
	s_setprio 1
	v_mfma_f32_16x16x32_bf16 v[52:55], v[172:175], v[190:193], v[52:55]
	v_mfma_f32_16x16x32_bf16 v[48:51], v[180:183], v[190:193], v[48:51]
	v_mfma_f32_16x16x32_bf16 v[36:39], v[172:175], v[198:201], v[36:39]
	v_mfma_f32_16x16x32_bf16 v[32:35], v[180:183], v[198:201], v[32:35]
	v_mfma_f32_16x16x32_bf16 v[20:23], v[172:175], v[206:209], v[20:23]
	v_mfma_f32_16x16x32_bf16 v[16:19], v[180:183], v[206:209], v[16:19]
	v_mfma_f32_16x16x32_bf16 v[4:7], v[172:175], v[214:217], v[4:7]
	v_mfma_f32_16x16x32_bf16 v[0:3], v[180:183], v[214:217], v[0:3]
	v_mfma_f32_16x16x32_bf16 v[52:55], v[176:179], v[194:197], v[52:55]
	v_mfma_f32_16x16x32_bf16 v[48:51], v[186:189], v[194:197], v[48:51]
	v_mfma_f32_16x16x32_bf16 v[36:39], v[176:179], v[202:205], v[36:39]
	v_mfma_f32_16x16x32_bf16 v[32:35], v[186:189], v[202:205], v[32:35]
	v_mfma_f32_16x16x32_bf16 v[20:23], v[176:179], v[210:213], v[20:23]
	v_mfma_f32_16x16x32_bf16 v[16:19], v[186:189], v[210:213], v[16:19]
	v_mfma_f32_16x16x32_bf16 v[4:7], v[176:179], v[218:221], v[4:7]
	v_mfma_f32_16x16x32_bf16 v[0:3], v[186:189], v[218:221], v[0:3]
	s_barrier
; #define PG8_STAGE(bufoff, gbase, voff) do { _Pragma("unroll") for (int _i = 0; _i < 2; ++_i) \
;         __builtin_amdgcn_global_load_lds((const unsigned*)((const char*)(gbase) + (voff)[_i]), (PG8_LAS unsigned*)(lds + (bufoff) + ldsw + _i * 8192), 16, 0, 0); } while (0)
; #define PG8_LDA(dst, b, h) do { _Pragma("unroll") for (int m = 0; m < 4; ++m) _Pragma("unroll") for (int k = 0; k < 2; ++k) dst[m][k] = *(const PG8_LAS bf16x8*)(lds + PG8_SA(b, h) + aoff + m * 2048 + k * 1024); } while (0)
; #define PG8_LDB(dst, b, h) do { _Pragma("unroll") for (int n = 0; n < 2; ++n) _Pragma("unroll") for (int k = 0; k < 2; ++k) dst[n][k] = *(const PG8_LAS bf16x8*)(lds + PG8_SB(b, h) + boff + n * 2048 + k * 1024); } while (0)
; #define PG8_MMA(ai, bj, At, Bt) do { __builtin_amdgcn_s_setprio(1); _Pragma("unroll") for (int m = 0; m < 4; ++m) _Pragma("unroll") for (int n = 0; n < 2; ++n) _Pragma("unroll") for (int k = 0; k < 2; ++k) \
;         acc[ai][bj][m][n] = __builtin_amdgcn_mfma_f32_16x16x32_bf16(Bt[n][k], At[m][k], acc[ai][bj][m][n], 0, 0, 0); __builtin_amdgcn_s_setprio(0); } while (0)
; #define PG8_WAIT_V(n) asm volatile("s_waitcnt vmcnt(" #n ")" ::: "memory")
; #define PG8_WAIT_L(n) asm volatile("s_waitcnt lgkmcnt(" #n ")" ::: "memory")
; #define PG8_BAR __builtin_amdgcn_s_barrier()
; #define PG8_SCHED __builtin_amdgcn_sched_barrier(0)
; template <class Epi, class Sched, bool ALIGN_EPI = false, bool SP2 = false>
; __device__ __forceinline__ void gemm_phase(PG8_LAS unsigned char* lds, const Gemm g, const Sched& S, const Epi& E) {
;     ...
;             PG8_LDB(B0, 1, 0); PG8_LDB(B1, 1, 1); PG8_SCHED; PG8_LDA(At, 1, 0); PG8_STAGE(PG8_SA(0, 1), a2 + hstepA, voffA);
;             PG8_WAIT_V(8); PG8_WAIT_L(0); PG8_BAR; PG8_MMA(0, 0, At, B0); PG8_MMA(0, 1, At, B1); PG8_BAR; PG8_SCHED;
	s_setprio 0
	s_add_i32 s62, 0, 0x18000
	v_add_u32_e32 v155, s62, v150
	s_add_i32 s63, 0, 0x1c000
	ds_read_b128 v[156:159], v155
	ds_read_b128 v[160:163], v155 offset:1024
	ds_read_b128 v[164:167], v155 offset:2048
	ds_read_b128 v[168:171], v155 offset:3072
	v_add_u32_e32 v155, s63, v150
	ds_read_b128 v[172:175], v155
	ds_read_b128 v[176:179], v155 offset:1024
	ds_read_b128 v[180:183], v155 offset:2048
	ds_read_b128 v[186:189], v155 offset:3072
	s_add_u32 s58, s58, 0x80000
	s_addc_u32 s59, s59, 0
	s_mov_b32 m0, s8
	v_lshl_add_u64 v[230:231], s[58:59], 0, v[128:129]
	ds_read_b128 v[190:193], v154 offset:32768
	ds_read_b128 v[194:197], v154 offset:33792
	ds_read_b128 v[198:201], v154 offset:34816
	ds_read_b128 v[202:205], v154 offset:35840
	ds_read_b128 v[206:209], v154 offset:36864
	ds_read_b128 v[210:213], v154 offset:37888
	ds_read_b128 v[214:217], v154 offset:38912
	ds_read_b128 v[218:221], v154 offset:39936
	global_load_lds_dwordx4 v[230:231], off
	v_lshl_add_u64 v[230:231], s[58:59], 0, v[132:133]
	s_mov_b32 m0, s9
	s_nop 0
	global_load_lds_dwordx4 v[230:231], off
	s_waitcnt vmcnt(8)
	s_waitcnt lgkmcnt(0)
	s_setprio 1
	s_barrier
	v_mfma_f32_16x16x32_bf16 v[124:127], v[156:159], v[190:193], v[124:127]
	v_mfma_f32_16x16x32_bf16 v[120:123], v[164:167], v[190:193], v[120:123]
	v_mfma_f32_16x16x32_bf16 v[108:111], v[156:159], v[198:201], v[108:111]
	v_mfma_f32_16x16x32_bf16 v[104:107], v[164:167], v[198:201], v[104:107]
	v_mfma_f32_16x16x32_bf16 v[92:95], v[156:159], v[206:209], v[92:95]
	v_mfma_f32_16x16x32_bf16 v[88:91], v[164:167], v[206:209], v[88:91]
	v_mfma_f32_16x16x32_bf16 v[76:79], v[156:159], v[214:217], v[76:79]
	v_mfma_f32_16x16x32_bf16 v[72:75], v[164:167], v[214:217], v[72:75]
	v_mfma_f32_16x16x32_bf16 v[124:127], v[160:163], v[194:197], v[124:127]
	v_mfma_f32_16x16x32_bf16 v[120:123], v[168:171], v[194:197], v[120:123]
	v_mfma_f32_16x16x32_bf16 v[108:111], v[160:163], v[202:205], v[108:111]
	v_mfma_f32_16x16x32_bf16 v[104:107], v[168:171], v[202:205], v[104:107]
	v_mfma_f32_16x16x32_bf16 v[92:95], v[160:163], v[210:213], v[92:95]
	v_mfma_f32_16x16x32_bf16 v[88:91], v[168:171], v[210:213], v[88:91]
	v_mfma_f32_16x16x32_bf16 v[76:79], v[160:163], v[218:221], v[76:79]
	v_mfma_f32_16x16x32_bf16 v[72:75], v[168:171], v[218:221], v[72:75]
	s_setprio 0
	s_setprio 1
	v_mfma_f32_16x16x32_bf16 v[116:119], v[172:175], v[190:193], v[116:119]
	v_mfma_f32_16x16x32_bf16 v[112:115], v[180:183], v[190:193], v[112:115]
	v_mfma_f32_16x16x32_bf16 v[100:103], v[172:175], v[198:201], v[100:103]
	v_mfma_f32_16x16x32_bf16 v[96:99], v[180:183], v[198:201], v[96:99]
	v_mfma_f32_16x16x32_bf16 v[84:87], v[172:175], v[206:209], v[84:87]
	v_mfma_f32_16x16x32_bf16 v[80:83], v[180:183], v[206:209], v[80:83]
	v_mfma_f32_16x16x32_bf16 v[68:71], v[172:175], v[214:217], v[68:71]
	v_mfma_f32_16x16x32_bf16 v[64:67], v[180:183], v[214:217], v[64:67]
	v_mfma_f32_16x16x32_bf16 v[116:119], v[176:179], v[194:197], v[116:119]
	v_mfma_f32_16x16x32_bf16 v[112:115], v[186:189], v[194:197], v[112:115]
	v_mfma_f32_16x16x32_bf16 v[100:103], v[176:179], v[202:205], v[100:103]
	v_mfma_f32_16x16x32_bf16 v[96:99], v[186:189], v[202:205], v[96:99]
	v_mfma_f32_16x16x32_bf16 v[84:87], v[176:179], v[210:213], v[84:87]
	v_mfma_f32_16x16x32_bf16 v[80:83], v[186:189], v[210:213], v[80:83]
	v_mfma_f32_16x16x32_bf16 v[68:71], v[176:179], v[218:221], v[68:71]
	v_mfma_f32_16x16x32_bf16 v[64:67], v[186:189], v[218:221], v[64:67]
	s_barrier
; #define PG8_STAGE(bufoff, gbase, voff) do { _Pragma("unroll") for (int _i = 0; _i < 2; ++_i) \
;         __builtin_amdgcn_global_load_lds((const unsigned*)((const char*)(gbase) + (voff)[_i]), (PG8_LAS unsigned*)(lds + (bufoff) + ldsw + _i * 8192), 16, 0, 0); } while (0)
; #define PG8_LDA(dst, b, h) do { _Pragma("unroll") for (int m = 0; m < 4; ++m) _Pragma("unroll") for (int k = 0; k < 2; ++k) dst[m][k] = *(const PG8_LAS bf16x8*)(lds + PG8_SA(b, h) + aoff + m * 2048 + k * 1024); } while (0)
; #define PG8_MMA(ai, bj, At, Bt) do { __builtin_amdgcn_s_setprio(1); _Pragma("unroll") for (int m = 0; m < 4; ++m) _Pragma("unroll") for (int n = 0; n < 2; ++n) _Pragma("unroll") for (int k = 0; k < 2; ++k) \
;         acc[ai][bj][m][n] = __builtin_amdgcn_mfma_f32_16x16x32_bf16(Bt[n][k], At[m][k], acc[ai][bj][m][n], 0, 0, 0); __builtin_amdgcn_s_setprio(0); } while (0)
; #define PG8_WAIT_V(n) asm volatile("s_waitcnt vmcnt(" #n ")" ::: "memory")
; #define PG8_WAIT_L(n) asm volatile("s_waitcnt lgkmcnt(" #n ")" ::: "memory")
; #define PG8_BAR __builtin_amdgcn_s_barrier()
; #define PG8_SCHED __builtin_amdgcn_sched_barrier(0)
; template <class Epi, class Sched, bool ALIGN_EPI = false, bool SP2 = false>
; __device__ __forceinline__ void gemm_phase(PG8_LAS unsigned char* lds, const Gemm g, const Sched& S, const Epi& E) {
;     ...
;             PG8_LDA(At, 1, 1); PG8_STAGE(PG8_SB(1, 0), b3, voffB); PG8_STAGE(PG8_SB(1, 1), b3 + hstepB, voffB); PG8_STAGE(PG8_SA(1, 0), a3, voffA);
;             PG8_WAIT_V(8); PG8_WAIT_L(0); PG8_BAR; PG8_MMA(1, 0, At, B0); PG8_MMA(1, 1, At, B1); PG8_BAR; PG8_SCHED;
	s_setprio 0
	s_add_i32 s58, s62, s3
	v_lshl_add_u64 v[222:223], v[222:223], 0, s[36:37]
	s_mov_b32 m0, s58
	ds_read_b128 v[190:193], v154 offset:49152
	ds_read_b128 v[194:197], v154 offset:50176
	ds_read_b128 v[198:201], v154 offset:51200
	ds_read_b128 v[202:205], v154 offset:52224
	ds_read_b128 v[206:209], v154 offset:53248
	ds_read_b128 v[210:213], v154 offset:54272
	ds_read_b128 v[214:217], v154 offset:55296
	ds_read_b128 v[218:221], v154 offset:56320
	global_load_lds_dwordx4 v[222:223], off
	s_add_i32 m0, s58, 0x2000
	s_add_u32 s56, s56, 0x80080
	v_lshl_add_u64 v[222:223], v[224:225], 0, s[36:37]
	s_addc_u32 s57, s57, 0
	s_add_i32 s58, s63, s3
	global_load_lds_dwordx4 v[222:223], off
	v_lshl_add_u64 v[222:223], s[56:57], 0, v[130:131]
	s_mov_b32 m0, s58
	s_nop 0
	global_load_lds_dwordx4 v[222:223], off
	v_lshl_add_u64 v[222:223], s[56:57], 0, v[134:135]
	s_add_i32 m0, s58, 0x2000
	s_nop 0
	global_load_lds_dwordx4 v[222:223], off
	v_lshl_add_u64 v[222:223], v[226:227], 0, s[36:37]
	s_mov_b32 m0, s44
	s_nop 0
	global_load_lds_dwordx4 v[222:223], off
	v_lshl_add_u64 v[222:223], v[228:229], 0, s[36:37]
	s_mov_b32 m0, s45
	s_nop 0
	global_load_lds_dwordx4 v[222:223], off
	s_waitcnt vmcnt(8)
	s_waitcnt lgkmcnt(0)
	s_setprio 1
	s_barrier
	v_mfma_f32_16x16x32_bf16 v[60:63], v[156:159], v[190:193], v[60:63]
	v_mfma_f32_16x16x32_bf16 v[56:59], v[164:167], v[190:193], v[56:59]
	v_mfma_f32_16x16x32_bf16 v[44:47], v[156:159], v[198:201], v[44:47]
	v_mfma_f32_16x16x32_bf16 v[40:43], v[164:167], v[198:201], v[40:43]
	v_mfma_f32_16x16x32_bf16 v[28:31], v[156:159], v[206:209], v[28:31]
	v_mfma_f32_16x16x32_bf16 v[24:27], v[164:167], v[206:209], v[24:27]
	v_mfma_f32_16x16x32_bf16 v[12:15], v[156:159], v[214:217], v[12:15]
	v_mfma_f32_16x16x32_bf16 v[8:11], v[164:167], v[214:217], v[8:11]
	v_mfma_f32_16x16x32_bf16 v[60:63], v[160:163], v[194:197], v[60:63]
	v_mfma_f32_16x16x32_bf16 v[56:59], v[168:171], v[194:197], v[56:59]
	v_mfma_f32_16x16x32_bf16 v[44:47], v[160:163], v[202:205], v[44:47]
	v_mfma_f32_16x16x32_bf16 v[40:43], v[168:171], v[202:205], v[40:43]
	v_mfma_f32_16x16x32_bf16 v[28:31], v[160:163], v[210:213], v[28:31]
	v_mfma_f32_16x16x32_bf16 v[24:27], v[168:171], v[210:213], v[24:27]
	v_mfma_f32_16x16x32_bf16 v[12:15], v[160:163], v[218:221], v[12:15]
	v_mfma_f32_16x16x32_bf16 v[8:11], v[168:171], v[218:221], v[8:11]
	s_setprio 0
	s_setprio 1
	v_mfma_f32_16x16x32_bf16 v[52:55], v[172:175], v[190:193], v[52:55]
	v_mfma_f32_16x16x32_bf16 v[48:51], v[180:183], v[190:193], v[48:51]
	v_mfma_f32_16x16x32_bf16 v[36:39], v[172:175], v[198:201], v[36:39]
	v_mfma_f32_16x16x32_bf16 v[32:35], v[180:183], v[198:201], v[32:35]
	v_mfma_f32_16x16x32_bf16 v[20:23], v[172:175], v[206:209], v[20:23]
	v_mfma_f32_16x16x32_bf16 v[16:19], v[180:183], v[206:209], v[16:19]
	v_mfma_f32_16x16x32_bf16 v[4:7], v[172:175], v[214:217], v[4:7]
	v_mfma_f32_16x16x32_bf16 v[0:3], v[180:183], v[214:217], v[0:3]
	v_mfma_f32_16x16x32_bf16 v[52:55], v[176:179], v[194:197], v[52:55]
	v_mfma_f32_16x16x32_bf16 v[48:51], v[186:189], v[194:197], v[48:51]
	v_mfma_f32_16x16x32_bf16 v[36:39], v[176:179], v[202:205], v[36:39]
	v_mfma_f32_16x16x32_bf16 v[32:35], v[186:189], v[202:205], v[32:35]
	v_mfma_f32_16x16x32_bf16 v[20:23], v[176:179], v[210:213], v[20:23]
	v_mfma_f32_16x16x32_bf16 v[16:19], v[186:189], v[210:213], v[16:19]
	v_mfma_f32_16x16x32_bf16 v[4:7], v[176:179], v[218:221], v[4:7]
	v_mfma_f32_16x16x32_bf16 v[0:3], v[186:189], v[218:221], v[0:3]
	s_barrier
	s_setprio 0
	s_add_i32 s61, s61, 2
	s_add_u32 s50, s50, 0x100
	s_addc_u32 s51, s51, 0
	s_add_u32 s41, s41, 0x100
	s_addc_u32 s43, s43, 0
	s_cmp_gt_u32 s61, 29
	s_cbranch_scc0 .LBB0_300

; #define PG8_STAGE(bufoff, gbase, voff) do { _Pragma("unroll") for (int _i = 0; _i < 2; ++_i) \
;         __builtin_amdgcn_global_load_lds((const unsigned*)((const char*)(gbase) + (voff)[_i]), (PG8_LAS unsigned*)(lds + (bufoff) + ldsw + _i * 8192), 16, 0, 0); } while (0)
; #define PG8_LDA(dst, b, h) do { _Pragma("unroll") for (int m = 0; m < 4; ++m) _Pragma("unroll") for (int k = 0; k < 2; ++k) dst[m][k] = *(const PG8_LAS bf16x8*)(lds + PG8_SA(b, h) + aoff + m * 2048 + k * 1024); } while (0)
; #define PG8_LDB(dst, b, h) do { _Pragma("unroll") for (int n = 0; n < 2; ++n) _Pragma("unroll") for (int k = 0; k < 2; ++k) dst[n][k] = *(const PG8_LAS bf16x8*)(lds + PG8_SB(b, h) + boff + n * 2048 + k * 1024); } while (0)
; #define PG8_MMA(ai, bj, At, Bt) do { __builtin_amdgcn_s_setprio(1); _Pragma("unroll") for (int m = 0; m < 4; ++m) _Pragma("unroll") for (int n = 0; n < 2; ++n) _Pragma("unroll") for (int k = 0; k < 2; ++k) \
;         acc[ai][bj][m][n] = __builtin_amdgcn_mfma_f32_16x16x32_bf16(Bt[n][k], At[m][k], acc[ai][bj][m][n], 0, 0, 0); __builtin_amdgcn_s_setprio(0); } while (0)
; #define PG8_WAIT_V(n) asm volatile("s_waitcnt vmcnt(" #n ")" ::: "memory")
; #define PG8_WAIT_L(n) asm volatile("s_waitcnt lgkmcnt(" #n ")" ::: "memory")
; #define PG8_BAR __builtin_amdgcn_s_barrier()
; template <class Epi, class Sched, bool ALIGN_EPI = false, bool SP2 = false>
; __device__ __forceinline__ void gemm_phase(PG8_LAS unsigned char* lds, const Gemm g, const Sched& S, const Epi& E) {
;     ...
;     f32x4 acc[2][2][4][2];
; #pragma unroll
;     for (int a = 0; a < 2; ++a)
; #pragma unroll
;         for (int b = 0; b < 2; ++b)
; #pragma unroll
;             for (int m = 0; m < 4; ++m)
; #pragma unroll
;                 for (int n = 0; n < 2; ++n) acc[a][b][m][n] = (f32x4){0.f, 0.f, 0.f, 0.f};
;     ...
;             if constexpr (SP2) {
;             PG8_LDB(B0, 0, 0); PG8_LDB(B1, 0, 1); PG8_SCHED; PG8_LDA(At, 0, 0); PG8_STAGE(PG8_SA(1, 1), a1 + hstepA, voffA);
;             PG8_WAIT_V(8); PG8_WAIT_L(0); PG8_BAR; PG8_MMA(0, 0, At, B0); PG8_MMA(0, 1, At, B1); PG8_BAR; PG8_SCHED;
;             PG8_LDA(At, 0, 1); PG8_STAGE(PG8_SB(0, 0), b2, voffB); PG8_STAGE(PG8_SB(0, 1), b2 + hstepB, voffB); PG8_STAGE(PG8_SA(0, 0), a2, voffA);
;             PG8_WAIT_V(8); PG8_WAIT_L(0); PG8_BAR; PG8_MMA(1, 0, At, B0); PG8_MMA(1, 1, At, B1); PG8_BAR; PG8_SCHED;
.LBB0_655:
	s_add_u32 s50, s50, 0x80080
	s_addc_u32 s51, s51, 0
	s_add_u32 s4, s52, 0x100
	s_addc_u32 s5, s53, 0
	s_mov_b32 s46, -2
	ds_read_b128 v[166:169], v163
	ds_read_b128 v[170:173], v163 offset:1024
	ds_read_b128 v[174:177], v163 offset:2048
	ds_read_b128 v[178:181], v163 offset:3072
	ds_read_b128 v[186:189], v164
	ds_read_b128 v[190:193], v164 offset:1024
	ds_read_b128 v[194:197], v164 offset:2048
	ds_read_b128 v[198:201], v164 offset:3072
	s_add_u32 s47, s50, 0xfff80080
	s_addc_u32 s52, s51, -1
	s_cmp_eq_u32 s46, 28
	s_cselect_b32 s59, s63, s52
	s_cselect_b32 s58, s62, s47
	s_cselect_b32 s53, s65, s5
	s_cselect_b32 s52, s64, s4
	v_lshl_add_u64 v[158:159], s[50:51], 0, v[152:153]
	s_add_i32 m0, s9, 0xc000
	ds_read_b128 v[202:205], v165
	ds_read_b128 v[206:209], v165 offset:1024
	ds_read_b128 v[210:213], v165 offset:2048
	ds_read_b128 v[214:217], v165 offset:3072
	ds_read_b128 v[218:221], v165 offset:4096
	ds_read_b128 v[222:225], v165 offset:5120
	ds_read_b128 v[226:229], v165 offset:6144
	ds_read_b128 v[230:233], v165 offset:7168
	global_load_lds_dwordx4 v[158:159], off
	v_lshl_add_u64 v[158:159], s[50:51], 0, v[154:155]
	s_add_i32 m0, s9, 0xe000
	s_nop 0
	global_load_lds_dwordx4 v[158:159], off
	s_waitcnt vmcnt(8)
	s_waitcnt lgkmcnt(0)
	s_setprio 1
	s_barrier
	v_mfma_f32_16x16x32_bf16 v[124:127], v[166:169], v[202:205], 0
	v_mfma_f32_16x16x32_bf16 v[120:123], v[174:177], v[202:205], 0
	v_mfma_f32_16x16x32_bf16 v[112:115], v[166:169], v[210:213], 0
	v_mfma_f32_16x16x32_bf16 v[104:107], v[174:177], v[210:213], 0
	v_mfma_f32_16x16x32_bf16 v[96:99], v[166:169], v[218:221], 0
	v_mfma_f32_16x16x32_bf16 v[88:91], v[174:177], v[218:221], 0
	v_mfma_f32_16x16x32_bf16 v[80:83], v[166:169], v[226:229], 0
	v_mfma_f32_16x16x32_bf16 v[72:75], v[174:177], v[226:229], 0
	v_mfma_f32_16x16x32_bf16 v[124:127], v[170:173], v[206:209], v[124:127]
	v_mfma_f32_16x16x32_bf16 v[120:123], v[178:181], v[206:209], v[120:123]
	v_mfma_f32_16x16x32_bf16 v[112:115], v[170:173], v[214:217], v[112:115]
	v_mfma_f32_16x16x32_bf16 v[104:107], v[178:181], v[214:217], v[104:107]
	v_mfma_f32_16x16x32_bf16 v[96:99], v[170:173], v[222:225], v[96:99]
	v_mfma_f32_16x16x32_bf16 v[88:91], v[178:181], v[222:225], v[88:91]
	v_mfma_f32_16x16x32_bf16 v[80:83], v[170:173], v[230:233], v[80:83]
	v_mfma_f32_16x16x32_bf16 v[72:75], v[178:181], v[230:233], v[72:75]
	s_setprio 0
	s_setprio 1
	v_mfma_f32_16x16x32_bf16 v[116:119], v[186:189], v[202:205], 0
	v_mfma_f32_16x16x32_bf16 v[108:111], v[194:197], v[202:205], 0
	v_mfma_f32_16x16x32_bf16 v[100:103], v[186:189], v[210:213], 0
	v_mfma_f32_16x16x32_bf16 v[92:95], v[194:197], v[210:213], 0
	v_mfma_f32_16x16x32_bf16 v[84:87], v[186:189], v[218:221], 0
	v_mfma_f32_16x16x32_bf16 v[76:79], v[194:197], v[218:221], 0
	v_mfma_f32_16x16x32_bf16 v[68:71], v[186:189], v[226:229], 0
	v_mfma_f32_16x16x32_bf16 v[64:67], v[194:197], v[226:229], 0
	v_mfma_f32_16x16x32_bf16 v[116:119], v[190:193], v[206:209], v[116:119]
	v_mfma_f32_16x16x32_bf16 v[108:111], v[198:201], v[206:209], v[108:111]
	v_mfma_f32_16x16x32_bf16 v[100:103], v[190:193], v[214:217], v[100:103]
	v_mfma_f32_16x16x32_bf16 v[92:95], v[198:201], v[214:217], v[92:95]
	v_mfma_f32_16x16x32_bf16 v[84:87], v[190:193], v[222:225], v[84:87]
	v_mfma_f32_16x16x32_bf16 v[76:79], v[198:201], v[222:225], v[76:79]
	v_mfma_f32_16x16x32_bf16 v[68:71], v[190:193], v[230:233], v[68:71]
	v_mfma_f32_16x16x32_bf16 v[64:67], v[198:201], v[230:233], v[64:67]
	s_barrier
	s_setprio 0
	s_add_i32 s47, s44, s8
	v_lshl_add_u64 v[158:159], s[52:53], 0, v[130:131]
	s_mov_b32 m0, s47
	ds_read_b128 v[202:205], v165 offset:16384
	ds_read_b128 v[206:209], v165 offset:17408
	ds_read_b128 v[210:213], v165 offset:18432
	ds_read_b128 v[214:217], v165 offset:19456
	ds_read_b128 v[218:221], v165 offset:20480
	ds_read_b128 v[222:225], v165 offset:21504
	ds_read_b128 v[226:229], v165 offset:22528
	ds_read_b128 v[230:233], v165 offset:23552
	global_load_lds_dwordx4 v[158:159], off
	s_add_i32 m0, s47, 0x2000
	s_add_u32 s66, s52, 0x80000
	v_lshl_add_u64 v[182:183], s[52:53], 0, v[134:135]
	s_addc_u32 s67, s53, 0
	s_add_i32 s47, s45, s8
	global_load_lds_dwordx4 v[182:183], off
	v_lshl_add_u64 v[234:235], s[66:67], 0, v[130:131]
	s_mov_b32 m0, s47
	v_lshl_add_u64 v[236:237], s[58:59], 0, v[132:133]
	global_load_lds_dwordx4 v[234:235], off
	v_lshl_add_u64 v[234:235], s[66:67], 0, v[134:135]
	s_add_i32 m0, s47, 0x2000
	s_nop 0
	global_load_lds_dwordx4 v[234:235], off
	v_lshl_add_u64 v[234:235], s[58:59], 0, v[128:129]
	s_mov_b32 m0, s9
	s_nop 0
	global_load_lds_dwordx4 v[234:235], off
	s_mov_b32 m0, s10
	s_nop 0
	global_load_lds_dwordx4 v[236:237], off
	s_waitcnt vmcnt(8)
	s_waitcnt lgkmcnt(0)
	s_setprio 1
	s_barrier
; #define PG8_STAGE(bufoff, gbase, voff) do { _Pragma("unroll") for (int _i = 0; _i < 2; ++_i) \
;         __builtin_amdgcn_global_load_lds((const unsigned*)((const char*)(gbase) + (voff)[_i]), (PG8_LAS unsigned*)(lds + (bufoff) + ldsw + _i * 8192), 16, 0, 0); } while (0)
; #define PG8_LDA(dst, b, h) do { _Pragma("unroll") for (int m = 0; m < 4; ++m) _Pragma("unroll") for (int k = 0; k < 2; ++k) dst[m][k] = *(const PG8_LAS bf16x8*)(lds + PG8_SA(b, h) + aoff + m * 2048 + k * 1024); } while (0)
; #define PG8_LDB(dst, b, h) do { _Pragma("unroll") for (int n = 0; n < 2; ++n) _Pragma("unroll") for (int k = 0; k < 2; ++k) dst[n][k] = *(const PG8_LAS bf16x8*)(lds + PG8_SB(b, h) + boff + n * 2048 + k * 1024); } while (0)
; #define PG8_MMA(ai, bj, At, Bt) do { __builtin_amdgcn_s_setprio(1); _Pragma("unroll") for (int m = 0; m < 4; ++m) _Pragma("unroll") for (int n = 0; n < 2; ++n) _Pragma("unroll") for (int k = 0; k < 2; ++k) \
;         acc[ai][bj][m][n] = __builtin_amdgcn_mfma_f32_16x16x32_bf16(Bt[n][k], At[m][k], acc[ai][bj][m][n], 0, 0, 0); __builtin_amdgcn_s_setprio(0); } while (0)
; #define PG8_WAIT_V(n) asm volatile("s_waitcnt vmcnt(" #n ")" ::: "memory")
; #define PG8_WAIT_L(n) asm volatile("s_waitcnt lgkmcnt(" #n ")" ::: "memory")
; #define PG8_BAR __builtin_amdgcn_s_barrier()
; #define PG8_SCHED __builtin_amdgcn_sched_barrier(0)
; template <class Epi, class Sched, bool ALIGN_EPI = false, bool SP2 = false>
; __device__ __forceinline__ void gemm_phase(PG8_LAS unsigned char* lds, const Gemm g, const Sched& S, const Epi& E) {
;     ...
;             if constexpr (SP2) {
;             PG8_LDB(B0, 0, 0); PG8_LDB(B1, 0, 1); PG8_SCHED; PG8_LDA(At, 0, 0); PG8_STAGE(PG8_SA(1, 1), a1 + hstepA, voffA);
;             PG8_WAIT_V(8); PG8_WAIT_L(0); PG8_BAR; PG8_MMA(0, 0, At, B0); PG8_MMA(0, 1, At, B1); PG8_BAR; PG8_SCHED;
;             PG8_LDA(At, 0, 1); PG8_STAGE(PG8_SB(0, 0), b2, voffB); PG8_STAGE(PG8_SB(0, 1), b2 + hstepB, voffB); PG8_STAGE(PG8_SA(0, 0), a2, voffA);
;             PG8_WAIT_V(8); PG8_WAIT_L(0); PG8_BAR; PG8_MMA(1, 0, At, B0); PG8_MMA(1, 1, At, B1); PG8_BAR; PG8_SCHED;
;             PG8_LDB(B0, 1, 0); PG8_LDB(B1, 1, 1); PG8_SCHED; PG8_LDA(At, 1, 0); PG8_STAGE(PG8_SA(0, 1), a2 + hstepA, voffA);
;             PG8_WAIT_V(8); PG8_WAIT_L(0); PG8_BAR; PG8_MMA(0, 0, At, B0); PG8_MMA(0, 1, At, B1); PG8_BAR; PG8_SCHED;
	v_mfma_f32_16x16x32_bf16 v[60:63], v[166:169], v[202:205], 0
	v_mfma_f32_16x16x32_bf16 v[56:59], v[174:177], v[202:205], 0
	v_mfma_f32_16x16x32_bf16 v[48:51], v[166:169], v[210:213], 0
	v_mfma_f32_16x16x32_bf16 v[40:43], v[174:177], v[210:213], 0
	v_mfma_f32_16x16x32_bf16 v[32:35], v[166:169], v[218:221], 0
	v_mfma_f32_16x16x32_bf16 v[24:27], v[174:177], v[218:221], 0
	v_mfma_f32_16x16x32_bf16 v[16:19], v[166:169], v[226:229], 0
	v_mfma_f32_16x16x32_bf16 v[8:11], v[174:177], v[226:229], 0
	v_mfma_f32_16x16x32_bf16 v[60:63], v[170:173], v[206:209], v[60:63]
	v_mfma_f32_16x16x32_bf16 v[56:59], v[178:181], v[206:209], v[56:59]
	v_mfma_f32_16x16x32_bf16 v[48:51], v[170:173], v[214:217], v[48:51]
	v_mfma_f32_16x16x32_bf16 v[40:43], v[178:181], v[214:217], v[40:43]
	v_mfma_f32_16x16x32_bf16 v[32:35], v[170:173], v[222:225], v[32:35]
	v_mfma_f32_16x16x32_bf16 v[24:27], v[178:181], v[222:225], v[24:27]
	v_mfma_f32_16x16x32_bf16 v[16:19], v[170:173], v[230:233], v[16:19]
	v_mfma_f32_16x16x32_bf16 v[8:11], v[178:181], v[230:233], v[8:11]
	s_setprio 0
	s_setprio 1
	v_mfma_f32_16x16x32_bf16 v[52:55], v[186:189], v[202:205], 0
	v_mfma_f32_16x16x32_bf16 v[44:47], v[194:197], v[202:205], 0
	v_mfma_f32_16x16x32_bf16 v[36:39], v[186:189], v[210:213], 0
	v_mfma_f32_16x16x32_bf16 v[28:31], v[194:197], v[210:213], 0
	v_mfma_f32_16x16x32_bf16 v[20:23], v[186:189], v[218:221], 0
	v_mfma_f32_16x16x32_bf16 v[12:15], v[194:197], v[218:221], 0
	v_mfma_f32_16x16x32_bf16 v[4:7], v[186:189], v[226:229], 0
	v_mfma_f32_16x16x32_bf16 v[0:3], v[194:197], v[226:229], 0
	v_mfma_f32_16x16x32_bf16 v[52:55], v[190:193], v[206:209], v[52:55]
	v_mfma_f32_16x16x32_bf16 v[44:47], v[198:201], v[206:209], v[44:47]
	v_mfma_f32_16x16x32_bf16 v[36:39], v[190:193], v[214:217], v[36:39]
	v_mfma_f32_16x16x32_bf16 v[28:31], v[198:201], v[214:217], v[28:31]
	v_mfma_f32_16x16x32_bf16 v[20:23], v[190:193], v[222:225], v[20:23]
	v_mfma_f32_16x16x32_bf16 v[12:15], v[198:201], v[222:225], v[12:15]
	v_mfma_f32_16x16x32_bf16 v[4:7], v[190:193], v[230:233], v[4:7]
	v_mfma_f32_16x16x32_bf16 v[0:3], v[198:201], v[230:233], v[0:3]
	s_barrier
	s_setprio 0
	s_add_i32 s47, 0, 0x18000
	s_add_i32 s55, 0, 0x1c000
	v_add_u32_e32 v178, s47, v160
	v_add_u32_e32 v185, s55, v160
	ds_read_b128 v[166:169], v178
	ds_read_b128 v[170:173], v178 offset:1024
	ds_read_b128 v[174:177], v178 offset:2048
	ds_read_b128 v[178:181], v178 offset:3072
	ds_read_b128 v[186:189], v185
	ds_read_b128 v[190:193], v185 offset:1024
	ds_read_b128 v[194:197], v185 offset:2048
	ds_read_b128 v[198:201], v185 offset:3072
	s_add_u32 s58, s58, 0x80000
	s_addc_u32 s59, s59, 0
	s_mov_b32 m0, s11
	v_lshl_add_u64 v[238:239], s[58:59], 0, v[128:129]
	ds_read_b128 v[202:205], v165 offset:32768
	ds_read_b128 v[206:209], v165 offset:33792
	ds_read_b128 v[210:213], v165 offset:34816
	ds_read_b128 v[214:217], v165 offset:35840
	ds_read_b128 v[218:221], v165 offset:36864
	ds_read_b128 v[222:225], v165 offset:37888
	ds_read_b128 v[226:229], v165 offset:38912
	ds_read_b128 v[230:233], v165 offset:39936
	global_load_lds_dwordx4 v[238:239], off
	v_lshl_add_u64 v[238:239], s[58:59], 0, v[132:133]
	s_mov_b32 m0, s12
	s_nop 0
	global_load_lds_dwordx4 v[238:239], off
	s_waitcnt vmcnt(8)
	s_waitcnt lgkmcnt(0)
	s_setprio 1
	s_barrier
	v_mfma_f32_16x16x32_bf16 v[124:127], v[166:169], v[202:205], v[124:127]
	v_mfma_f32_16x16x32_bf16 v[120:123], v[174:177], v[202:205], v[120:123]
	v_mfma_f32_16x16x32_bf16 v[112:115], v[166:169], v[210:213], v[112:115]
	v_mfma_f32_16x16x32_bf16 v[104:107], v[174:177], v[210:213], v[104:107]
	v_mfma_f32_16x16x32_bf16 v[96:99], v[166:169], v[218:221], v[96:99]
	v_mfma_f32_16x16x32_bf16 v[88:91], v[174:177], v[218:221], v[88:91]
	v_mfma_f32_16x16x32_bf16 v[80:83], v[166:169], v[226:229], v[80:83]
	v_mfma_f32_16x16x32_bf16 v[72:75], v[174:177], v[226:229], v[72:75]
	v_mfma_f32_16x16x32_bf16 v[124:127], v[170:173], v[206:209], v[124:127]
	v_mfma_f32_16x16x32_bf16 v[120:123], v[178:181], v[206:209], v[120:123]
	v_mfma_f32_16x16x32_bf16 v[112:115], v[170:173], v[214:217], v[112:115]
	v_mfma_f32_16x16x32_bf16 v[104:107], v[178:181], v[214:217], v[104:107]
	v_mfma_f32_16x16x32_bf16 v[96:99], v[170:173], v[222:225], v[96:99]
	v_mfma_f32_16x16x32_bf16 v[88:91], v[178:181], v[222:225], v[88:91]
	v_mfma_f32_16x16x32_bf16 v[80:83], v[170:173], v[230:233], v[80:83]
	v_mfma_f32_16x16x32_bf16 v[72:75], v[178:181], v[230:233], v[72:75]
	s_setprio 0
	s_setprio 1
	v_mfma_f32_16x16x32_bf16 v[116:119], v[186:189], v[202:205], v[116:119]
	v_mfma_f32_16x16x32_bf16 v[108:111], v[194:197], v[202:205], v[108:111]
	v_mfma_f32_16x16x32_bf16 v[100:103], v[186:189], v[210:213], v[100:103]
	v_mfma_f32_16x16x32_bf16 v[92:95], v[194:197], v[210:213], v[92:95]
	v_mfma_f32_16x16x32_bf16 v[84:87], v[186:189], v[218:221], v[84:87]
	v_mfma_f32_16x16x32_bf16 v[76:79], v[194:197], v[218:221], v[76:79]
	v_mfma_f32_16x16x32_bf16 v[68:71], v[186:189], v[226:229], v[68:71]
	v_mfma_f32_16x16x32_bf16 v[64:67], v[194:197], v[226:229], v[64:67]
	v_mfma_f32_16x16x32_bf16 v[116:119], v[190:193], v[206:209], v[116:119]
	v_mfma_f32_16x16x32_bf16 v[108:111], v[198:201], v[206:209], v[108:111]
	v_mfma_f32_16x16x32_bf16 v[100:103], v[190:193], v[214:217], v[100:103]
	v_mfma_f32_16x16x32_bf16 v[92:95], v[198:201], v[214:217], v[92:95]
	v_mfma_f32_16x16x32_bf16 v[84:87], v[190:193], v[222:225], v[84:87]
	v_mfma_f32_16x16x32_bf16 v[76:79], v[198:201], v[222:225], v[76:79]
	v_mfma_f32_16x16x32_bf16 v[68:71], v[190:193], v[230:233], v[68:71]
	v_mfma_f32_16x16x32_bf16 v[64:67], v[198:201], v[230:233], v[64:67]
	s_barrier
; #define PG8_STAGE(bufoff, gbase, voff) do { _Pragma("unroll") for (int _i = 0; _i < 2; ++_i) \
;         __builtin_amdgcn_global_load_lds((const unsigned*)((const char*)(gbase) + (voff)[_i]), (PG8_LAS unsigned*)(lds + (bufoff) + ldsw + _i * 8192), 16, 0, 0); } while (0)
; #define PG8_LDA(dst, b, h) do { _Pragma("unroll") for (int m = 0; m < 4; ++m) _Pragma("unroll") for (int k = 0; k < 2; ++k) dst[m][k] = *(const PG8_LAS bf16x8*)(lds + PG8_SA(b, h) + aoff + m * 2048 + k * 1024); } while (0)
; #define PG8_MMA(ai, bj, At, Bt) do { __builtin_amdgcn_s_setprio(1); _Pragma("unroll") for (int m = 0; m < 4; ++m) _Pragma("unroll") for (int n = 0; n < 2; ++n) _Pragma("unroll") for (int k = 0; k < 2; ++k) \
;         acc[ai][bj][m][n] = __builtin_amdgcn_mfma_f32_16x16x32_bf16(Bt[n][k], At[m][k], acc[ai][bj][m][n], 0, 0, 0); __builtin_amdgcn_s_setprio(0); } while (0)
; #define PG8_WAIT_V(n) asm volatile("s_waitcnt vmcnt(" #n ")" ::: "memory")
; #define PG8_WAIT_L(n) asm volatile("s_waitcnt lgkmcnt(" #n ")" ::: "memory")
; #define PG8_BAR __builtin_amdgcn_s_barrier()
; #define PG8_SCHED __builtin_amdgcn_sched_barrier(0)
; template <class Epi, class Sched, bool ALIGN_EPI = false, bool SP2 = false>
; __device__ __forceinline__ void gemm_phase(PG8_LAS unsigned char* lds, const Gemm g, const Sched& S, const Epi& E) {
;     ...
;             PG8_LDA(At, 1, 1); PG8_STAGE(PG8_SB(1, 0), b3, voffB); PG8_STAGE(PG8_SB(1, 1), b3 + hstepB, voffB); PG8_STAGE(PG8_SA(1, 0), a3, voffA);
;             PG8_WAIT_V(8); PG8_WAIT_L(0); PG8_BAR; PG8_MMA(1, 0, At, B0); PG8_MMA(1, 1, At, B1); PG8_BAR; PG8_SCHED;
	s_setprio 0
	s_add_i32 s47, s47, s8
	v_lshl_add_u64 v[158:159], v[158:159], 0, s[38:39]
	s_mov_b32 m0, s47
	ds_read_b128 v[202:205], v165 offset:49152
	ds_read_b128 v[206:209], v165 offset:50176
	ds_read_b128 v[210:213], v165 offset:51200
	ds_read_b128 v[214:217], v165 offset:52224
	ds_read_b128 v[218:221], v165 offset:53248
	ds_read_b128 v[222:225], v165 offset:54272
	ds_read_b128 v[226:229], v165 offset:55296
	ds_read_b128 v[230:233], v165 offset:56320
	global_load_lds_dwordx4 v[158:159], off
	s_add_i32 m0, s47, 0x2000
	s_add_u32 s52, s52, 0x80080
	v_lshl_add_u64 v[158:159], v[182:183], 0, s[38:39]
	s_addc_u32 s53, s53, 0
	s_add_i32 s47, s55, s8
	global_load_lds_dwordx4 v[158:159], off
	v_lshl_add_u64 v[158:159], s[52:53], 0, v[130:131]
	s_mov_b32 m0, s47
	s_nop 0
	global_load_lds_dwordx4 v[158:159], off
	v_lshl_add_u64 v[158:159], s[52:53], 0, v[134:135]
	s_add_i32 m0, s47, 0x2000
	s_nop 0
	global_load_lds_dwordx4 v[158:159], off
	v_lshl_add_u64 v[158:159], v[234:235], 0, s[38:39]
	s_mov_b32 m0, s13
	s_nop 0
	global_load_lds_dwordx4 v[158:159], off
	v_lshl_add_u64 v[158:159], v[236:237], 0, s[38:39]
	s_mov_b32 m0, s33
	s_nop 0
	global_load_lds_dwordx4 v[158:159], off
	s_waitcnt vmcnt(8)
	s_waitcnt lgkmcnt(0)
	s_setprio 1
	s_barrier
	v_mfma_f32_16x16x32_bf16 v[60:63], v[166:169], v[202:205], v[60:63]
	v_mfma_f32_16x16x32_bf16 v[56:59], v[174:177], v[202:205], v[56:59]
	v_mfma_f32_16x16x32_bf16 v[48:51], v[166:169], v[210:213], v[48:51]
	v_mfma_f32_16x16x32_bf16 v[40:43], v[174:177], v[210:213], v[40:43]
	v_mfma_f32_16x16x32_bf16 v[32:35], v[166:169], v[218:221], v[32:35]
	v_mfma_f32_16x16x32_bf16 v[24:27], v[174:177], v[218:221], v[24:27]
	v_mfma_f32_16x16x32_bf16 v[16:19], v[166:169], v[226:229], v[16:19]
	v_mfma_f32_16x16x32_bf16 v[8:11], v[174:177], v[226:229], v[8:11]
	v_mfma_f32_16x16x32_bf16 v[60:63], v[170:173], v[206:209], v[60:63]
	v_mfma_f32_16x16x32_bf16 v[56:59], v[178:181], v[206:209], v[56:59]
	v_mfma_f32_16x16x32_bf16 v[48:51], v[170:173], v[214:217], v[48:51]
	v_mfma_f32_16x16x32_bf16 v[40:43], v[178:181], v[214:217], v[40:43]
	v_mfma_f32_16x16x32_bf16 v[32:35], v[170:173], v[222:225], v[32:35]
	v_mfma_f32_16x16x32_bf16 v[24:27], v[178:181], v[222:225], v[24:27]
	v_mfma_f32_16x16x32_bf16 v[16:19], v[170:173], v[230:233], v[16:19]
	v_mfma_f32_16x16x32_bf16 v[8:11], v[178:181], v[230:233], v[8:11]
	s_setprio 0
	s_setprio 1
	v_mfma_f32_16x16x32_bf16 v[52:55], v[186:189], v[202:205], v[52:55]
	v_mfma_f32_16x16x32_bf16 v[44:47], v[194:197], v[202:205], v[44:47]
	v_mfma_f32_16x16x32_bf16 v[36:39], v[186:189], v[210:213], v[36:39]
	v_mfma_f32_16x16x32_bf16 v[28:31], v[194:197], v[210:213], v[28:31]
	v_mfma_f32_16x16x32_bf16 v[20:23], v[186:189], v[218:221], v[20:23]
	v_mfma_f32_16x16x32_bf16 v[12:15], v[194:197], v[218:221], v[12:15]
	v_mfma_f32_16x16x32_bf16 v[4:7], v[186:189], v[226:229], v[4:7]
	v_mfma_f32_16x16x32_bf16 v[0:3], v[194:197], v[226:229], v[0:3]
	v_mfma_f32_16x16x32_bf16 v[52:55], v[190:193], v[206:209], v[52:55]
	v_mfma_f32_16x16x32_bf16 v[44:47], v[198:201], v[206:209], v[44:47]
	v_mfma_f32_16x16x32_bf16 v[36:39], v[190:193], v[214:217], v[36:39]
	v_mfma_f32_16x16x32_bf16 v[28:31], v[198:201], v[214:217], v[28:31]
	v_mfma_f32_16x16x32_bf16 v[20:23], v[190:193], v[222:225], v[20:23]
	v_mfma_f32_16x16x32_bf16 v[12:15], v[198:201], v[222:225], v[12:15]
	v_mfma_f32_16x16x32_bf16 v[4:7], v[190:193], v[230:233], v[4:7]
	v_mfma_f32_16x16x32_bf16 v[0:3], v[198:201], v[230:233], v[0:3]
	s_barrier
	s_setprio 0
	s_add_i32 s46, s46, 2
	s_add_u32 s50, s50, 0x100
	s_addc_u32 s51, s51, 0
	s_add_u32 s4, s4, 0x100
	s_addc_u32 s5, s5, 0
	s_cmp_gt_u32 s46, 29
	s_cbranch_scc1 .Lmy_peel_2_exit

; #define PG8_BAR __builtin_amdgcn_s_barrier()
; template <class Epi, class Sched, bool ALIGN_EPI = false, bool SP2 = false>
; __device__ __forceinline__ void gemm_phase(PG8_LAS unsigned char* lds, const Gemm g, const Sched& S, const Epi& E) {
;     ...
;         if constexpr (ALIGN_EPI) { if (wr == 0) PG8_BAR; }
;         if constexpr (!Epi::AFTER_DRAIN) { E(acc, cur, wr, wc, fr, fq); S.done(cur); }
.Lmy_peel_2_exit:
	s_and_b64 vcc, exec, s[40:41]
	s_cbranch_vccz .LBB0_659
	s_barrier

; #define PG8_STAGE(bufoff, gbase, voff) do { _Pragma("unroll") for (int _i = 0; _i < 2; ++_i) \
;         __builtin_amdgcn_global_load_lds((const unsigned*)((const char*)(gbase) + (voff)[_i]), (PG8_LAS unsigned*)(lds + (bufoff) + ldsw + _i * 8192), 16, 0, 0); } while (0)
; #define PG8_LDA(dst, b, h) do { _Pragma("unroll") for (int m = 0; m < 4; ++m) _Pragma("unroll") for (int k = 0; k < 2; ++k) dst[m][k] = *(const PG8_LAS bf16x8*)(lds + PG8_SA(b, h) + aoff + m * 2048 + k * 1024); } while (0)
; #define PG8_LDB(dst, b, h) do { _Pragma("unroll") for (int n = 0; n < 2; ++n) _Pragma("unroll") for (int k = 0; k < 2; ++k) dst[n][k] = *(const PG8_LAS bf16x8*)(lds + PG8_SB(b, h) + boff + n * 2048 + k * 1024); } while (0)
; #define PG8_MMA(ai, bj, At, Bt) do { __builtin_amdgcn_s_setprio(1); _Pragma("unroll") for (int m = 0; m < 4; ++m) _Pragma("unroll") for (int n = 0; n < 2; ++n) _Pragma("unroll") for (int k = 0; k < 2; ++k) \
;         acc[ai][bj][m][n] = __builtin_amdgcn_mfma_f32_16x16x32_bf16(Bt[n][k], At[m][k], acc[ai][bj][m][n], 0, 0, 0); __builtin_amdgcn_s_setprio(0); } while (0)
; #define PG8_WAIT_V(n) asm volatile("s_waitcnt vmcnt(" #n ")" ::: "memory")
; #define PG8_WAIT_L(n) asm volatile("s_waitcnt lgkmcnt(" #n ")" ::: "memory")
; #define PG8_BAR __builtin_amdgcn_s_barrier()
; template <class Epi, class Sched, bool ALIGN_EPI = false, bool SP2 = false>
; __device__ __forceinline__ void gemm_phase(PG8_LAS unsigned char* lds, const Gemm g, const Sched& S, const Epi& E) {
;     ...
;     f32x4 acc[2][2][4][2];
; #pragma unroll
;     for (int a = 0; a < 2; ++a)
; #pragma unroll
;         for (int b = 0; b < 2; ++b)
; #pragma unroll
;             for (int m = 0; m < 4; ++m)
; #pragma unroll
;                 for (int n = 0; n < 2; ++n) acc[a][b][m][n] = (f32x4){0.f, 0.f, 0.f, 0.f};
;     ...
;             if constexpr (SP2) {
;             PG8_LDB(B0, 0, 0); PG8_LDB(B1, 0, 1); PG8_SCHED; PG8_LDA(At, 0, 0); PG8_STAGE(PG8_SA(1, 1), a1 + hstepA, voffA);
;             PG8_WAIT_V(8); PG8_WAIT_L(0); PG8_BAR; PG8_MMA(0, 0, At, B0); PG8_MMA(0, 1, At, B1); PG8_BAR; PG8_SCHED;
;             PG8_LDA(At, 0, 1); PG8_STAGE(PG8_SB(0, 0), b2, voffB); PG8_STAGE(PG8_SB(0, 1), b2 + hstepB, voffB); PG8_STAGE(PG8_SA(0, 0), a2, voffA);
;             PG8_WAIT_V(8); PG8_WAIT_L(0); PG8_BAR; PG8_MMA(1, 0, At, B0); PG8_MMA(1, 1, At, B1); PG8_BAR; PG8_SCHED;
.LBB0_1306:
	s_ashr_i32 s41, s40, 31
	s_lshl_b64 s[4:5], s[40:41], 20
	v_readlane_b32 s12, v254, 41
	v_readlane_b32 s13, v254, 42
	s_add_u32 s44, s12, s4
	s_addc_u32 s45, s13, s5
	s_and_b64 s[4:5], s[42:43], exec
	s_cselect_b32 s4, s45, s51
	s_cselect_b32 s5, s44, s50
	s_ashr_i32 s39, s38, 31
	s_lshl_b64 s[12:13], s[38:39], 20
	s_add_u32 s48, s3, s12
	s_addc_u32 s49, s10, s13
	s_and_b64 s[12:13], s[42:43], exec
	s_cselect_b32 s12, s49, s53
	s_cselect_b32 s13, s48, s52
	s_add_u32 s50, s50, 0x80080
	s_addc_u32 s51, s51, 0
	s_add_u32 s39, s52, 0x100
	s_addc_u32 s41, s53, 0
	s_mov_b32 s63, -2
	ds_read_b128 v[156:159], v152
	ds_read_b128 v[160:163], v152 offset:1024
	ds_read_b128 v[164:167], v152 offset:2048
	ds_read_b128 v[168:171], v152 offset:3072
	ds_read_b128 v[172:175], v153
	ds_read_b128 v[176:179], v153 offset:1024
	ds_read_b128 v[180:183], v153 offset:2048
	ds_read_b128 v[190:193], v153 offset:3072
	s_add_u32 s52, s50, 0xfff80080
	s_addc_u32 s53, s51, -1
	s_cmp_eq_u32 s63, 28
	s_cselect_b32 s59, s4, s53
	s_cselect_b32 s58, s5, s52
	s_cselect_b32 s53, s12, s41
	s_cselect_b32 s52, s13, s39
	v_lshl_add_u64 v[226:227], s[50:51], 0, v[142:143]
	s_add_i32 m0, s7, 0xc000
	ds_read_b128 v[194:197], v154
	ds_read_b128 v[198:201], v154 offset:1024
	ds_read_b128 v[202:205], v154 offset:2048
	ds_read_b128 v[206:209], v154 offset:3072
	ds_read_b128 v[210:213], v154 offset:4096
	ds_read_b128 v[214:217], v154 offset:5120
	ds_read_b128 v[218:221], v154 offset:6144
	ds_read_b128 v[222:225], v154 offset:7168
	global_load_lds_dwordx4 v[226:227], off
	v_lshl_add_u64 v[226:227], s[50:51], 0, v[144:145]
	s_add_i32 m0, s7, 0xe000
	s_nop 0
	global_load_lds_dwordx4 v[226:227], off
	s_waitcnt vmcnt(8)
	s_waitcnt lgkmcnt(0)
	s_setprio 1
	s_barrier
	v_mfma_f32_16x16x32_bf16 v[124:127], v[156:159], v[194:197], 0
	v_mfma_f32_16x16x32_bf16 v[120:123], v[164:167], v[194:197], 0
	v_mfma_f32_16x16x32_bf16 v[108:111], v[156:159], v[202:205], 0
	v_mfma_f32_16x16x32_bf16 v[104:107], v[164:167], v[202:205], 0
	v_mfma_f32_16x16x32_bf16 v[92:95], v[156:159], v[210:213], 0
	v_mfma_f32_16x16x32_bf16 v[88:91], v[164:167], v[210:213], 0
	v_mfma_f32_16x16x32_bf16 v[76:79], v[156:159], v[218:221], 0
	v_mfma_f32_16x16x32_bf16 v[72:75], v[164:167], v[218:221], 0
	v_mfma_f32_16x16x32_bf16 v[124:127], v[160:163], v[198:201], v[124:127]
	v_mfma_f32_16x16x32_bf16 v[120:123], v[168:171], v[198:201], v[120:123]
	v_mfma_f32_16x16x32_bf16 v[108:111], v[160:163], v[206:209], v[108:111]
	v_mfma_f32_16x16x32_bf16 v[104:107], v[168:171], v[206:209], v[104:107]
	v_mfma_f32_16x16x32_bf16 v[92:95], v[160:163], v[214:217], v[92:95]
	v_mfma_f32_16x16x32_bf16 v[88:91], v[168:171], v[214:217], v[88:91]
	v_mfma_f32_16x16x32_bf16 v[76:79], v[160:163], v[222:225], v[76:79]
	v_mfma_f32_16x16x32_bf16 v[72:75], v[168:171], v[222:225], v[72:75]
	s_setprio 0
	s_setprio 1
	v_mfma_f32_16x16x32_bf16 v[116:119], v[172:175], v[194:197], 0
	v_mfma_f32_16x16x32_bf16 v[112:115], v[180:183], v[194:197], 0
	v_mfma_f32_16x16x32_bf16 v[100:103], v[172:175], v[202:205], 0
	v_mfma_f32_16x16x32_bf16 v[96:99], v[180:183], v[202:205], 0
	v_mfma_f32_16x16x32_bf16 v[84:87], v[172:175], v[210:213], 0
	v_mfma_f32_16x16x32_bf16 v[80:83], v[180:183], v[210:213], 0
	v_mfma_f32_16x16x32_bf16 v[68:71], v[172:175], v[218:221], 0
	v_mfma_f32_16x16x32_bf16 v[64:67], v[180:183], v[218:221], 0
	v_mfma_f32_16x16x32_bf16 v[116:119], v[176:179], v[198:201], v[116:119]
	v_mfma_f32_16x16x32_bf16 v[112:115], v[190:193], v[198:201], v[112:115]
	v_mfma_f32_16x16x32_bf16 v[100:103], v[176:179], v[206:209], v[100:103]
	v_mfma_f32_16x16x32_bf16 v[96:99], v[190:193], v[206:209], v[96:99]
	v_mfma_f32_16x16x32_bf16 v[84:87], v[176:179], v[214:217], v[84:87]
	v_mfma_f32_16x16x32_bf16 v[80:83], v[190:193], v[214:217], v[80:83]
	v_mfma_f32_16x16x32_bf16 v[68:71], v[176:179], v[222:225], v[68:71]
	v_mfma_f32_16x16x32_bf16 v[64:67], v[190:193], v[222:225], v[64:67]
	s_barrier
	s_setprio 0
	s_add_i32 s64, s57, s6
	v_lshl_add_u64 v[226:227], s[52:53], 0, v[130:131]
	s_mov_b32 m0, s64
	ds_read_b128 v[194:197], v154 offset:16384
	ds_read_b128 v[198:201], v154 offset:17408
	ds_read_b128 v[202:205], v154 offset:18432
	ds_read_b128 v[206:209], v154 offset:19456
	ds_read_b128 v[210:213], v154 offset:20480
	ds_read_b128 v[214:217], v154 offset:21504
	ds_read_b128 v[218:221], v154 offset:22528
	ds_read_b128 v[222:225], v154 offset:23552
	global_load_lds_dwordx4 v[226:227], off
	s_add_i32 m0, s64, 0x2000
	s_add_u32 s64, s52, 0x80000
	v_lshl_add_u64 v[228:229], s[52:53], 0, v[134:135]
	s_addc_u32 s65, s53, 0
	s_add_i32 s66, s61, s6
	global_load_lds_dwordx4 v[228:229], off
	v_lshl_add_u64 v[230:231], s[64:65], 0, v[130:131]
	s_mov_b32 m0, s66
	v_lshl_add_u64 v[232:233], s[58:59], 0, v[132:133]
	global_load_lds_dwordx4 v[230:231], off
	v_lshl_add_u64 v[230:231], s[64:65], 0, v[134:135]
	s_add_i32 m0, s66, 0x2000
	s_nop 0
	global_load_lds_dwordx4 v[230:231], off
	v_lshl_add_u64 v[230:231], s[58:59], 0, v[128:129]
	s_mov_b32 m0, s7
	s_nop 0
	global_load_lds_dwordx4 v[230:231], off
	s_mov_b32 m0, s8
	s_nop 0
	global_load_lds_dwordx4 v[232:233], off
	s_waitcnt vmcnt(8)
	s_waitcnt lgkmcnt(0)
	s_setprio 1
	s_barrier
; #define PG8_STAGE(bufoff, gbase, voff) do { _Pragma("unroll") for (int _i = 0; _i < 2; ++_i) \
;         __builtin_amdgcn_global_load_lds((const unsigned*)((const char*)(gbase) + (voff)[_i]), (PG8_LAS unsigned*)(lds + (bufoff) + ldsw + _i * 8192), 16, 0, 0); } while (0)
; #define PG8_LDA(dst, b, h) do { _Pragma("unroll") for (int m = 0; m < 4; ++m) _Pragma("unroll") for (int k = 0; k < 2; ++k) dst[m][k] = *(const PG8_LAS bf16x8*)(lds + PG8_SA(b, h) + aoff + m * 2048 + k * 1024); } while (0)
; #define PG8_LDB(dst, b, h) do { _Pragma("unroll") for (int n = 0; n < 2; ++n) _Pragma("unroll") for (int k = 0; k < 2; ++k) dst[n][k] = *(const PG8_LAS bf16x8*)(lds + PG8_SB(b, h) + boff + n * 2048 + k * 1024); } while (0)
; #define PG8_MMA(ai, bj, At, Bt) do { __builtin_amdgcn_s_setprio(1); _Pragma("unroll") for (int m = 0; m < 4; ++m) _Pragma("unroll") for (int n = 0; n < 2; ++n) _Pragma("unroll") for (int k = 0; k < 2; ++k) \
;         acc[ai][bj][m][n] = __builtin_amdgcn_mfma_f32_16x16x32_bf16(Bt[n][k], At[m][k], acc[ai][bj][m][n], 0, 0, 0); __builtin_amdgcn_s_setprio(0); } while (0)
; #define PG8_WAIT_V(n) asm volatile("s_waitcnt vmcnt(" #n ")" ::: "memory")
; #define PG8_WAIT_L(n) asm volatile("s_waitcnt lgkmcnt(" #n ")" ::: "memory")
; #define PG8_BAR __builtin_amdgcn_s_barrier()
; #define PG8_SCHED __builtin_amdgcn_sched_barrier(0)
; template <class Epi, class Sched, bool ALIGN_EPI = false, bool SP2 = false>
; __device__ __forceinline__ void gemm_phase(PG8_LAS unsigned char* lds, const Gemm g, const Sched& S, const Epi& E) {
;     ...
;             PG8_WAIT_V(8); PG8_WAIT_L(0); PG8_BAR; PG8_MMA(0, 0, At, B0); PG8_MMA(0, 1, At, B1); PG8_BAR; PG8_SCHED;
;             PG8_LDA(At, 0, 1); PG8_STAGE(PG8_SB(0, 0), b2, voffB); PG8_STAGE(PG8_SB(0, 1), b2 + hstepB, voffB); PG8_STAGE(PG8_SA(0, 0), a2, voffA);
;             PG8_WAIT_V(8); PG8_WAIT_L(0); PG8_BAR; PG8_MMA(1, 0, At, B0); PG8_MMA(1, 1, At, B1); PG8_BAR; PG8_SCHED;
;             PG8_LDB(B0, 1, 0); PG8_LDB(B1, 1, 1); PG8_SCHED; PG8_LDA(At, 1, 0); PG8_STAGE(PG8_SA(0, 1), a2 + hstepA, voffA);
;             PG8_WAIT_V(8); PG8_WAIT_L(0); PG8_BAR; PG8_MMA(0, 0, At, B0); PG8_MMA(0, 1, At, B1); PG8_BAR; PG8_SCHED;
	v_mfma_f32_16x16x32_bf16 v[60:63], v[156:159], v[194:197], 0
	v_mfma_f32_16x16x32_bf16 v[56:59], v[164:167], v[194:197], 0
	v_mfma_f32_16x16x32_bf16 v[44:47], v[156:159], v[202:205], 0
	v_mfma_f32_16x16x32_bf16 v[40:43], v[164:167], v[202:205], 0
	v_mfma_f32_16x16x32_bf16 v[28:31], v[156:159], v[210:213], 0
	v_mfma_f32_16x16x32_bf16 v[24:27], v[164:167], v[210:213], 0
	v_mfma_f32_16x16x32_bf16 v[12:15], v[156:159], v[218:221], 0
	v_mfma_f32_16x16x32_bf16 v[8:11], v[164:167], v[218:221], 0
	v_mfma_f32_16x16x32_bf16 v[60:63], v[160:163], v[198:201], v[60:63]
	v_mfma_f32_16x16x32_bf16 v[56:59], v[168:171], v[198:201], v[56:59]
	v_mfma_f32_16x16x32_bf16 v[44:47], v[160:163], v[206:209], v[44:47]
	v_mfma_f32_16x16x32_bf16 v[40:43], v[168:171], v[206:209], v[40:43]
	v_mfma_f32_16x16x32_bf16 v[28:31], v[160:163], v[214:217], v[28:31]
	v_mfma_f32_16x16x32_bf16 v[24:27], v[168:171], v[214:217], v[24:27]
	v_mfma_f32_16x16x32_bf16 v[12:15], v[160:163], v[222:225], v[12:15]
	v_mfma_f32_16x16x32_bf16 v[8:11], v[168:171], v[222:225], v[8:11]
	s_setprio 0
	s_setprio 1
	v_mfma_f32_16x16x32_bf16 v[52:55], v[172:175], v[194:197], 0
	v_mfma_f32_16x16x32_bf16 v[48:51], v[180:183], v[194:197], 0
	v_mfma_f32_16x16x32_bf16 v[36:39], v[172:175], v[202:205], 0
	v_mfma_f32_16x16x32_bf16 v[32:35], v[180:183], v[202:205], 0
	v_mfma_f32_16x16x32_bf16 v[20:23], v[172:175], v[210:213], 0
	v_mfma_f32_16x16x32_bf16 v[16:19], v[180:183], v[210:213], 0
	v_mfma_f32_16x16x32_bf16 v[4:7], v[172:175], v[218:221], 0
	v_mfma_f32_16x16x32_bf16 v[0:3], v[180:183], v[218:221], 0
	v_mfma_f32_16x16x32_bf16 v[52:55], v[176:179], v[198:201], v[52:55]
	v_mfma_f32_16x16x32_bf16 v[48:51], v[190:193], v[198:201], v[48:51]
	v_mfma_f32_16x16x32_bf16 v[36:39], v[176:179], v[206:209], v[36:39]
	v_mfma_f32_16x16x32_bf16 v[32:35], v[190:193], v[206:209], v[32:35]
	v_mfma_f32_16x16x32_bf16 v[20:23], v[176:179], v[214:217], v[20:23]
	v_mfma_f32_16x16x32_bf16 v[16:19], v[190:193], v[214:217], v[16:19]
	v_mfma_f32_16x16x32_bf16 v[4:7], v[176:179], v[222:225], v[4:7]
	v_mfma_f32_16x16x32_bf16 v[0:3], v[190:193], v[222:225], v[0:3]
	s_barrier
	s_setprio 0
	s_add_i32 s64, 0, 0x18000
	v_add_u32_e32 v155, s64, v150
	s_add_i32 s65, 0, 0x1c000
	ds_read_b128 v[156:159], v155
	ds_read_b128 v[160:163], v155 offset:1024
	ds_read_b128 v[164:167], v155 offset:2048
	ds_read_b128 v[168:171], v155 offset:3072
	v_add_u32_e32 v155, s65, v150
	ds_read_b128 v[172:175], v155
	ds_read_b128 v[176:179], v155 offset:1024
	ds_read_b128 v[180:183], v155 offset:2048
	ds_read_b128 v[190:193], v155 offset:3072
	s_add_u32 s58, s58, 0x80000
	s_addc_u32 s59, s59, 0
	s_mov_b32 m0, s9
	v_lshl_add_u64 v[234:235], s[58:59], 0, v[128:129]
	ds_read_b128 v[194:197], v154 offset:32768
	ds_read_b128 v[198:201], v154 offset:33792
	ds_read_b128 v[202:205], v154 offset:34816
	ds_read_b128 v[206:209], v154 offset:35840
	ds_read_b128 v[210:213], v154 offset:36864
	ds_read_b128 v[214:217], v154 offset:37888
	ds_read_b128 v[218:221], v154 offset:38912
	ds_read_b128 v[222:225], v154 offset:39936
	global_load_lds_dwordx4 v[234:235], off
	v_lshl_add_u64 v[234:235], s[58:59], 0, v[132:133]
	s_mov_b32 m0, s11
	s_nop 0
	global_load_lds_dwordx4 v[234:235], off
	s_waitcnt vmcnt(8)
	s_waitcnt lgkmcnt(0)
	s_setprio 1
	s_barrier
	v_mfma_f32_16x16x32_bf16 v[124:127], v[156:159], v[194:197], v[124:127]
	v_mfma_f32_16x16x32_bf16 v[120:123], v[164:167], v[194:197], v[120:123]
	v_mfma_f32_16x16x32_bf16 v[108:111], v[156:159], v[202:205], v[108:111]
	v_mfma_f32_16x16x32_bf16 v[104:107], v[164:167], v[202:205], v[104:107]
	v_mfma_f32_16x16x32_bf16 v[92:95], v[156:159], v[210:213], v[92:95]
	v_mfma_f32_16x16x32_bf16 v[88:91], v[164:167], v[210:213], v[88:91]
	v_mfma_f32_16x16x32_bf16 v[76:79], v[156:159], v[218:221], v[76:79]
	v_mfma_f32_16x16x32_bf16 v[72:75], v[164:167], v[218:221], v[72:75]
	v_mfma_f32_16x16x32_bf16 v[124:127], v[160:163], v[198:201], v[124:127]
	v_mfma_f32_16x16x32_bf16 v[120:123], v[168:171], v[198:201], v[120:123]
	v_mfma_f32_16x16x32_bf16 v[108:111], v[160:163], v[206:209], v[108:111]
	v_mfma_f32_16x16x32_bf16 v[104:107], v[168:171], v[206:209], v[104:107]
	v_mfma_f32_16x16x32_bf16 v[92:95], v[160:163], v[214:217], v[92:95]
	v_mfma_f32_16x16x32_bf16 v[88:91], v[168:171], v[214:217], v[88:91]
	v_mfma_f32_16x16x32_bf16 v[76:79], v[160:163], v[222:225], v[76:79]
	v_mfma_f32_16x16x32_bf16 v[72:75], v[168:171], v[222:225], v[72:75]
	s_setprio 0
	s_setprio 1
	v_mfma_f32_16x16x32_bf16 v[116:119], v[172:175], v[194:197], v[116:119]
	v_mfma_f32_16x16x32_bf16 v[112:115], v[180:183], v[194:197], v[112:115]
	v_mfma_f32_16x16x32_bf16 v[100:103], v[172:175], v[202:205], v[100:103]
	v_mfma_f32_16x16x32_bf16 v[96:99], v[180:183], v[202:205], v[96:99]
	v_mfma_f32_16x16x32_bf16 v[84:87], v[172:175], v[210:213], v[84:87]
	v_mfma_f32_16x16x32_bf16 v[80:83], v[180:183], v[210:213], v[80:83]
	v_mfma_f32_16x16x32_bf16 v[68:71], v[172:175], v[218:221], v[68:71]
	v_mfma_f32_16x16x32_bf16 v[64:67], v[180:183], v[218:221], v[64:67]
	v_mfma_f32_16x16x32_bf16 v[116:119], v[176:179], v[198:201], v[116:119]
	v_mfma_f32_16x16x32_bf16 v[112:115], v[190:193], v[198:201], v[112:115]
	v_mfma_f32_16x16x32_bf16 v[100:103], v[176:179], v[206:209], v[100:103]
	v_mfma_f32_16x16x32_bf16 v[96:99], v[190:193], v[206:209], v[96:99]
	v_mfma_f32_16x16x32_bf16 v[84:87], v[176:179], v[214:217], v[84:87]
	v_mfma_f32_16x16x32_bf16 v[80:83], v[190:193], v[214:217], v[80:83]
	v_mfma_f32_16x16x32_bf16 v[68:71], v[176:179], v[222:225], v[68:71]
	v_mfma_f32_16x16x32_bf16 v[64:67], v[190:193], v[222:225], v[64:67]
	s_barrier
; #define PG8_STAGE(bufoff, gbase, voff) do { _Pragma("unroll") for (int _i = 0; _i < 2; ++_i) \
;         __builtin_amdgcn_global_load_lds((const unsigned*)((const char*)(gbase) + (voff)[_i]), (PG8_LAS unsigned*)(lds + (bufoff) + ldsw + _i * 8192), 16, 0, 0); } while (0)
; #define PG8_LDA(dst, b, h) do { _Pragma("unroll") for (int m = 0; m < 4; ++m) _Pragma("unroll") for (int k = 0; k < 2; ++k) dst[m][k] = *(const PG8_LAS bf16x8*)(lds + PG8_SA(b, h) + aoff + m * 2048 + k * 1024); } while (0)
; #define PG8_MMA(ai, bj, At, Bt) do { __builtin_amdgcn_s_setprio(1); _Pragma("unroll") for (int m = 0; m < 4; ++m) _Pragma("unroll") for (int n = 0; n < 2; ++n) _Pragma("unroll") for (int k = 0; k < 2; ++k) \
;         acc[ai][bj][m][n] = __builtin_amdgcn_mfma_f32_16x16x32_bf16(Bt[n][k], At[m][k], acc[ai][bj][m][n], 0, 0, 0); __builtin_amdgcn_s_setprio(0); } while (0)
; #define PG8_WAIT_V(n) asm volatile("s_waitcnt vmcnt(" #n ")" ::: "memory")
; #define PG8_WAIT_L(n) asm volatile("s_waitcnt lgkmcnt(" #n ")" ::: "memory")
; #define PG8_BAR __builtin_amdgcn_s_barrier()
; #define PG8_SCHED __builtin_amdgcn_sched_barrier(0)
; template <class Epi, class Sched, bool ALIGN_EPI = false, bool SP2 = false>
; __device__ __forceinline__ void gemm_phase(PG8_LAS unsigned char* lds, const Gemm g, const Sched& S, const Epi& E) {
;     ...
;         for (int t = 0; t < nt; t += 2) {
;     ...
;             PG8_LDA(At, 1, 1); PG8_STAGE(PG8_SB(1, 0), b3, voffB); PG8_STAGE(PG8_SB(1, 1), b3 + hstepB, voffB); PG8_STAGE(PG8_SA(1, 0), a3, voffA);
;             PG8_WAIT_V(8); PG8_WAIT_L(0); PG8_BAR; PG8_MMA(1, 0, At, B0); PG8_MMA(1, 1, At, B1); PG8_BAR; PG8_SCHED;
	s_setprio 0
	s_add_i32 s58, s64, s6
	v_lshl_add_u64 v[226:227], v[226:227], 0, s[20:21]
	s_mov_b32 m0, s58
	ds_read_b128 v[194:197], v154 offset:49152
	ds_read_b128 v[198:201], v154 offset:50176
	ds_read_b128 v[202:205], v154 offset:51200
	ds_read_b128 v[206:209], v154 offset:52224
	ds_read_b128 v[210:213], v154 offset:53248
	ds_read_b128 v[214:217], v154 offset:54272
	ds_read_b128 v[218:221], v154 offset:55296
	ds_read_b128 v[222:225], v154 offset:56320
	global_load_lds_dwordx4 v[226:227], off
	s_add_i32 m0, s58, 0x2000
	s_add_u32 s52, s52, 0x80080
	v_lshl_add_u64 v[226:227], v[228:229], 0, s[20:21]
	s_addc_u32 s53, s53, 0
	s_add_i32 s58, s65, s6
	global_load_lds_dwordx4 v[226:227], off
	v_lshl_add_u64 v[226:227], s[52:53], 0, v[130:131]
	s_mov_b32 m0, s58
	s_nop 0
	global_load_lds_dwordx4 v[226:227], off
	v_lshl_add_u64 v[226:227], s[52:53], 0, v[134:135]
	s_add_i32 m0, s58, 0x2000
	s_nop 0
	global_load_lds_dwordx4 v[226:227], off
	v_lshl_add_u64 v[226:227], v[230:231], 0, s[20:21]
	s_mov_b32 m0, s55
	s_nop 0
	global_load_lds_dwordx4 v[226:227], off
	v_lshl_add_u64 v[226:227], v[232:233], 0, s[20:21]
	s_mov_b32 m0, s56
	s_nop 0
	global_load_lds_dwordx4 v[226:227], off
	s_waitcnt vmcnt(8)
	s_waitcnt lgkmcnt(0)
	s_setprio 1
	s_barrier
	v_mfma_f32_16x16x32_bf16 v[60:63], v[156:159], v[194:197], v[60:63]
	v_mfma_f32_16x16x32_bf16 v[56:59], v[164:167], v[194:197], v[56:59]
	v_mfma_f32_16x16x32_bf16 v[44:47], v[156:159], v[202:205], v[44:47]
	v_mfma_f32_16x16x32_bf16 v[40:43], v[164:167], v[202:205], v[40:43]
	v_mfma_f32_16x16x32_bf16 v[28:31], v[156:159], v[210:213], v[28:31]
	v_mfma_f32_16x16x32_bf16 v[24:27], v[164:167], v[210:213], v[24:27]
	v_mfma_f32_16x16x32_bf16 v[12:15], v[156:159], v[218:221], v[12:15]
	v_mfma_f32_16x16x32_bf16 v[8:11], v[164:167], v[218:221], v[8:11]
	v_mfma_f32_16x16x32_bf16 v[60:63], v[160:163], v[198:201], v[60:63]
	v_mfma_f32_16x16x32_bf16 v[56:59], v[168:171], v[198:201], v[56:59]
	v_mfma_f32_16x16x32_bf16 v[44:47], v[160:163], v[206:209], v[44:47]
	v_mfma_f32_16x16x32_bf16 v[40:43], v[168:171], v[206:209], v[40:43]
	v_mfma_f32_16x16x32_bf16 v[28:31], v[160:163], v[214:217], v[28:31]
	v_mfma_f32_16x16x32_bf16 v[24:27], v[168:171], v[214:217], v[24:27]
	v_mfma_f32_16x16x32_bf16 v[12:15], v[160:163], v[222:225], v[12:15]
	v_mfma_f32_16x16x32_bf16 v[8:11], v[168:171], v[222:225], v[8:11]
	s_setprio 0
	s_setprio 1
	v_mfma_f32_16x16x32_bf16 v[52:55], v[172:175], v[194:197], v[52:55]
	v_mfma_f32_16x16x32_bf16 v[48:51], v[180:183], v[194:197], v[48:51]
	v_mfma_f32_16x16x32_bf16 v[36:39], v[172:175], v[202:205], v[36:39]
	v_mfma_f32_16x16x32_bf16 v[32:35], v[180:183], v[202:205], v[32:35]
	v_mfma_f32_16x16x32_bf16 v[20:23], v[172:175], v[210:213], v[20:23]
	v_mfma_f32_16x16x32_bf16 v[16:19], v[180:183], v[210:213], v[16:19]
	v_mfma_f32_16x16x32_bf16 v[4:7], v[172:175], v[218:221], v[4:7]
	v_mfma_f32_16x16x32_bf16 v[0:3], v[180:183], v[218:221], v[0:3]
	v_mfma_f32_16x16x32_bf16 v[52:55], v[176:179], v[198:201], v[52:55]
	v_mfma_f32_16x16x32_bf16 v[48:51], v[190:193], v[198:201], v[48:51]
	v_mfma_f32_16x16x32_bf16 v[36:39], v[176:179], v[206:209], v[36:39]
	v_mfma_f32_16x16x32_bf16 v[32:35], v[190:193], v[206:209], v[32:35]
	v_mfma_f32_16x16x32_bf16 v[20:23], v[176:179], v[214:217], v[20:23]
	v_mfma_f32_16x16x32_bf16 v[16:19], v[190:193], v[214:217], v[16:19]
	v_mfma_f32_16x16x32_bf16 v[4:7], v[176:179], v[222:225], v[4:7]
	v_mfma_f32_16x16x32_bf16 v[0:3], v[190:193], v[222:225], v[0:3]
	s_barrier
	s_setprio 0
	s_add_i32 s63, s63, 2
	s_add_u32 s50, s50, 0x100
	s_addc_u32 s51, s51, 0
	s_add_u32 s39, s39, 0x100
	s_addc_u32 s41, s41, 0
	s_cmp_gt_u32 s63, 29
	s_cbranch_scc1 .Lmy_peel_5_exit

; #define PG8_BAR __builtin_amdgcn_s_barrier()
; template <class Epi, class Sched, bool ALIGN_EPI = false, bool SP2 = false>
; __device__ __forceinline__ void gemm_phase(PG8_LAS unsigned char* lds, const Gemm g, const Sched& S, const Epi& E) {
;     ...
;         if constexpr (ALIGN_EPI) { if (wr == 0) PG8_BAR; }
.Lmy_peel_5_exit:
	s_and_b64 vcc, exec, s[34:35]
	s_cbranch_vccz .LBB0_1310
	s_barrier

; #define PG8_STAGE(bufoff, gbase, voff) do { _Pragma("unroll") for (int _i = 0; _i < 2; ++_i) \
;         __builtin_amdgcn_global_load_lds((const unsigned*)((const char*)(gbase) + (voff)[_i]), (PG8_LAS unsigned*)(lds + (bufoff) + ldsw + _i * 8192), 16, 0, 0); } while (0)
; #define PG8_LDA(dst, b, h) do { _Pragma("unroll") for (int m = 0; m < 4; ++m) _Pragma("unroll") for (int k = 0; k < 2; ++k) dst[m][k] = *(const PG8_LAS bf16x8*)(lds + PG8_SA(b, h) + aoff + m * 2048 + k * 1024); } while (0)
; #define PG8_LDB(dst, b, h) do { _Pragma("unroll") for (int n = 0; n < 2; ++n) _Pragma("unroll") for (int k = 0; k < 2; ++k) dst[n][k] = *(const PG8_LAS bf16x8*)(lds + PG8_SB(b, h) + boff + n * 2048 + k * 1024); } while (0)
; #define PG8_WAIT_V(n) asm volatile("s_waitcnt vmcnt(" #n ")" ::: "memory")
; #define PG8_WAIT_L(n) asm volatile("s_waitcnt lgkmcnt(" #n ")" ::: "memory")
; #define PG8_BAR __builtin_amdgcn_s_barrier()
; template <class Epi, class Sched, bool ALIGN_EPI = false, bool SP2 = false>
; __device__ __forceinline__ void gemm_phase(PG8_LAS unsigned char* lds, const Gemm g, const Sched& S, const Epi& E) {
;     ...
;         const char* nA = has_next ? (const char*)g.A + (size_t)nxt.pm * tstepA + (size_t)nxt.z * g.azs + (size_t)(nxt.k0 >> 6) * kstA : cA; const char* nB = has_next ? (const char*)g.Bt + (size_t)nxt.pn * tstepB + (size_t)nxt.z * g.bzs + (size_t)nxt.k0 * 2 : cB;
;         const int nt = cur.nt;
;         for (int t = 0; t < nt; t += 2) {
;             const bool last = (t == nt - 2);
;             const char* a1 = cA + (size_t)(t + 1) * kstA;
;             const char* a2 = last ? nA : cA + (size_t)(t + 2) * kstA; const char* b2 = last ? nB : cB + (size_t)(t + 2) * kstep;
;             const char* a3 = a2 + kstA; const char* b3 = b2 + kstep;
;             if (last && has_next) S.a_ready(nxt);
;             if constexpr (SP2) {
;             PG8_LDB(B0, 0, 0); PG8_LDB(B1, 0, 1); PG8_SCHED; PG8_LDA(At, 0, 0); PG8_STAGE(PG8_SA(1, 1), a1 + hstepA, voffA);
;             PG8_WAIT_V(8); PG8_WAIT_L(0); PG8_BAR; PG8_MMA(0, 0, At, B0); PG8_MMA(0, 1, At, B1); PG8_BAR; PG8_SCHED;
;             PG8_LDA(At, 0, 1); PG8_STAGE(PG8_SB(0, 0), b2, voffB); PG8_STAGE(PG8_SB(0, 1), b2 + hstepB, voffB); PG8_STAGE(PG8_SA(0, 0), a2, voffA);
;             PG8_WAIT_V(8); PG8_WAIT_L(0); PG8_BAR; PG8_MMA(1, 0, At, B0); PG8_MMA(1, 1, At, B1); PG8_BAR; PG8_SCHED;
.LBB0_1656:
	s_ashr_i32 s41, s40, 31
	s_lshl_b64 s[4:5], s[40:41], 20
	v_readlane_b32 s12, v254, 41
	v_readlane_b32 s13, v254, 42
	s_add_u32 s48, s12, s4
	s_addc_u32 s49, s13, s5
	s_and_b64 s[4:5], s[44:45], exec
	s_cselect_b32 s4, s49, s51
	s_cselect_b32 s5, s48, s50
	s_ashr_i32 s39, s38, 31
	s_lshl_b64 s[12:13], s[38:39], 20
	s_add_u32 s54, s3, s12
	s_addc_u32 s55, s10, s13
	s_and_b64 s[12:13], s[44:45], exec
	s_cselect_b32 s12, s55, s53
	s_cselect_b32 s13, s54, s52
	s_add_u32 s50, s50, 0x80080
	s_addc_u32 s51, s51, 0
	s_add_u32 s39, s52, 0x100
	s_addc_u32 s41, s53, 0
	s_mov_b32 s63, -2
	ds_read_b128 v[156:159], v152
	ds_read_b128 v[160:163], v152 offset:1024
	ds_read_b128 v[164:167], v152 offset:2048
	ds_read_b128 v[168:171], v152 offset:3072
	ds_read_b128 v[172:175], v153
	ds_read_b128 v[176:179], v153 offset:1024
	ds_read_b128 v[180:183], v153 offset:2048
	ds_read_b128 v[190:193], v153 offset:3072
	s_add_u32 s52, s50, 0xfff80080
	s_addc_u32 s53, s51, -1
	s_cmp_eq_u32 s63, 28
	s_cselect_b32 s59, s4, s53
	s_cselect_b32 s58, s5, s52
	s_cselect_b32 s53, s12, s41
	s_cselect_b32 s52, s13, s39
	v_lshl_add_u64 v[226:227], s[50:51], 0, v[142:143]
	s_add_i32 m0, s7, 0xc000
	ds_read_b128 v[194:197], v154
	ds_read_b128 v[198:201], v154 offset:1024
	ds_read_b128 v[202:205], v154 offset:2048
	ds_read_b128 v[206:209], v154 offset:3072
	ds_read_b128 v[210:213], v154 offset:4096
	ds_read_b128 v[214:217], v154 offset:5120
	ds_read_b128 v[218:221], v154 offset:6144
	ds_read_b128 v[222:225], v154 offset:7168
	global_load_lds_dwordx4 v[226:227], off
	v_lshl_add_u64 v[226:227], s[50:51], 0, v[144:145]
	s_add_i32 m0, s7, 0xe000
	s_nop 0
	global_load_lds_dwordx4 v[226:227], off
	s_waitcnt vmcnt(8)
	s_waitcnt lgkmcnt(0)
	s_setprio 1
	s_barrier
	v_mfma_f32_16x16x32_bf16 v[124:127], v[156:159], v[194:197], 0
	v_mfma_f32_16x16x32_bf16 v[120:123], v[164:167], v[194:197], 0
	v_mfma_f32_16x16x32_bf16 v[108:111], v[156:159], v[202:205], 0
	v_mfma_f32_16x16x32_bf16 v[104:107], v[164:167], v[202:205], 0
	v_mfma_f32_16x16x32_bf16 v[92:95], v[156:159], v[210:213], 0
	v_mfma_f32_16x16x32_bf16 v[88:91], v[164:167], v[210:213], 0
	v_mfma_f32_16x16x32_bf16 v[76:79], v[156:159], v[218:221], 0
	v_mfma_f32_16x16x32_bf16 v[72:75], v[164:167], v[218:221], 0
	v_mfma_f32_16x16x32_bf16 v[124:127], v[160:163], v[198:201], v[124:127]
	v_mfma_f32_16x16x32_bf16 v[120:123], v[168:171], v[198:201], v[120:123]
	v_mfma_f32_16x16x32_bf16 v[108:111], v[160:163], v[206:209], v[108:111]
	v_mfma_f32_16x16x32_bf16 v[104:107], v[168:171], v[206:209], v[104:107]
	v_mfma_f32_16x16x32_bf16 v[92:95], v[160:163], v[214:217], v[92:95]
	v_mfma_f32_16x16x32_bf16 v[88:91], v[168:171], v[214:217], v[88:91]
	v_mfma_f32_16x16x32_bf16 v[76:79], v[160:163], v[222:225], v[76:79]
	v_mfma_f32_16x16x32_bf16 v[72:75], v[168:171], v[222:225], v[72:75]
	s_setprio 0
	s_setprio 1
	v_mfma_f32_16x16x32_bf16 v[116:119], v[172:175], v[194:197], 0
	v_mfma_f32_16x16x32_bf16 v[112:115], v[180:183], v[194:197], 0
	v_mfma_f32_16x16x32_bf16 v[100:103], v[172:175], v[202:205], 0
	v_mfma_f32_16x16x32_bf16 v[96:99], v[180:183], v[202:205], 0
	v_mfma_f32_16x16x32_bf16 v[84:87], v[172:175], v[210:213], 0
	v_mfma_f32_16x16x32_bf16 v[80:83], v[180:183], v[210:213], 0
	v_mfma_f32_16x16x32_bf16 v[68:71], v[172:175], v[218:221], 0
	v_mfma_f32_16x16x32_bf16 v[64:67], v[180:183], v[218:221], 0
	v_mfma_f32_16x16x32_bf16 v[116:119], v[176:179], v[198:201], v[116:119]
	v_mfma_f32_16x16x32_bf16 v[112:115], v[190:193], v[198:201], v[112:115]
	v_mfma_f32_16x16x32_bf16 v[100:103], v[176:179], v[206:209], v[100:103]
	v_mfma_f32_16x16x32_bf16 v[96:99], v[190:193], v[206:209], v[96:99]
	v_mfma_f32_16x16x32_bf16 v[84:87], v[176:179], v[214:217], v[84:87]
	v_mfma_f32_16x16x32_bf16 v[80:83], v[190:193], v[214:217], v[80:83]
	v_mfma_f32_16x16x32_bf16 v[68:71], v[176:179], v[222:225], v[68:71]
	v_mfma_f32_16x16x32_bf16 v[64:67], v[190:193], v[222:225], v[64:67]
	s_barrier
	s_setprio 0
	s_add_i32 s64, s56, s6
	v_lshl_add_u64 v[226:227], s[52:53], 0, v[130:131]
	s_mov_b32 m0, s64
	ds_read_b128 v[194:197], v154 offset:16384
	ds_read_b128 v[198:201], v154 offset:17408
	ds_read_b128 v[202:205], v154 offset:18432
	ds_read_b128 v[206:209], v154 offset:19456
	ds_read_b128 v[210:213], v154 offset:20480
	ds_read_b128 v[214:217], v154 offset:21504
	ds_read_b128 v[218:221], v154 offset:22528
	ds_read_b128 v[222:225], v154 offset:23552
	global_load_lds_dwordx4 v[226:227], off
	s_add_i32 m0, s64, 0x2000
	s_add_u32 s64, s52, 0x80000
	v_lshl_add_u64 v[228:229], s[52:53], 0, v[134:135]
	s_addc_u32 s65, s53, 0
	s_add_i32 s66, s57, s6
	global_load_lds_dwordx4 v[228:229], off
	v_lshl_add_u64 v[230:231], s[64:65], 0, v[130:131]
	s_mov_b32 m0, s66
	v_lshl_add_u64 v[232:233], s[58:59], 0, v[132:133]
	global_load_lds_dwordx4 v[230:231], off
	v_lshl_add_u64 v[230:231], s[64:65], 0, v[134:135]
	s_add_i32 m0, s66, 0x2000
	s_nop 0
	global_load_lds_dwordx4 v[230:231], off
	v_lshl_add_u64 v[230:231], s[58:59], 0, v[128:129]
	s_mov_b32 m0, s7
	s_nop 0
	global_load_lds_dwordx4 v[230:231], off
	s_mov_b32 m0, s8
	s_nop 0
	global_load_lds_dwordx4 v[232:233], off
	s_waitcnt vmcnt(8)
	s_waitcnt lgkmcnt(0)
	s_setprio 1
	s_barrier
; #define PG8_STAGE(bufoff, gbase, voff) do { _Pragma("unroll") for (int _i = 0; _i < 2; ++_i) \
;         __builtin_amdgcn_global_load_lds((const unsigned*)((const char*)(gbase) + (voff)[_i]), (PG8_LAS unsigned*)(lds + (bufoff) + ldsw + _i * 8192), 16, 0, 0); } while (0)
; #define PG8_LDA(dst, b, h) do { _Pragma("unroll") for (int m = 0; m < 4; ++m) _Pragma("unroll") for (int k = 0; k < 2; ++k) dst[m][k] = *(const PG8_LAS bf16x8*)(lds + PG8_SA(b, h) + aoff + m * 2048 + k * 1024); } while (0)
; #define PG8_LDB(dst, b, h) do { _Pragma("unroll") for (int n = 0; n < 2; ++n) _Pragma("unroll") for (int k = 0; k < 2; ++k) dst[n][k] = *(const PG8_LAS bf16x8*)(lds + PG8_SB(b, h) + boff + n * 2048 + k * 1024); } while (0)
; #define PG8_MMA(ai, bj, At, Bt) do { __builtin_amdgcn_s_setprio(1); _Pragma("unroll") for (int m = 0; m < 4; ++m) _Pragma("unroll") for (int n = 0; n < 2; ++n) _Pragma("unroll") for (int k = 0; k < 2; ++k) \
;         acc[ai][bj][m][n] = __builtin_amdgcn_mfma_f32_16x16x32_bf16(Bt[n][k], At[m][k], acc[ai][bj][m][n], 0, 0, 0); __builtin_amdgcn_s_setprio(0); } while (0)
; #define PG8_WAIT_V(n) asm volatile("s_waitcnt vmcnt(" #n ")" ::: "memory")
; #define PG8_WAIT_L(n) asm volatile("s_waitcnt lgkmcnt(" #n ")" ::: "memory")
; #define PG8_BAR __builtin_amdgcn_s_barrier()
; #define PG8_SCHED __builtin_amdgcn_sched_barrier(0)
; template <class Epi, class Sched, bool ALIGN_EPI = false, bool SP2 = false>
; __device__ __forceinline__ void gemm_phase(PG8_LAS unsigned char* lds, const Gemm g, const Sched& S, const Epi& E) {
;     ...
;             PG8_WAIT_V(8); PG8_WAIT_L(0); PG8_BAR; PG8_MMA(1, 0, At, B0); PG8_MMA(1, 1, At, B1); PG8_BAR; PG8_SCHED;
;             PG8_LDB(B0, 1, 0); PG8_LDB(B1, 1, 1); PG8_SCHED; PG8_LDA(At, 1, 0); PG8_STAGE(PG8_SA(0, 1), a2 + hstepA, voffA);
;             PG8_WAIT_V(8); PG8_WAIT_L(0); PG8_BAR; PG8_MMA(0, 0, At, B0); PG8_MMA(0, 1, At, B1); PG8_BAR; PG8_SCHED;
	v_mfma_f32_16x16x32_bf16 v[60:63], v[156:159], v[194:197], 0
	v_mfma_f32_16x16x32_bf16 v[56:59], v[164:167], v[194:197], 0
	v_mfma_f32_16x16x32_bf16 v[44:47], v[156:159], v[202:205], 0
	v_mfma_f32_16x16x32_bf16 v[40:43], v[164:167], v[202:205], 0
	v_mfma_f32_16x16x32_bf16 v[28:31], v[156:159], v[210:213], 0
	v_mfma_f32_16x16x32_bf16 v[24:27], v[164:167], v[210:213], 0
	v_mfma_f32_16x16x32_bf16 v[12:15], v[156:159], v[218:221], 0
	v_mfma_f32_16x16x32_bf16 v[8:11], v[164:167], v[218:221], 0
	v_mfma_f32_16x16x32_bf16 v[60:63], v[160:163], v[198:201], v[60:63]
	v_mfma_f32_16x16x32_bf16 v[56:59], v[168:171], v[198:201], v[56:59]
	v_mfma_f32_16x16x32_bf16 v[44:47], v[160:163], v[206:209], v[44:47]
	v_mfma_f32_16x16x32_bf16 v[40:43], v[168:171], v[206:209], v[40:43]
	v_mfma_f32_16x16x32_bf16 v[28:31], v[160:163], v[214:217], v[28:31]
	v_mfma_f32_16x16x32_bf16 v[24:27], v[168:171], v[214:217], v[24:27]
	v_mfma_f32_16x16x32_bf16 v[12:15], v[160:163], v[222:225], v[12:15]
	v_mfma_f32_16x16x32_bf16 v[8:11], v[168:171], v[222:225], v[8:11]
	s_setprio 0
	s_setprio 1
	v_mfma_f32_16x16x32_bf16 v[52:55], v[172:175], v[194:197], 0
	v_mfma_f32_16x16x32_bf16 v[48:51], v[180:183], v[194:197], 0
	v_mfma_f32_16x16x32_bf16 v[36:39], v[172:175], v[202:205], 0
	v_mfma_f32_16x16x32_bf16 v[32:35], v[180:183], v[202:205], 0
	v_mfma_f32_16x16x32_bf16 v[20:23], v[172:175], v[210:213], 0
	v_mfma_f32_16x16x32_bf16 v[16:19], v[180:183], v[210:213], 0
	v_mfma_f32_16x16x32_bf16 v[4:7], v[172:175], v[218:221], 0
	v_mfma_f32_16x16x32_bf16 v[0:3], v[180:183], v[218:221], 0
	v_mfma_f32_16x16x32_bf16 v[52:55], v[176:179], v[198:201], v[52:55]
	v_mfma_f32_16x16x32_bf16 v[48:51], v[190:193], v[198:201], v[48:51]
	v_mfma_f32_16x16x32_bf16 v[36:39], v[176:179], v[206:209], v[36:39]
	v_mfma_f32_16x16x32_bf16 v[32:35], v[190:193], v[206:209], v[32:35]
	v_mfma_f32_16x16x32_bf16 v[20:23], v[176:179], v[214:217], v[20:23]
	v_mfma_f32_16x16x32_bf16 v[16:19], v[190:193], v[214:217], v[16:19]
	v_mfma_f32_16x16x32_bf16 v[4:7], v[176:179], v[222:225], v[4:7]
	v_mfma_f32_16x16x32_bf16 v[0:3], v[190:193], v[222:225], v[0:3]
	s_barrier
	s_setprio 0
	s_add_i32 s64, 0, 0x18000
	v_add_u32_e32 v155, s64, v150
	s_add_i32 s65, 0, 0x1c000
	ds_read_b128 v[156:159], v155
	ds_read_b128 v[160:163], v155 offset:1024
	ds_read_b128 v[164:167], v155 offset:2048
	ds_read_b128 v[168:171], v155 offset:3072
	v_add_u32_e32 v155, s65, v150
	ds_read_b128 v[172:175], v155
	ds_read_b128 v[176:179], v155 offset:1024
	ds_read_b128 v[180:183], v155 offset:2048
	ds_read_b128 v[190:193], v155 offset:3072
	s_add_u32 s58, s58, 0x80000
	s_addc_u32 s59, s59, 0
	s_mov_b32 m0, s9
	v_lshl_add_u64 v[234:235], s[58:59], 0, v[128:129]
	ds_read_b128 v[194:197], v154 offset:32768
	ds_read_b128 v[198:201], v154 offset:33792
	ds_read_b128 v[202:205], v154 offset:34816
	ds_read_b128 v[206:209], v154 offset:35840
	ds_read_b128 v[210:213], v154 offset:36864
	ds_read_b128 v[214:217], v154 offset:37888
	ds_read_b128 v[218:221], v154 offset:38912
	ds_read_b128 v[222:225], v154 offset:39936
	global_load_lds_dwordx4 v[234:235], off
	v_lshl_add_u64 v[234:235], s[58:59], 0, v[132:133]
	s_mov_b32 m0, s11
	s_nop 0
	global_load_lds_dwordx4 v[234:235], off
	s_waitcnt vmcnt(8)
	s_waitcnt lgkmcnt(0)
	s_setprio 1
	s_barrier
	v_mfma_f32_16x16x32_bf16 v[124:127], v[156:159], v[194:197], v[124:127]
	v_mfma_f32_16x16x32_bf16 v[120:123], v[164:167], v[194:197], v[120:123]
	v_mfma_f32_16x16x32_bf16 v[108:111], v[156:159], v[202:205], v[108:111]
	v_mfma_f32_16x16x32_bf16 v[104:107], v[164:167], v[202:205], v[104:107]
	v_mfma_f32_16x16x32_bf16 v[92:95], v[156:159], v[210:213], v[92:95]
	v_mfma_f32_16x16x32_bf16 v[88:91], v[164:167], v[210:213], v[88:91]
	v_mfma_f32_16x16x32_bf16 v[76:79], v[156:159], v[218:221], v[76:79]
	v_mfma_f32_16x16x32_bf16 v[72:75], v[164:167], v[218:221], v[72:75]
	v_mfma_f32_16x16x32_bf16 v[124:127], v[160:163], v[198:201], v[124:127]
	v_mfma_f32_16x16x32_bf16 v[120:123], v[168:171], v[198:201], v[120:123]
	v_mfma_f32_16x16x32_bf16 v[108:111], v[160:163], v[206:209], v[108:111]
	v_mfma_f32_16x16x32_bf16 v[104:107], v[168:171], v[206:209], v[104:107]
	v_mfma_f32_16x16x32_bf16 v[92:95], v[160:163], v[214:217], v[92:95]
	v_mfma_f32_16x16x32_bf16 v[88:91], v[168:171], v[214:217], v[88:91]
	v_mfma_f32_16x16x32_bf16 v[76:79], v[160:163], v[222:225], v[76:79]
	v_mfma_f32_16x16x32_bf16 v[72:75], v[168:171], v[222:225], v[72:75]
	s_setprio 0
	s_setprio 1
	v_mfma_f32_16x16x32_bf16 v[116:119], v[172:175], v[194:197], v[116:119]
	v_mfma_f32_16x16x32_bf16 v[112:115], v[180:183], v[194:197], v[112:115]
	v_mfma_f32_16x16x32_bf16 v[100:103], v[172:175], v[202:205], v[100:103]
	v_mfma_f32_16x16x32_bf16 v[96:99], v[180:183], v[202:205], v[96:99]
	v_mfma_f32_16x16x32_bf16 v[84:87], v[172:175], v[210:213], v[84:87]
	v_mfma_f32_16x16x32_bf16 v[80:83], v[180:183], v[210:213], v[80:83]
	v_mfma_f32_16x16x32_bf16 v[68:71], v[172:175], v[218:221], v[68:71]
	v_mfma_f32_16x16x32_bf16 v[64:67], v[180:183], v[218:221], v[64:67]
	v_mfma_f32_16x16x32_bf16 v[116:119], v[176:179], v[198:201], v[116:119]
	v_mfma_f32_16x16x32_bf16 v[112:115], v[190:193], v[198:201], v[112:115]
	v_mfma_f32_16x16x32_bf16 v[100:103], v[176:179], v[206:209], v[100:103]
	v_mfma_f32_16x16x32_bf16 v[96:99], v[190:193], v[206:209], v[96:99]
	v_mfma_f32_16x16x32_bf16 v[84:87], v[176:179], v[214:217], v[84:87]
	v_mfma_f32_16x16x32_bf16 v[80:83], v[190:193], v[214:217], v[80:83]
	v_mfma_f32_16x16x32_bf16 v[68:71], v[176:179], v[222:225], v[68:71]
	v_mfma_f32_16x16x32_bf16 v[64:67], v[190:193], v[222:225], v[64:67]
	s_barrier
; #define PG8_STAGE(bufoff, gbase, voff) do { _Pragma("unroll") for (int _i = 0; _i < 2; ++_i) \
;         __builtin_amdgcn_global_load_lds((const unsigned*)((const char*)(gbase) + (voff)[_i]), (PG8_LAS unsigned*)(lds + (bufoff) + ldsw + _i * 8192), 16, 0, 0); } while (0)
; #define PG8_LDA(dst, b, h) do { _Pragma("unroll") for (int m = 0; m < 4; ++m) _Pragma("unroll") for (int k = 0; k < 2; ++k) dst[m][k] = *(const PG8_LAS bf16x8*)(lds + PG8_SA(b, h) + aoff + m * 2048 + k * 1024); } while (0)
; #define PG8_MMA(ai, bj, At, Bt) do { __builtin_amdgcn_s_setprio(1); _Pragma("unroll") for (int m = 0; m < 4; ++m) _Pragma("unroll") for (int n = 0; n < 2; ++n) _Pragma("unroll") for (int k = 0; k < 2; ++k) \
;         acc[ai][bj][m][n] = __builtin_amdgcn_mfma_f32_16x16x32_bf16(Bt[n][k], At[m][k], acc[ai][bj][m][n], 0, 0, 0); __builtin_amdgcn_s_setprio(0); } while (0)
; #define PG8_WAIT_V(n) asm volatile("s_waitcnt vmcnt(" #n ")" ::: "memory")
; #define PG8_WAIT_L(n) asm volatile("s_waitcnt lgkmcnt(" #n ")" ::: "memory")
; #define PG8_BAR __builtin_amdgcn_s_barrier()
; #define PG8_SCHED __builtin_amdgcn_sched_barrier(0)
; template <class Epi, class Sched, bool ALIGN_EPI = false, bool SP2 = false>
; __device__ __forceinline__ void gemm_phase(PG8_LAS unsigned char* lds, const Gemm g, const Sched& S, const Epi& E) {
;     ...
;             PG8_LDA(At, 1, 1); PG8_STAGE(PG8_SB(1, 0), b3, voffB); PG8_STAGE(PG8_SB(1, 1), b3 + hstepB, voffB); PG8_STAGE(PG8_SA(1, 0), a3, voffA);
;             PG8_WAIT_V(8); PG8_WAIT_L(0); PG8_BAR; PG8_MMA(1, 0, At, B0); PG8_MMA(1, 1, At, B1); PG8_BAR; PG8_SCHED;
	s_setprio 0
	s_add_i32 s58, s64, s6
	v_lshl_add_u64 v[226:227], v[226:227], 0, s[20:21]
	s_mov_b32 m0, s58
	ds_read_b128 v[194:197], v154 offset:49152
	ds_read_b128 v[198:201], v154 offset:50176
	ds_read_b128 v[202:205], v154 offset:51200
	ds_read_b128 v[206:209], v154 offset:52224
	ds_read_b128 v[210:213], v154 offset:53248
	ds_read_b128 v[214:217], v154 offset:54272
	ds_read_b128 v[218:221], v154 offset:55296
	ds_read_b128 v[222:225], v154 offset:56320
	global_load_lds_dwordx4 v[226:227], off
	s_add_i32 m0, s58, 0x2000
	s_add_u32 s52, s52, 0x80080
	v_lshl_add_u64 v[226:227], v[228:229], 0, s[20:21]
	s_addc_u32 s53, s53, 0
	s_add_i32 s58, s65, s6
	global_load_lds_dwordx4 v[226:227], off
	v_lshl_add_u64 v[226:227], s[52:53], 0, v[130:131]
	s_mov_b32 m0, s58
	s_nop 0
	global_load_lds_dwordx4 v[226:227], off
	v_lshl_add_u64 v[226:227], s[52:53], 0, v[134:135]
	s_add_i32 m0, s58, 0x2000
	s_nop 0
	global_load_lds_dwordx4 v[226:227], off
	v_lshl_add_u64 v[226:227], v[230:231], 0, s[20:21]
	s_mov_b32 m0, s46
	s_nop 0
	global_load_lds_dwordx4 v[226:227], off
	v_lshl_add_u64 v[226:227], v[232:233], 0, s[20:21]
	s_mov_b32 m0, s47
	s_nop 0
	global_load_lds_dwordx4 v[226:227], off
	s_waitcnt vmcnt(8)
	s_waitcnt lgkmcnt(0)
	s_setprio 1
	s_barrier
	v_mfma_f32_16x16x32_bf16 v[60:63], v[156:159], v[194:197], v[60:63]
	v_mfma_f32_16x16x32_bf16 v[56:59], v[164:167], v[194:197], v[56:59]
	v_mfma_f32_16x16x32_bf16 v[44:47], v[156:159], v[202:205], v[44:47]
	v_mfma_f32_16x16x32_bf16 v[40:43], v[164:167], v[202:205], v[40:43]
	v_mfma_f32_16x16x32_bf16 v[28:31], v[156:159], v[210:213], v[28:31]
	v_mfma_f32_16x16x32_bf16 v[24:27], v[164:167], v[210:213], v[24:27]
	v_mfma_f32_16x16x32_bf16 v[12:15], v[156:159], v[218:221], v[12:15]
	v_mfma_f32_16x16x32_bf16 v[8:11], v[164:167], v[218:221], v[8:11]
	v_mfma_f32_16x16x32_bf16 v[60:63], v[160:163], v[198:201], v[60:63]
	v_mfma_f32_16x16x32_bf16 v[56:59], v[168:171], v[198:201], v[56:59]
	v_mfma_f32_16x16x32_bf16 v[44:47], v[160:163], v[206:209], v[44:47]
	v_mfma_f32_16x16x32_bf16 v[40:43], v[168:171], v[206:209], v[40:43]
	v_mfma_f32_16x16x32_bf16 v[28:31], v[160:163], v[214:217], v[28:31]
	v_mfma_f32_16x16x32_bf16 v[24:27], v[168:171], v[214:217], v[24:27]
	v_mfma_f32_16x16x32_bf16 v[12:15], v[160:163], v[222:225], v[12:15]
	v_mfma_f32_16x16x32_bf16 v[8:11], v[168:171], v[222:225], v[8:11]
	s_setprio 0
	s_setprio 1
	v_mfma_f32_16x16x32_bf16 v[52:55], v[172:175], v[194:197], v[52:55]
	v_mfma_f32_16x16x32_bf16 v[48:51], v[180:183], v[194:197], v[48:51]
	v_mfma_f32_16x16x32_bf16 v[36:39], v[172:175], v[202:205], v[36:39]
	v_mfma_f32_16x16x32_bf16 v[32:35], v[180:183], v[202:205], v[32:35]
	v_mfma_f32_16x16x32_bf16 v[20:23], v[172:175], v[210:213], v[20:23]
	v_mfma_f32_16x16x32_bf16 v[16:19], v[180:183], v[210:213], v[16:19]
	v_mfma_f32_16x16x32_bf16 v[4:7], v[172:175], v[218:221], v[4:7]
	v_mfma_f32_16x16x32_bf16 v[0:3], v[180:183], v[218:221], v[0:3]
	v_mfma_f32_16x16x32_bf16 v[52:55], v[176:179], v[198:201], v[52:55]
	v_mfma_f32_16x16x32_bf16 v[48:51], v[190:193], v[198:201], v[48:51]
	v_mfma_f32_16x16x32_bf16 v[36:39], v[176:179], v[206:209], v[36:39]
	v_mfma_f32_16x16x32_bf16 v[32:35], v[190:193], v[206:209], v[32:35]
	v_mfma_f32_16x16x32_bf16 v[20:23], v[176:179], v[214:217], v[20:23]
	v_mfma_f32_16x16x32_bf16 v[16:19], v[190:193], v[214:217], v[16:19]
	v_mfma_f32_16x16x32_bf16 v[4:7], v[176:179], v[222:225], v[4:7]
	v_mfma_f32_16x16x32_bf16 v[0:3], v[190:193], v[222:225], v[0:3]
	s_barrier
	s_setprio 0
	s_add_i32 s63, s63, 2
	s_add_u32 s50, s50, 0x100
	s_addc_u32 s51, s51, 0
	s_add_u32 s39, s39, 0x100
	s_addc_u32 s41, s41, 0
	s_cmp_gt_u32 s63, 29
	s_cbranch_scc1 .Lmy_peel_7_exit

; #define PG8_STAGE(bufoff, gbase, voff) do { _Pragma("unroll") for (int _i = 0; _i < 2; ++_i) \
;         __builtin_amdgcn_global_load_lds((const unsigned*)((const char*)(gbase) + (voff)[_i]), (PG8_LAS unsigned*)(lds + (bufoff) + ldsw + _i * 8192), 16, 0, 0); } while (0)
; #define PG8_LDA(dst, b, h) do { _Pragma("unroll") for (int m = 0; m < 4; ++m) _Pragma("unroll") for (int k = 0; k < 2; ++k) dst[m][k] = *(const PG8_LAS bf16x8*)(lds + PG8_SA(b, h) + aoff + m * 2048 + k * 1024); } while (0)
; #define PG8_LDB(dst, b, h) do { _Pragma("unroll") for (int n = 0; n < 2; ++n) _Pragma("unroll") for (int k = 0; k < 2; ++k) dst[n][k] = *(const PG8_LAS bf16x8*)(lds + PG8_SB(b, h) + boff + n * 2048 + k * 1024); } while (0)
; #define PG8_WAIT_V(n) asm volatile("s_waitcnt vmcnt(" #n ")" ::: "memory")
; #define PG8_WAIT_L(n) asm volatile("s_waitcnt lgkmcnt(" #n ")" ::: "memory")
; #define PG8_BAR __builtin_amdgcn_s_barrier()
; template <class Epi, class Sched, bool ALIGN_EPI = false, bool SP2 = false>
; __device__ __forceinline__ void gemm_phase(PG8_LAS unsigned char* lds, const Gemm g, const Sched& S, const Epi& E) {
;     ...
;         const char* nA = has_next ? (const char*)g.A + (size_t)nxt.pm * tstepA + (size_t)nxt.z * g.azs + (size_t)(nxt.k0 >> 6) * kstA : cA; const char* nB = has_next ? (const char*)g.Bt + (size_t)nxt.pn * tstepB + (size_t)nxt.z * g.bzs + (size_t)nxt.k0 * 2 : cB;
;         const int nt = cur.nt;
;         for (int t = 0; t < nt; t += 2) {
;             const bool last = (t == nt - 2);
;             const char* a1 = cA + (size_t)(t + 1) * kstA;
;             const char* a2 = last ? nA : cA + (size_t)(t + 2) * kstA; const char* b2 = last ? nB : cB + (size_t)(t + 2) * kstep;
;             const char* a3 = a2 + kstA; const char* b3 = b2 + kstep;
;             if (last && has_next) S.a_ready(nxt);
;             if constexpr (SP2) {
;             PG8_LDB(B0, 0, 0); PG8_LDB(B1, 0, 1); PG8_SCHED; PG8_LDA(At, 0, 0); PG8_STAGE(PG8_SA(1, 1), a1 + hstepA, voffA);
;             PG8_WAIT_V(8); PG8_WAIT_L(0); PG8_BAR; PG8_MMA(0, 0, At, B0); PG8_MMA(0, 1, At, B1); PG8_BAR; PG8_SCHED;
;             PG8_LDA(At, 0, 1); PG8_STAGE(PG8_SB(0, 0), b2, voffB); PG8_STAGE(PG8_SB(0, 1), b2 + hstepB, voffB); PG8_STAGE(PG8_SA(0, 0), a2, voffA);
;             PG8_WAIT_V(8); PG8_WAIT_L(0); PG8_BAR; PG8_MMA(1, 0, At, B0); PG8_MMA(1, 1, At, B1); PG8_BAR; PG8_SCHED;
.LBB0_2049:
	s_ashr_i32 s61, s60, 31
	s_lshl_b64 s[4:5], s[60:61], 20
	v_readlane_b32 s10, v254, 41
	v_readlane_b32 s11, v254, 42
	s_add_u32 s62, s10, s4
	s_addc_u32 s63, s11, s5
	s_and_b64 s[4:5], s[42:43], exec
	s_cselect_b32 s1, s63, s21
	s_cselect_b32 s3, s62, s20
	s_ashr_i32 s59, s58, 31
	s_lshl_b64 s[4:5], s[58:59], 20
	s_add_u32 s64, s72, s4
	s_addc_u32 s65, s73, s5
	s_and_b64 s[4:5], s[42:43], exec
	s_cselect_b32 s4, s65, s39
	s_cselect_b32 s5, s64, s38
	s_add_u32 s20, s20, 0x80080
	s_addc_u32 s21, s21, 0
	s_add_u32 s10, s38, 0x100
	s_addc_u32 s11, s39, 0
	s_mov_b32 s12, -2
	ds_read_b128 v[128:131], v159
	ds_read_b128 v[132:135], v159 offset:1024
	ds_read_b128 v[164:167], v159 offset:2048
	ds_read_b128 v[168:171], v159 offset:3072
	ds_read_b128 v[172:175], v160
	ds_read_b128 v[176:179], v160 offset:1024
	ds_read_b128 v[180:183], v160 offset:2048
	ds_read_b128 v[190:193], v160 offset:3072
	s_add_u32 s13, s20, 0xfff80080
	s_addc_u32 s33, s21, -1
	s_cmp_eq_u32 s12, 28
	s_cselect_b32 s41, s1, s33
	s_cselect_b32 s40, s3, s13
	s_cselect_b32 s39, s4, s11
	s_cselect_b32 s38, s5, s10
	v_lshl_add_u64 v[226:227], s[20:21], 0, v[148:149]
	s_add_i32 m0, s7, 0xc000
	ds_read_b128 v[194:197], v161
	ds_read_b128 v[198:201], v161 offset:1024
	ds_read_b128 v[202:205], v161 offset:2048
	ds_read_b128 v[206:209], v161 offset:3072
	ds_read_b128 v[210:213], v161 offset:4096
	ds_read_b128 v[214:217], v161 offset:5120
	ds_read_b128 v[218:221], v161 offset:6144
	ds_read_b128 v[222:225], v161 offset:7168
	global_load_lds_dwordx4 v[226:227], off
	v_lshl_add_u64 v[226:227], s[20:21], 0, v[150:151]
	s_add_i32 m0, s7, 0xe000
	s_nop 0
	global_load_lds_dwordx4 v[226:227], off
	s_waitcnt vmcnt(8)
	s_waitcnt lgkmcnt(0)
	s_setprio 1
	s_barrier
	v_mfma_f32_16x16x32_bf16 v[124:127], v[128:131], v[194:197], 0
	v_mfma_f32_16x16x32_bf16 v[120:123], v[164:167], v[194:197], 0
	v_mfma_f32_16x16x32_bf16 v[108:111], v[128:131], v[202:205], 0
	v_mfma_f32_16x16x32_bf16 v[104:107], v[164:167], v[202:205], 0
	v_mfma_f32_16x16x32_bf16 v[92:95], v[128:131], v[210:213], 0
	v_mfma_f32_16x16x32_bf16 v[88:91], v[164:167], v[210:213], 0
	v_mfma_f32_16x16x32_bf16 v[76:79], v[128:131], v[218:221], 0
	v_mfma_f32_16x16x32_bf16 v[72:75], v[164:167], v[218:221], 0
	v_mfma_f32_16x16x32_bf16 v[124:127], v[132:135], v[198:201], v[124:127]
	v_mfma_f32_16x16x32_bf16 v[120:123], v[168:171], v[198:201], v[120:123]
	v_mfma_f32_16x16x32_bf16 v[108:111], v[132:135], v[206:209], v[108:111]
	v_mfma_f32_16x16x32_bf16 v[104:107], v[168:171], v[206:209], v[104:107]
	v_mfma_f32_16x16x32_bf16 v[92:95], v[132:135], v[214:217], v[92:95]
	v_mfma_f32_16x16x32_bf16 v[88:91], v[168:171], v[214:217], v[88:91]
	v_mfma_f32_16x16x32_bf16 v[76:79], v[132:135], v[222:225], v[76:79]
	v_mfma_f32_16x16x32_bf16 v[72:75], v[168:171], v[222:225], v[72:75]
	s_setprio 0
	s_setprio 1
	v_mfma_f32_16x16x32_bf16 v[116:119], v[172:175], v[194:197], 0
	v_mfma_f32_16x16x32_bf16 v[112:115], v[180:183], v[194:197], 0
	v_mfma_f32_16x16x32_bf16 v[100:103], v[172:175], v[202:205], 0
	v_mfma_f32_16x16x32_bf16 v[96:99], v[180:183], v[202:205], 0
	v_mfma_f32_16x16x32_bf16 v[84:87], v[172:175], v[210:213], 0
	v_mfma_f32_16x16x32_bf16 v[80:83], v[180:183], v[210:213], 0
	v_mfma_f32_16x16x32_bf16 v[68:71], v[172:175], v[218:221], 0
	v_mfma_f32_16x16x32_bf16 v[64:67], v[180:183], v[218:221], 0
	v_mfma_f32_16x16x32_bf16 v[116:119], v[176:179], v[198:201], v[116:119]
	v_mfma_f32_16x16x32_bf16 v[112:115], v[190:193], v[198:201], v[112:115]
	v_mfma_f32_16x16x32_bf16 v[100:103], v[176:179], v[206:209], v[100:103]
	v_mfma_f32_16x16x32_bf16 v[96:99], v[190:193], v[206:209], v[96:99]
	v_mfma_f32_16x16x32_bf16 v[84:87], v[176:179], v[214:217], v[84:87]
	v_mfma_f32_16x16x32_bf16 v[80:83], v[190:193], v[214:217], v[80:83]
	v_mfma_f32_16x16x32_bf16 v[68:71], v[176:179], v[222:225], v[68:71]
	v_mfma_f32_16x16x32_bf16 v[64:67], v[190:193], v[222:225], v[64:67]
	s_barrier
	s_setprio 0
	s_add_i32 s13, s69, s6
	v_lshl_add_u64 v[226:227], s[38:39], 0, v[138:139]
	s_mov_b32 m0, s13
	ds_read_b128 v[194:197], v161 offset:16384
	ds_read_b128 v[198:201], v161 offset:17408
	ds_read_b128 v[202:205], v161 offset:18432
	ds_read_b128 v[206:209], v161 offset:19456
	ds_read_b128 v[210:213], v161 offset:20480
	ds_read_b128 v[214:217], v161 offset:21504
	ds_read_b128 v[218:221], v161 offset:22528
	ds_read_b128 v[222:225], v161 offset:23552
	global_load_lds_dwordx4 v[226:227], off
	s_add_i32 m0, s13, 0x2000
	s_add_u32 s44, s38, 0x80000
	v_lshl_add_u64 v[228:229], s[38:39], 0, v[142:143]
	s_addc_u32 s45, s39, 0
	s_add_i32 s13, s70, s6
	global_load_lds_dwordx4 v[228:229], off
	v_lshl_add_u64 v[230:231], s[44:45], 0, v[138:139]
	s_mov_b32 m0, s13
	v_lshl_add_u64 v[232:233], s[40:41], 0, v[140:141]
	global_load_lds_dwordx4 v[230:231], off
	v_lshl_add_u64 v[230:231], s[44:45], 0, v[142:143]
	s_add_i32 m0, s13, 0x2000
	s_nop 0
	global_load_lds_dwordx4 v[230:231], off
	v_lshl_add_u64 v[230:231], s[40:41], 0, v[136:137]
	s_mov_b32 m0, s7
	s_nop 0
	global_load_lds_dwordx4 v[230:231], off
	s_mov_b32 m0, s8
	s_nop 0
	global_load_lds_dwordx4 v[232:233], off
	s_waitcnt vmcnt(8)
	s_waitcnt lgkmcnt(0)
	s_setprio 1
	s_barrier
; #define PG8_STAGE(bufoff, gbase, voff) do { _Pragma("unroll") for (int _i = 0; _i < 2; ++_i) \
;         __builtin_amdgcn_global_load_lds((const unsigned*)((const char*)(gbase) + (voff)[_i]), (PG8_LAS unsigned*)(lds + (bufoff) + ldsw + _i * 8192), 16, 0, 0); } while (0)
; #define PG8_LDA(dst, b, h) do { _Pragma("unroll") for (int m = 0; m < 4; ++m) _Pragma("unroll") for (int k = 0; k < 2; ++k) dst[m][k] = *(const PG8_LAS bf16x8*)(lds + PG8_SA(b, h) + aoff + m * 2048 + k * 1024); } while (0)
; #define PG8_LDB(dst, b, h) do { _Pragma("unroll") for (int n = 0; n < 2; ++n) _Pragma("unroll") for (int k = 0; k < 2; ++k) dst[n][k] = *(const PG8_LAS bf16x8*)(lds + PG8_SB(b, h) + boff + n * 2048 + k * 1024); } while (0)
; #define PG8_MMA(ai, bj, At, Bt) do { __builtin_amdgcn_s_setprio(1); _Pragma("unroll") for (int m = 0; m < 4; ++m) _Pragma("unroll") for (int n = 0; n < 2; ++n) _Pragma("unroll") for (int k = 0; k < 2; ++k) \
;         acc[ai][bj][m][n] = __builtin_amdgcn_mfma_f32_16x16x32_bf16(Bt[n][k], At[m][k], acc[ai][bj][m][n], 0, 0, 0); __builtin_amdgcn_s_setprio(0); } while (0)
; #define PG8_WAIT_V(n) asm volatile("s_waitcnt vmcnt(" #n ")" ::: "memory")
; #define PG8_WAIT_L(n) asm volatile("s_waitcnt lgkmcnt(" #n ")" ::: "memory")
; #define PG8_BAR __builtin_amdgcn_s_barrier()
; #define PG8_SCHED __builtin_amdgcn_sched_barrier(0)
; template <class Epi, class Sched, bool ALIGN_EPI = false, bool SP2 = false>
; __device__ __forceinline__ void gemm_phase(PG8_LAS unsigned char* lds, const Gemm g, const Sched& S, const Epi& E) {
;     ...
;             PG8_WAIT_V(8); PG8_WAIT_L(0); PG8_BAR; PG8_MMA(1, 0, At, B0); PG8_MMA(1, 1, At, B1); PG8_BAR; PG8_SCHED;
;             PG8_LDB(B0, 1, 0); PG8_LDB(B1, 1, 1); PG8_SCHED; PG8_LDA(At, 1, 0); PG8_STAGE(PG8_SA(0, 1), a2 + hstepA, voffA);
;             PG8_WAIT_V(8); PG8_WAIT_L(0); PG8_BAR; PG8_MMA(0, 0, At, B0); PG8_MMA(0, 1, At, B1); PG8_BAR; PG8_SCHED;
	v_mfma_f32_16x16x32_bf16 v[60:63], v[128:131], v[194:197], 0
	v_mfma_f32_16x16x32_bf16 v[56:59], v[164:167], v[194:197], 0
	v_mfma_f32_16x16x32_bf16 v[44:47], v[128:131], v[202:205], 0
	v_mfma_f32_16x16x32_bf16 v[40:43], v[164:167], v[202:205], 0
	v_mfma_f32_16x16x32_bf16 v[28:31], v[128:131], v[210:213], 0
	v_mfma_f32_16x16x32_bf16 v[24:27], v[164:167], v[210:213], 0
	v_mfma_f32_16x16x32_bf16 v[12:15], v[128:131], v[218:221], 0
	v_mfma_f32_16x16x32_bf16 v[8:11], v[164:167], v[218:221], 0
	v_mfma_f32_16x16x32_bf16 v[60:63], v[132:135], v[198:201], v[60:63]
	v_mfma_f32_16x16x32_bf16 v[56:59], v[168:171], v[198:201], v[56:59]
	v_mfma_f32_16x16x32_bf16 v[44:47], v[132:135], v[206:209], v[44:47]
	v_mfma_f32_16x16x32_bf16 v[40:43], v[168:171], v[206:209], v[40:43]
	v_mfma_f32_16x16x32_bf16 v[28:31], v[132:135], v[214:217], v[28:31]
	v_mfma_f32_16x16x32_bf16 v[24:27], v[168:171], v[214:217], v[24:27]
	v_mfma_f32_16x16x32_bf16 v[12:15], v[132:135], v[222:225], v[12:15]
	v_mfma_f32_16x16x32_bf16 v[8:11], v[168:171], v[222:225], v[8:11]
	s_setprio 0
	s_setprio 1
	v_mfma_f32_16x16x32_bf16 v[52:55], v[172:175], v[194:197], 0
	v_mfma_f32_16x16x32_bf16 v[48:51], v[180:183], v[194:197], 0
	v_mfma_f32_16x16x32_bf16 v[36:39], v[172:175], v[202:205], 0
	v_mfma_f32_16x16x32_bf16 v[32:35], v[180:183], v[202:205], 0
	v_mfma_f32_16x16x32_bf16 v[20:23], v[172:175], v[210:213], 0
	v_mfma_f32_16x16x32_bf16 v[16:19], v[180:183], v[210:213], 0
	v_mfma_f32_16x16x32_bf16 v[4:7], v[172:175], v[218:221], 0
	v_mfma_f32_16x16x32_bf16 v[0:3], v[180:183], v[218:221], 0
	v_mfma_f32_16x16x32_bf16 v[52:55], v[176:179], v[198:201], v[52:55]
	v_mfma_f32_16x16x32_bf16 v[48:51], v[190:193], v[198:201], v[48:51]
	v_mfma_f32_16x16x32_bf16 v[36:39], v[176:179], v[206:209], v[36:39]
	v_mfma_f32_16x16x32_bf16 v[32:35], v[190:193], v[206:209], v[32:35]
	v_mfma_f32_16x16x32_bf16 v[20:23], v[176:179], v[214:217], v[20:23]
	v_mfma_f32_16x16x32_bf16 v[16:19], v[190:193], v[214:217], v[16:19]
	v_mfma_f32_16x16x32_bf16 v[4:7], v[176:179], v[222:225], v[4:7]
	v_mfma_f32_16x16x32_bf16 v[0:3], v[190:193], v[222:225], v[0:3]
	s_barrier
	s_setprio 0
	s_add_i32 s13, 0, 0x18000
	v_add_u32_e32 v144, s13, v157
	s_add_i32 s33, 0, 0x1c000
	ds_read_b128 v[128:131], v144
	ds_read_b128 v[132:135], v144 offset:1024
	ds_read_b128 v[164:167], v144 offset:2048
	ds_read_b128 v[168:171], v144 offset:3072
	v_add_u32_e32 v144, s33, v157
	ds_read_b128 v[172:175], v144
	ds_read_b128 v[176:179], v144 offset:1024
	ds_read_b128 v[180:183], v144 offset:2048
	ds_read_b128 v[190:193], v144 offset:3072
	s_add_u32 s40, s40, 0x80000
	s_addc_u32 s41, s41, 0
	s_mov_b32 m0, s9
	v_lshl_add_u64 v[234:235], s[40:41], 0, v[136:137]
	ds_read_b128 v[194:197], v161 offset:32768
	ds_read_b128 v[198:201], v161 offset:33792
	ds_read_b128 v[202:205], v161 offset:34816
	ds_read_b128 v[206:209], v161 offset:35840
	ds_read_b128 v[210:213], v161 offset:36864
	ds_read_b128 v[214:217], v161 offset:37888
	ds_read_b128 v[218:221], v161 offset:38912
	ds_read_b128 v[222:225], v161 offset:39936
	global_load_lds_dwordx4 v[234:235], off
	v_lshl_add_u64 v[234:235], s[40:41], 0, v[140:141]
	s_mov_b32 m0, s35
	s_nop 0
	global_load_lds_dwordx4 v[234:235], off
	s_waitcnt vmcnt(8)
	s_waitcnt lgkmcnt(0)
	s_setprio 1
	s_barrier
	v_mfma_f32_16x16x32_bf16 v[124:127], v[128:131], v[194:197], v[124:127]
	v_mfma_f32_16x16x32_bf16 v[120:123], v[164:167], v[194:197], v[120:123]
	v_mfma_f32_16x16x32_bf16 v[108:111], v[128:131], v[202:205], v[108:111]
	v_mfma_f32_16x16x32_bf16 v[104:107], v[164:167], v[202:205], v[104:107]
	v_mfma_f32_16x16x32_bf16 v[92:95], v[128:131], v[210:213], v[92:95]
	v_mfma_f32_16x16x32_bf16 v[88:91], v[164:167], v[210:213], v[88:91]
	v_mfma_f32_16x16x32_bf16 v[76:79], v[128:131], v[218:221], v[76:79]
	v_mfma_f32_16x16x32_bf16 v[72:75], v[164:167], v[218:221], v[72:75]
	v_mfma_f32_16x16x32_bf16 v[124:127], v[132:135], v[198:201], v[124:127]
	v_mfma_f32_16x16x32_bf16 v[120:123], v[168:171], v[198:201], v[120:123]
	v_mfma_f32_16x16x32_bf16 v[108:111], v[132:135], v[206:209], v[108:111]
	v_mfma_f32_16x16x32_bf16 v[104:107], v[168:171], v[206:209], v[104:107]
	v_mfma_f32_16x16x32_bf16 v[92:95], v[132:135], v[214:217], v[92:95]
	v_mfma_f32_16x16x32_bf16 v[88:91], v[168:171], v[214:217], v[88:91]
	v_mfma_f32_16x16x32_bf16 v[76:79], v[132:135], v[222:225], v[76:79]
	v_mfma_f32_16x16x32_bf16 v[72:75], v[168:171], v[222:225], v[72:75]
	s_setprio 0
	s_setprio 1
	v_mfma_f32_16x16x32_bf16 v[116:119], v[172:175], v[194:197], v[116:119]
	v_mfma_f32_16x16x32_bf16 v[112:115], v[180:183], v[194:197], v[112:115]
	v_mfma_f32_16x16x32_bf16 v[100:103], v[172:175], v[202:205], v[100:103]
	v_mfma_f32_16x16x32_bf16 v[96:99], v[180:183], v[202:205], v[96:99]
	v_mfma_f32_16x16x32_bf16 v[84:87], v[172:175], v[210:213], v[84:87]
	v_mfma_f32_16x16x32_bf16 v[80:83], v[180:183], v[210:213], v[80:83]
	v_mfma_f32_16x16x32_bf16 v[68:71], v[172:175], v[218:221], v[68:71]
	v_mfma_f32_16x16x32_bf16 v[64:67], v[180:183], v[218:221], v[64:67]
	v_mfma_f32_16x16x32_bf16 v[116:119], v[176:179], v[198:201], v[116:119]
	v_mfma_f32_16x16x32_bf16 v[112:115], v[190:193], v[198:201], v[112:115]
	v_mfma_f32_16x16x32_bf16 v[100:103], v[176:179], v[206:209], v[100:103]
	v_mfma_f32_16x16x32_bf16 v[96:99], v[190:193], v[206:209], v[96:99]
	v_mfma_f32_16x16x32_bf16 v[84:87], v[176:179], v[214:217], v[84:87]
	v_mfma_f32_16x16x32_bf16 v[80:83], v[190:193], v[214:217], v[80:83]
	v_mfma_f32_16x16x32_bf16 v[68:71], v[176:179], v[222:225], v[68:71]
	v_mfma_f32_16x16x32_bf16 v[64:67], v[190:193], v[222:225], v[64:67]
	s_barrier
; #define PG8_STAGE(bufoff, gbase, voff) do { _Pragma("unroll") for (int _i = 0; _i < 2; ++_i) \
;         __builtin_amdgcn_global_load_lds((const unsigned*)((const char*)(gbase) + (voff)[_i]), (PG8_LAS unsigned*)(lds + (bufoff) + ldsw + _i * 8192), 16, 0, 0); } while (0)
; #define PG8_LDA(dst, b, h) do { _Pragma("unroll") for (int m = 0; m < 4; ++m) _Pragma("unroll") for (int k = 0; k < 2; ++k) dst[m][k] = *(const PG8_LAS bf16x8*)(lds + PG8_SA(b, h) + aoff + m * 2048 + k * 1024); } while (0)
; #define PG8_LDB(dst, b, h) do { _Pragma("unroll") for (int n = 0; n < 2; ++n) _Pragma("unroll") for (int k = 0; k < 2; ++k) dst[n][k] = *(const PG8_LAS bf16x8*)(lds + PG8_SB(b, h) + boff + n * 2048 + k * 1024); } while (0)
; #define PG8_MMA(ai, bj, At, Bt) do { __builtin_amdgcn_s_setprio(1); _Pragma("unroll") for (int m = 0; m < 4; ++m) _Pragma("unroll") for (int n = 0; n < 2; ++n) _Pragma("unroll") for (int k = 0; k < 2; ++k) \
;         acc[ai][bj][m][n] = __builtin_amdgcn_mfma_f32_16x16x32_bf16(Bt[n][k], At[m][k], acc[ai][bj][m][n], 0, 0, 0); __builtin_amdgcn_s_setprio(0); } while (0)
; #define PG8_WAIT_V(n) asm volatile("s_waitcnt vmcnt(" #n ")" ::: "memory")
; #define PG8_WAIT_L(n) asm volatile("s_waitcnt lgkmcnt(" #n ")" ::: "memory")
; #define PG8_BAR __builtin_amdgcn_s_barrier()
; #define PG8_SCHED __builtin_amdgcn_sched_barrier(0)
; template <class Epi, class Sched, bool ALIGN_EPI = false, bool SP2 = false>
; __device__ __forceinline__ void gemm_phase(PG8_LAS unsigned char* lds, const Gemm g, const Sched& S, const Epi& E) {
;     ...
;             PG8_LDB(B0, 0, 0); PG8_LDB(B1, 0, 1); PG8_SCHED; PG8_LDA(At, 0, 0); PG8_STAGE(PG8_SA(1, 1), a1 + hstepA, voffA);
;             PG8_WAIT_V(8); PG8_WAIT_L(0); PG8_BAR; PG8_MMA(0, 0, At, B0); PG8_MMA(0, 1, At, B1); PG8_BAR; PG8_SCHED;
;     ...
;             PG8_LDA(At, 1, 1); PG8_STAGE(PG8_SB(1, 0), b3, voffB); PG8_STAGE(PG8_SB(1, 1), b3 + hstepB, voffB); PG8_STAGE(PG8_SA(1, 0), a3, voffA);
;             PG8_WAIT_V(8); PG8_WAIT_L(0); PG8_BAR; PG8_MMA(1, 0, At, B0); PG8_MMA(1, 1, At, B1); PG8_BAR; PG8_SCHED;
	s_setprio 0
	s_add_i32 s13, s13, s6
	v_lshl_add_u64 v[226:227], v[226:227], 0, s[54:55]
	s_mov_b32 m0, s13
	ds_read_b128 v[194:197], v161 offset:49152
	ds_read_b128 v[198:201], v161 offset:50176
	ds_read_b128 v[202:205], v161 offset:51200
	ds_read_b128 v[206:209], v161 offset:52224
	ds_read_b128 v[210:213], v161 offset:53248
	ds_read_b128 v[214:217], v161 offset:54272
	ds_read_b128 v[218:221], v161 offset:55296
	ds_read_b128 v[222:225], v161 offset:56320
	global_load_lds_dwordx4 v[226:227], off
	s_add_i32 m0, s13, 0x2000
	s_add_u32 s38, s38, 0x80080
	v_lshl_add_u64 v[226:227], v[228:229], 0, s[54:55]
	s_addc_u32 s39, s39, 0
	s_add_i32 s13, s33, s6
	global_load_lds_dwordx4 v[226:227], off
	v_lshl_add_u64 v[226:227], s[38:39], 0, v[138:139]
	s_mov_b32 m0, s13
	s_nop 0
	global_load_lds_dwordx4 v[226:227], off
	v_lshl_add_u64 v[226:227], s[38:39], 0, v[142:143]
	s_add_i32 m0, s13, 0x2000
	s_nop 0
	global_load_lds_dwordx4 v[226:227], off
	v_lshl_add_u64 v[226:227], v[230:231], 0, s[54:55]
	s_mov_b32 m0, s51
	s_nop 0
	global_load_lds_dwordx4 v[226:227], off
	v_lshl_add_u64 v[226:227], v[232:233], 0, s[54:55]
	s_mov_b32 m0, s68
	s_nop 0
	global_load_lds_dwordx4 v[226:227], off
	s_waitcnt vmcnt(8)
	s_waitcnt lgkmcnt(0)
	s_setprio 1
	s_barrier
	v_mfma_f32_16x16x32_bf16 v[60:63], v[128:131], v[194:197], v[60:63]
	v_mfma_f32_16x16x32_bf16 v[56:59], v[164:167], v[194:197], v[56:59]
	v_mfma_f32_16x16x32_bf16 v[44:47], v[128:131], v[202:205], v[44:47]
	v_mfma_f32_16x16x32_bf16 v[40:43], v[164:167], v[202:205], v[40:43]
	v_mfma_f32_16x16x32_bf16 v[28:31], v[128:131], v[210:213], v[28:31]
	v_mfma_f32_16x16x32_bf16 v[24:27], v[164:167], v[210:213], v[24:27]
	v_mfma_f32_16x16x32_bf16 v[12:15], v[128:131], v[218:221], v[12:15]
	v_mfma_f32_16x16x32_bf16 v[8:11], v[164:167], v[218:221], v[8:11]
	v_mfma_f32_16x16x32_bf16 v[60:63], v[132:135], v[198:201], v[60:63]
	v_mfma_f32_16x16x32_bf16 v[56:59], v[168:171], v[198:201], v[56:59]
	v_mfma_f32_16x16x32_bf16 v[44:47], v[132:135], v[206:209], v[44:47]
	v_mfma_f32_16x16x32_bf16 v[40:43], v[168:171], v[206:209], v[40:43]
	v_mfma_f32_16x16x32_bf16 v[28:31], v[132:135], v[214:217], v[28:31]
	v_mfma_f32_16x16x32_bf16 v[24:27], v[168:171], v[214:217], v[24:27]
	v_mfma_f32_16x16x32_bf16 v[12:15], v[132:135], v[222:225], v[12:15]
	v_mfma_f32_16x16x32_bf16 v[8:11], v[168:171], v[222:225], v[8:11]
	s_setprio 0
	s_setprio 1
	v_mfma_f32_16x16x32_bf16 v[52:55], v[172:175], v[194:197], v[52:55]
	v_mfma_f32_16x16x32_bf16 v[48:51], v[180:183], v[194:197], v[48:51]
	v_mfma_f32_16x16x32_bf16 v[36:39], v[172:175], v[202:205], v[36:39]
	v_mfma_f32_16x16x32_bf16 v[32:35], v[180:183], v[202:205], v[32:35]
	v_mfma_f32_16x16x32_bf16 v[20:23], v[172:175], v[210:213], v[20:23]
	v_mfma_f32_16x16x32_bf16 v[16:19], v[180:183], v[210:213], v[16:19]
	v_mfma_f32_16x16x32_bf16 v[4:7], v[172:175], v[218:221], v[4:7]
	v_mfma_f32_16x16x32_bf16 v[0:3], v[180:183], v[218:221], v[0:3]
	v_mfma_f32_16x16x32_bf16 v[52:55], v[176:179], v[198:201], v[52:55]
	v_mfma_f32_16x16x32_bf16 v[48:51], v[190:193], v[198:201], v[48:51]
	v_mfma_f32_16x16x32_bf16 v[36:39], v[176:179], v[206:209], v[36:39]
	v_mfma_f32_16x16x32_bf16 v[32:35], v[190:193], v[206:209], v[32:35]
	v_mfma_f32_16x16x32_bf16 v[20:23], v[176:179], v[214:217], v[20:23]
	v_mfma_f32_16x16x32_bf16 v[16:19], v[190:193], v[214:217], v[16:19]
	v_mfma_f32_16x16x32_bf16 v[4:7], v[176:179], v[222:225], v[4:7]
	v_mfma_f32_16x16x32_bf16 v[0:3], v[190:193], v[222:225], v[0:3]
	s_barrier
	s_setprio 0
	s_add_i32 s12, s12, 2
	s_add_u32 s20, s20, 0x100
	s_addc_u32 s21, s21, 0
	s_add_u32 s10, s10, 0x100
	s_addc_u32 s11, s11, 0
	s_cmp_gt_u32 s12, 29
	s_cbranch_scc1 .Lmy_peel_9_exit
.LBB0_2050:
	ds_read_b128 v[128:131], v159
	ds_read_b128 v[132:135], v159 offset:1024
	ds_read_b128 v[164:167], v159 offset:2048
	ds_read_b128 v[168:171], v159 offset:3072
	ds_read_b128 v[172:175], v160
	ds_read_b128 v[176:179], v160 offset:1024
	ds_read_b128 v[180:183], v160 offset:2048
	ds_read_b128 v[190:193], v160 offset:3072
	s_add_u32 s13, s20, 0xfff80080
	s_addc_u32 s33, s21, -1
	s_cmp_eq_u32 s12, 28
	s_cselect_b32 s41, s1, s33
	s_cselect_b32 s40, s3, s13
	s_cselect_b32 s39, s4, s11
	s_cselect_b32 s38, s5, s10
	v_lshl_add_u64 v[226:227], s[20:21], 0, v[148:149]
	s_add_i32 m0, s7, 0xc000
	ds_read_b128 v[194:197], v161
	ds_read_b128 v[198:201], v161 offset:1024
	ds_read_b128 v[202:205], v161 offset:2048
	ds_read_b128 v[206:209], v161 offset:3072
	ds_read_b128 v[210:213], v161 offset:4096
	ds_read_b128 v[214:217], v161 offset:5120
	ds_read_b128 v[218:221], v161 offset:6144
	ds_read_b128 v[222:225], v161 offset:7168
	global_load_lds_dwordx4 v[226:227], off
	v_lshl_add_u64 v[226:227], s[20:21], 0, v[150:151]
	s_add_i32 m0, s7, 0xe000
	s_nop 0
	global_load_lds_dwordx4 v[226:227], off
	s_waitcnt vmcnt(8)
	s_waitcnt lgkmcnt(0)
	s_setprio 1
	s_barrier
; #define PG8_STAGE(bufoff, gbase, voff) do { _Pragma("unroll") for (int _i = 0; _i < 2; ++_i) \
;         __builtin_amdgcn_global_load_lds((const unsigned*)((const char*)(gbase) + (voff)[_i]), (PG8_LAS unsigned*)(lds + (bufoff) + ldsw + _i * 8192), 16, 0, 0); } while (0)
; #define PG8_LDA(dst, b, h) do { _Pragma("unroll") for (int m = 0; m < 4; ++m) _Pragma("unroll") for (int k = 0; k < 2; ++k) dst[m][k] = *(const PG8_LAS bf16x8*)(lds + PG8_SA(b, h) + aoff + m * 2048 + k * 1024); } while (0)
; #define PG8_MMA(ai, bj, At, Bt) do { __builtin_amdgcn_s_setprio(1); _Pragma("unroll") for (int m = 0; m < 4; ++m) _Pragma("unroll") for (int n = 0; n < 2; ++n) _Pragma("unroll") for (int k = 0; k < 2; ++k) \
;         acc[ai][bj][m][n] = __builtin_amdgcn_mfma_f32_16x16x32_bf16(Bt[n][k], At[m][k], acc[ai][bj][m][n], 0, 0, 0); __builtin_amdgcn_s_setprio(0); } while (0)
; #define PG8_WAIT_V(n) asm volatile("s_waitcnt vmcnt(" #n ")" ::: "memory")
; #define PG8_WAIT_L(n) asm volatile("s_waitcnt lgkmcnt(" #n ")" ::: "memory")
; #define PG8_BAR __builtin_amdgcn_s_barrier()
; #define PG8_SCHED __builtin_amdgcn_sched_barrier(0)
; template <class Epi, class Sched, bool ALIGN_EPI = false, bool SP2 = false>
; __device__ __forceinline__ void gemm_phase(PG8_LAS unsigned char* lds, const Gemm g, const Sched& S, const Epi& E) {
;     ...
;             PG8_WAIT_V(8); PG8_WAIT_L(0); PG8_BAR; PG8_MMA(0, 0, At, B0); PG8_MMA(0, 1, At, B1); PG8_BAR; PG8_SCHED;
;             PG8_LDA(At, 0, 1); PG8_STAGE(PG8_SB(0, 0), b2, voffB); PG8_STAGE(PG8_SB(0, 1), b2 + hstepB, voffB); PG8_STAGE(PG8_SA(0, 0), a2, voffA);
;             PG8_WAIT_V(8); PG8_WAIT_L(0); PG8_BAR; PG8_MMA(1, 0, At, B0); PG8_MMA(1, 1, At, B1); PG8_BAR; PG8_SCHED;
	v_mfma_f32_16x16x32_bf16 v[124:127], v[128:131], v[194:197], v[124:127]
	v_mfma_f32_16x16x32_bf16 v[120:123], v[164:167], v[194:197], v[120:123]
	v_mfma_f32_16x16x32_bf16 v[108:111], v[128:131], v[202:205], v[108:111]
	v_mfma_f32_16x16x32_bf16 v[104:107], v[164:167], v[202:205], v[104:107]
	v_mfma_f32_16x16x32_bf16 v[92:95], v[128:131], v[210:213], v[92:95]
	v_mfma_f32_16x16x32_bf16 v[88:91], v[164:167], v[210:213], v[88:91]
	v_mfma_f32_16x16x32_bf16 v[76:79], v[128:131], v[218:221], v[76:79]
	v_mfma_f32_16x16x32_bf16 v[72:75], v[164:167], v[218:221], v[72:75]
	v_mfma_f32_16x16x32_bf16 v[124:127], v[132:135], v[198:201], v[124:127]
	v_mfma_f32_16x16x32_bf16 v[120:123], v[168:171], v[198:201], v[120:123]
	v_mfma_f32_16x16x32_bf16 v[108:111], v[132:135], v[206:209], v[108:111]
	v_mfma_f32_16x16x32_bf16 v[104:107], v[168:171], v[206:209], v[104:107]
	v_mfma_f32_16x16x32_bf16 v[92:95], v[132:135], v[214:217], v[92:95]
	v_mfma_f32_16x16x32_bf16 v[88:91], v[168:171], v[214:217], v[88:91]
	v_mfma_f32_16x16x32_bf16 v[76:79], v[132:135], v[222:225], v[76:79]
	v_mfma_f32_16x16x32_bf16 v[72:75], v[168:171], v[222:225], v[72:75]
	s_setprio 0
	s_setprio 1
	v_mfma_f32_16x16x32_bf16 v[116:119], v[172:175], v[194:197], v[116:119]
	v_mfma_f32_16x16x32_bf16 v[112:115], v[180:183], v[194:197], v[112:115]
	v_mfma_f32_16x16x32_bf16 v[100:103], v[172:175], v[202:205], v[100:103]
	v_mfma_f32_16x16x32_bf16 v[96:99], v[180:183], v[202:205], v[96:99]
	v_mfma_f32_16x16x32_bf16 v[84:87], v[172:175], v[210:213], v[84:87]
	v_mfma_f32_16x16x32_bf16 v[80:83], v[180:183], v[210:213], v[80:83]
	v_mfma_f32_16x16x32_bf16 v[68:71], v[172:175], v[218:221], v[68:71]
	v_mfma_f32_16x16x32_bf16 v[64:67], v[180:183], v[218:221], v[64:67]
	v_mfma_f32_16x16x32_bf16 v[116:119], v[176:179], v[198:201], v[116:119]
	v_mfma_f32_16x16x32_bf16 v[112:115], v[190:193], v[198:201], v[112:115]
	v_mfma_f32_16x16x32_bf16 v[100:103], v[176:179], v[206:209], v[100:103]
	v_mfma_f32_16x16x32_bf16 v[96:99], v[190:193], v[206:209], v[96:99]
	v_mfma_f32_16x16x32_bf16 v[84:87], v[176:179], v[214:217], v[84:87]
	v_mfma_f32_16x16x32_bf16 v[80:83], v[190:193], v[214:217], v[80:83]
	v_mfma_f32_16x16x32_bf16 v[68:71], v[176:179], v[222:225], v[68:71]
	v_mfma_f32_16x16x32_bf16 v[64:67], v[190:193], v[222:225], v[64:67]
	s_barrier
	s_setprio 0
	s_add_i32 s13, s69, s6
	v_lshl_add_u64 v[226:227], s[38:39], 0, v[138:139]
	s_mov_b32 m0, s13
	ds_read_b128 v[194:197], v161 offset:16384
	ds_read_b128 v[198:201], v161 offset:17408
	ds_read_b128 v[202:205], v161 offset:18432
	ds_read_b128 v[206:209], v161 offset:19456
	ds_read_b128 v[210:213], v161 offset:20480
	ds_read_b128 v[214:217], v161 offset:21504
	ds_read_b128 v[218:221], v161 offset:22528
	ds_read_b128 v[222:225], v161 offset:23552
	global_load_lds_dwordx4 v[226:227], off
	s_add_i32 m0, s13, 0x2000
	s_add_u32 s44, s38, 0x80000
	v_lshl_add_u64 v[228:229], s[38:39], 0, v[142:143]
	s_addc_u32 s45, s39, 0
	s_add_i32 s13, s70, s6
	global_load_lds_dwordx4 v[228:229], off
	v_lshl_add_u64 v[230:231], s[44:45], 0, v[138:139]
	s_mov_b32 m0, s13
	v_lshl_add_u64 v[232:233], s[40:41], 0, v[140:141]
	global_load_lds_dwordx4 v[230:231], off
	v_lshl_add_u64 v[230:231], s[44:45], 0, v[142:143]
	s_add_i32 m0, s13, 0x2000
	s_nop 0
	global_load_lds_dwordx4 v[230:231], off
	v_lshl_add_u64 v[230:231], s[40:41], 0, v[136:137]
	s_mov_b32 m0, s7
	s_nop 0
	global_load_lds_dwordx4 v[230:231], off
	s_mov_b32 m0, s8
	s_nop 0
	global_load_lds_dwordx4 v[232:233], off
	s_waitcnt vmcnt(8)
	s_waitcnt lgkmcnt(0)
	s_setprio 1
	s_barrier
	v_mfma_f32_16x16x32_bf16 v[60:63], v[128:131], v[194:197], v[60:63]
	v_mfma_f32_16x16x32_bf16 v[56:59], v[164:167], v[194:197], v[56:59]
	v_mfma_f32_16x16x32_bf16 v[44:47], v[128:131], v[202:205], v[44:47]
	v_mfma_f32_16x16x32_bf16 v[40:43], v[164:167], v[202:205], v[40:43]
	v_mfma_f32_16x16x32_bf16 v[28:31], v[128:131], v[210:213], v[28:31]
	v_mfma_f32_16x16x32_bf16 v[24:27], v[164:167], v[210:213], v[24:27]
	v_mfma_f32_16x16x32_bf16 v[12:15], v[128:131], v[218:221], v[12:15]
	v_mfma_f32_16x16x32_bf16 v[8:11], v[164:167], v[218:221], v[8:11]
	v_mfma_f32_16x16x32_bf16 v[60:63], v[132:135], v[198:201], v[60:63]
	v_mfma_f32_16x16x32_bf16 v[56:59], v[168:171], v[198:201], v[56:59]
	v_mfma_f32_16x16x32_bf16 v[44:47], v[132:135], v[206:209], v[44:47]
	v_mfma_f32_16x16x32_bf16 v[40:43], v[168:171], v[206:209], v[40:43]
	v_mfma_f32_16x16x32_bf16 v[28:31], v[132:135], v[214:217], v[28:31]
	v_mfma_f32_16x16x32_bf16 v[24:27], v[168:171], v[214:217], v[24:27]
	v_mfma_f32_16x16x32_bf16 v[12:15], v[132:135], v[222:225], v[12:15]
	v_mfma_f32_16x16x32_bf16 v[8:11], v[168:171], v[222:225], v[8:11]
	s_setprio 0
	s_setprio 1
	v_mfma_f32_16x16x32_bf16 v[52:55], v[172:175], v[194:197], v[52:55]
	v_mfma_f32_16x16x32_bf16 v[48:51], v[180:183], v[194:197], v[48:51]
	v_mfma_f32_16x16x32_bf16 v[36:39], v[172:175], v[202:205], v[36:39]
	v_mfma_f32_16x16x32_bf16 v[32:35], v[180:183], v[202:205], v[32:35]
	v_mfma_f32_16x16x32_bf16 v[20:23], v[172:175], v[210:213], v[20:23]
	v_mfma_f32_16x16x32_bf16 v[16:19], v[180:183], v[210:213], v[16:19]
	v_mfma_f32_16x16x32_bf16 v[4:7], v[172:175], v[218:221], v[4:7]
	v_mfma_f32_16x16x32_bf16 v[0:3], v[180:183], v[218:221], v[0:3]
	v_mfma_f32_16x16x32_bf16 v[52:55], v[176:179], v[198:201], v[52:55]
	v_mfma_f32_16x16x32_bf16 v[48:51], v[190:193], v[198:201], v[48:51]
	v_mfma_f32_16x16x32_bf16 v[36:39], v[176:179], v[206:209], v[36:39]
	v_mfma_f32_16x16x32_bf16 v[32:35], v[190:193], v[206:209], v[32:35]
	v_mfma_f32_16x16x32_bf16 v[20:23], v[176:179], v[214:217], v[20:23]
	v_mfma_f32_16x16x32_bf16 v[16:19], v[190:193], v[214:217], v[16:19]
	v_mfma_f32_16x16x32_bf16 v[4:7], v[176:179], v[222:225], v[4:7]
	v_mfma_f32_16x16x32_bf16 v[0:3], v[190:193], v[222:225], v[0:3]
	s_barrier
; #define PG8_STAGE(bufoff, gbase, voff) do { _Pragma("unroll") for (int _i = 0; _i < 2; ++_i) \
;         __builtin_amdgcn_global_load_lds((const unsigned*)((const char*)(gbase) + (voff)[_i]), (PG8_LAS unsigned*)(lds + (bufoff) + ldsw + _i * 8192), 16, 0, 0); } while (0)
; #define PG8_LDA(dst, b, h) do { _Pragma("unroll") for (int m = 0; m < 4; ++m) _Pragma("unroll") for (int k = 0; k < 2; ++k) dst[m][k] = *(const PG8_LAS bf16x8*)(lds + PG8_SA(b, h) + aoff + m * 2048 + k * 1024); } while (0)
; #define PG8_LDB(dst, b, h) do { _Pragma("unroll") for (int n = 0; n < 2; ++n) _Pragma("unroll") for (int k = 0; k < 2; ++k) dst[n][k] = *(const PG8_LAS bf16x8*)(lds + PG8_SB(b, h) + boff + n * 2048 + k * 1024); } while (0)
; #define PG8_MMA(ai, bj, At, Bt) do { __builtin_amdgcn_s_setprio(1); _Pragma("unroll") for (int m = 0; m < 4; ++m) _Pragma("unroll") for (int n = 0; n < 2; ++n) _Pragma("unroll") for (int k = 0; k < 2; ++k) \
;         acc[ai][bj][m][n] = __builtin_amdgcn_mfma_f32_16x16x32_bf16(Bt[n][k], At[m][k], acc[ai][bj][m][n], 0, 0, 0); __builtin_amdgcn_s_setprio(0); } while (0)
; #define PG8_WAIT_V(n) asm volatile("s_waitcnt vmcnt(" #n ")" ::: "memory")
; #define PG8_WAIT_L(n) asm volatile("s_waitcnt lgkmcnt(" #n ")" ::: "memory")
; #define PG8_BAR __builtin_amdgcn_s_barrier()
; #define PG8_SCHED __builtin_amdgcn_sched_barrier(0)
; template <class Epi, class Sched, bool ALIGN_EPI = false, bool SP2 = false>
; __device__ __forceinline__ void gemm_phase(PG8_LAS unsigned char* lds, const Gemm g, const Sched& S, const Epi& E) {
;     ...
;             PG8_LDB(B0, 1, 0); PG8_LDB(B1, 1, 1); PG8_SCHED; PG8_LDA(At, 1, 0); PG8_STAGE(PG8_SA(0, 1), a2 + hstepA, voffA);
;             PG8_WAIT_V(8); PG8_WAIT_L(0); PG8_BAR; PG8_MMA(0, 0, At, B0); PG8_MMA(0, 1, At, B1); PG8_BAR; PG8_SCHED;
;             PG8_LDA(At, 1, 1); PG8_STAGE(PG8_SB(1, 0), b3, voffB); PG8_STAGE(PG8_SB(1, 1), b3 + hstepB, voffB); PG8_STAGE(PG8_SA(1, 0), a3, voffA);
;             PG8_WAIT_V(8); PG8_WAIT_L(0); PG8_BAR; PG8_MMA(1, 0, At, B0); PG8_MMA(1, 1, At, B1); PG8_BAR; PG8_SCHED;
	s_setprio 0
	s_add_i32 s13, 0, 0x18000
	v_add_u32_e32 v144, s13, v157
	s_add_i32 s33, 0, 0x1c000
	ds_read_b128 v[128:131], v144
	ds_read_b128 v[132:135], v144 offset:1024
	ds_read_b128 v[164:167], v144 offset:2048
	ds_read_b128 v[168:171], v144 offset:3072
	v_add_u32_e32 v144, s33, v157
	ds_read_b128 v[172:175], v144
	ds_read_b128 v[176:179], v144 offset:1024
	ds_read_b128 v[180:183], v144 offset:2048
	ds_read_b128 v[190:193], v144 offset:3072
	s_add_u32 s40, s40, 0x80000
	s_addc_u32 s41, s41, 0
	s_mov_b32 m0, s9
	v_lshl_add_u64 v[234:235], s[40:41], 0, v[136:137]
	ds_read_b128 v[194:197], v161 offset:32768
	ds_read_b128 v[198:201], v161 offset:33792
	ds_read_b128 v[202:205], v161 offset:34816
	ds_read_b128 v[206:209], v161 offset:35840
	ds_read_b128 v[210:213], v161 offset:36864
	ds_read_b128 v[214:217], v161 offset:37888
	ds_read_b128 v[218:221], v161 offset:38912
	ds_read_b128 v[222:225], v161 offset:39936
	global_load_lds_dwordx4 v[234:235], off
	v_lshl_add_u64 v[234:235], s[40:41], 0, v[140:141]
	s_mov_b32 m0, s35
	s_nop 0
	global_load_lds_dwordx4 v[234:235], off
	s_waitcnt vmcnt(8)
	s_waitcnt lgkmcnt(0)
	s_setprio 1
	s_barrier
	v_mfma_f32_16x16x32_bf16 v[124:127], v[128:131], v[194:197], v[124:127]
	v_mfma_f32_16x16x32_bf16 v[120:123], v[164:167], v[194:197], v[120:123]
	v_mfma_f32_16x16x32_bf16 v[108:111], v[128:131], v[202:205], v[108:111]
	v_mfma_f32_16x16x32_bf16 v[104:107], v[164:167], v[202:205], v[104:107]
	v_mfma_f32_16x16x32_bf16 v[92:95], v[128:131], v[210:213], v[92:95]
	v_mfma_f32_16x16x32_bf16 v[88:91], v[164:167], v[210:213], v[88:91]
	v_mfma_f32_16x16x32_bf16 v[76:79], v[128:131], v[218:221], v[76:79]
	v_mfma_f32_16x16x32_bf16 v[72:75], v[164:167], v[218:221], v[72:75]
	v_mfma_f32_16x16x32_bf16 v[124:127], v[132:135], v[198:201], v[124:127]
	v_mfma_f32_16x16x32_bf16 v[120:123], v[168:171], v[198:201], v[120:123]
	v_mfma_f32_16x16x32_bf16 v[108:111], v[132:135], v[206:209], v[108:111]
	v_mfma_f32_16x16x32_bf16 v[104:107], v[168:171], v[206:209], v[104:107]
	v_mfma_f32_16x16x32_bf16 v[92:95], v[132:135], v[214:217], v[92:95]
	v_mfma_f32_16x16x32_bf16 v[88:91], v[168:171], v[214:217], v[88:91]
	v_mfma_f32_16x16x32_bf16 v[76:79], v[132:135], v[222:225], v[76:79]
	v_mfma_f32_16x16x32_bf16 v[72:75], v[168:171], v[222:225], v[72:75]
	s_setprio 0
	s_setprio 1
	v_mfma_f32_16x16x32_bf16 v[116:119], v[172:175], v[194:197], v[116:119]
	v_mfma_f32_16x16x32_bf16 v[112:115], v[180:183], v[194:197], v[112:115]
	v_mfma_f32_16x16x32_bf16 v[100:103], v[172:175], v[202:205], v[100:103]
	v_mfma_f32_16x16x32_bf16 v[96:99], v[180:183], v[202:205], v[96:99]
	v_mfma_f32_16x16x32_bf16 v[84:87], v[172:175], v[210:213], v[84:87]
	v_mfma_f32_16x16x32_bf16 v[80:83], v[180:183], v[210:213], v[80:83]
	v_mfma_f32_16x16x32_bf16 v[68:71], v[172:175], v[218:221], v[68:71]
	v_mfma_f32_16x16x32_bf16 v[64:67], v[180:183], v[218:221], v[64:67]
	v_mfma_f32_16x16x32_bf16 v[116:119], v[176:179], v[198:201], v[116:119]
	v_mfma_f32_16x16x32_bf16 v[112:115], v[190:193], v[198:201], v[112:115]
	v_mfma_f32_16x16x32_bf16 v[100:103], v[176:179], v[206:209], v[100:103]
	v_mfma_f32_16x16x32_bf16 v[96:99], v[190:193], v[206:209], v[96:99]
	v_mfma_f32_16x16x32_bf16 v[84:87], v[176:179], v[214:217], v[84:87]
	v_mfma_f32_16x16x32_bf16 v[80:83], v[190:193], v[214:217], v[80:83]
	v_mfma_f32_16x16x32_bf16 v[68:71], v[176:179], v[222:225], v[68:71]
	v_mfma_f32_16x16x32_bf16 v[64:67], v[190:193], v[222:225], v[64:67]
	s_barrier
	s_setprio 0
	s_add_i32 s13, s13, s6
	v_lshl_add_u64 v[226:227], v[226:227], 0, s[54:55]
	s_mov_b32 m0, s13
	ds_read_b128 v[194:197], v161 offset:49152
	ds_read_b128 v[198:201], v161 offset:50176
	ds_read_b128 v[202:205], v161 offset:51200
	ds_read_b128 v[206:209], v161 offset:52224
	ds_read_b128 v[210:213], v161 offset:53248
	ds_read_b128 v[214:217], v161 offset:54272
	ds_read_b128 v[218:221], v161 offset:55296
	ds_read_b128 v[222:225], v161 offset:56320
	global_load_lds_dwordx4 v[226:227], off
	s_add_i32 m0, s13, 0x2000
	s_add_u32 s38, s38, 0x80080
	v_lshl_add_u64 v[226:227], v[228:229], 0, s[54:55]
	s_addc_u32 s39, s39, 0
	s_add_i32 s13, s33, s6
	global_load_lds_dwordx4 v[226:227], off
	v_lshl_add_u64 v[226:227], s[38:39], 0, v[138:139]
	s_mov_b32 m0, s13
	s_nop 0
	global_load_lds_dwordx4 v[226:227], off
	v_lshl_add_u64 v[226:227], s[38:39], 0, v[142:143]
	s_add_i32 m0, s13, 0x2000
	s_nop 0
	global_load_lds_dwordx4 v[226:227], off
	v_lshl_add_u64 v[226:227], v[230:231], 0, s[54:55]
	s_mov_b32 m0, s51
	s_nop 0
	global_load_lds_dwordx4 v[226:227], off
	v_lshl_add_u64 v[226:227], v[232:233], 0, s[54:55]
	s_mov_b32 m0, s68
	s_nop 0
	global_load_lds_dwordx4 v[226:227], off
	s_waitcnt vmcnt(8)
	s_waitcnt lgkmcnt(0)
	s_setprio 1
	s_barrier
; __device__ __forceinline__ float fast_sigmoid(float x) { return __builtin_amdgcn_rcpf(1.f + __builtin_amdgcn_exp2f(-1.4426950408889634f * x)); }
;     __device__ __forceinline__ void operator()(const f32x4 (&acc)[2][2][4][2], const Unit& u, int wr, int wc, int fr, int fq) const {
;         const int sec = u.pn >> 3, row0 = u.pm * BM + wr * 64 + fr, col0 = u.pn * BM + wc * 32 + 8 * fq, cs0 = (u.pn & 7) * BM + wc * 32 + 8 * fq;
;         float lb[2][8];
;         if (sec == 1 || sec == 2) {
; #pragma unroll
;             for (int bj = 0; bj < 2; ++bj)
; #pragma unroll
;                 for (int e = 0; e < 8; ++e) { const int c = cs0 + bj * HALF + e; lb[bj][e] = fast_sigmoid(lbl[2048 + c] - lbl[c]); }
; template <class Epi, class Sched, bool ALIGN_EPI = false, bool SP2 = false>
; __device__ __forceinline__ void gemm_phase(PG8_LAS unsigned char* lds, const Gemm g, const Sched& S, const Epi& E) {
;     ...
;             PG8_WAIT_V(8); PG8_WAIT_L(0); PG8_BAR; PG8_MMA(1, 0, At, B0); PG8_MMA(1, 1, At, B1); PG8_BAR; PG8_SCHED;
;             } else {
;             PG8_LDB(B0, 0, 0); PG8_SCHED; PG8_LDA(At, 0, 0); PG8_STAGE(PG8_SA(1, 1), a1 + hstepA, voffA);
;             PG8_WAIT_L(8); PG8_BAR; PG8_WAIT_L(0); PG8_MMA(0, 0, At, B0); PG8_BAR; PG8_SCHED;
;             PG8_LDB(B1, 0, 1); PG8_STAGE(PG8_SB(0, 0), b2, voffB);
;             PG8_BAR; PG8_WAIT_L(0); PG8_MMA(0, 1, At, B1); PG8_BAR;
;             PG8_LDA(At, 0, 1); PG8_STAGE(PG8_SA(0, 0), a2, voffA);
;             PG8_BAR; PG8_WAIT_L(0); PG8_MMA(1, 0, At, B0); PG8_BAR; PG8_SCHED;
;             PG8_STAGE(PG8_SB(0, 1), b2 + hstepB, voffB);
;             PG8_WAIT_V(6); PG8_BAR; PG8_MMA(1, 1, At, B1); PG8_BAR;
;             PG8_LDB(B0, 1, 0); PG8_SCHED; PG8_LDA(At, 1, 0); PG8_STAGE(PG8_SA(0, 1), a2 + hstepA, voffA);
;             PG8_WAIT_L(8); PG8_BAR; PG8_WAIT_L(0); PG8_MMA(0, 0, At, B0); PG8_BAR; PG8_SCHED;
;             PG8_LDB(B1, 1, 1); PG8_STAGE(PG8_SB(1, 0), b3, voffB);
;             PG8_BAR; PG8_WAIT_L(0); PG8_MMA(0, 1, At, B1); PG8_BAR;
;             PG8_LDA(At, 1, 1); PG8_STAGE(PG8_SA(1, 0), a3, voffA);
;             PG8_BAR; PG8_WAIT_L(0); PG8_MMA(1, 0, At, B0); PG8_BAR; PG8_SCHED;
;             PG8_STAGE(PG8_SB(1, 1), b3 + hstepB, voffB);
;             PG8_WAIT_V(6); PG8_BAR; PG8_MMA(1, 1, At, B1); PG8_BAR;
;             }
;         }
;         if constexpr (ALIGN_EPI) { if (wr == 0) PG8_BAR; }
	v_mfma_f32_16x16x32_bf16 v[60:63], v[128:131], v[194:197], v[60:63]
	v_mfma_f32_16x16x32_bf16 v[56:59], v[164:167], v[194:197], v[56:59]
	v_mfma_f32_16x16x32_bf16 v[44:47], v[128:131], v[202:205], v[44:47]
	v_mfma_f32_16x16x32_bf16 v[40:43], v[164:167], v[202:205], v[40:43]
	v_mfma_f32_16x16x32_bf16 v[28:31], v[128:131], v[210:213], v[28:31]
	v_mfma_f32_16x16x32_bf16 v[24:27], v[164:167], v[210:213], v[24:27]
	v_mfma_f32_16x16x32_bf16 v[12:15], v[128:131], v[218:221], v[12:15]
	v_mfma_f32_16x16x32_bf16 v[8:11], v[164:167], v[218:221], v[8:11]
	v_mfma_f32_16x16x32_bf16 v[60:63], v[132:135], v[198:201], v[60:63]
	v_mfma_f32_16x16x32_bf16 v[56:59], v[168:171], v[198:201], v[56:59]
	v_mfma_f32_16x16x32_bf16 v[44:47], v[132:135], v[206:209], v[44:47]
	v_mfma_f32_16x16x32_bf16 v[40:43], v[168:171], v[206:209], v[40:43]
	v_mfma_f32_16x16x32_bf16 v[28:31], v[132:135], v[214:217], v[28:31]
	v_mfma_f32_16x16x32_bf16 v[24:27], v[168:171], v[214:217], v[24:27]
	v_mfma_f32_16x16x32_bf16 v[12:15], v[132:135], v[222:225], v[12:15]
	v_mfma_f32_16x16x32_bf16 v[8:11], v[168:171], v[222:225], v[8:11]
	s_setprio 0
	s_setprio 1
	v_mfma_f32_16x16x32_bf16 v[52:55], v[172:175], v[194:197], v[52:55]
	v_mfma_f32_16x16x32_bf16 v[48:51], v[180:183], v[194:197], v[48:51]
	v_mfma_f32_16x16x32_bf16 v[36:39], v[172:175], v[202:205], v[36:39]
	v_mfma_f32_16x16x32_bf16 v[32:35], v[180:183], v[202:205], v[32:35]
	v_mfma_f32_16x16x32_bf16 v[20:23], v[172:175], v[210:213], v[20:23]
	v_mfma_f32_16x16x32_bf16 v[16:19], v[180:183], v[210:213], v[16:19]
	v_mfma_f32_16x16x32_bf16 v[4:7], v[172:175], v[218:221], v[4:7]
	v_mfma_f32_16x16x32_bf16 v[0:3], v[180:183], v[218:221], v[0:3]
	v_mfma_f32_16x16x32_bf16 v[52:55], v[176:179], v[198:201], v[52:55]
	v_mfma_f32_16x16x32_bf16 v[48:51], v[190:193], v[198:201], v[48:51]
	v_mfma_f32_16x16x32_bf16 v[36:39], v[176:179], v[206:209], v[36:39]
	v_mfma_f32_16x16x32_bf16 v[32:35], v[190:193], v[206:209], v[32:35]
	v_mfma_f32_16x16x32_bf16 v[20:23], v[176:179], v[214:217], v[20:23]
	v_mfma_f32_16x16x32_bf16 v[16:19], v[190:193], v[214:217], v[16:19]
	v_mfma_f32_16x16x32_bf16 v[4:7], v[176:179], v[222:225], v[4:7]
	v_mfma_f32_16x16x32_bf16 v[0:3], v[190:193], v[222:225], v[0:3]
	s_barrier
	s_setprio 0
	s_add_i32 s12, s12, 2
	s_add_u32 s20, s20, 0x100
	s_addc_u32 s21, s21, 0
	s_add_u32 s10, s10, 0x100
	s_addc_u32 s11, s11, 0
	s_cmp_gt_u32 s12, 29
	s_cbranch_scc0 .LBB0_2050
.Lmy_peel_9_exit:
	s_and_b64 vcc, exec, s[56:57]
	s_cbranch_vccz .LBB0_2053
	s_barrier
.LBB0_2053:
	s_ashr_i32 s1, s34, 3
	s_add_i32 s3, s1, -1
	s_cmp_gt_u32 s3, 1
	s_cselect_b64 s[20:21], -1, 0
	s_and_b64 vcc, exec, s[20:21]
	s_cbranch_vccnz .LBB0_2055
	s_lshl_b32 s3, s34, 8
	s_and_b32 s3, s3, 0x700
	v_or_b32_e32 v128, s3, v158
	v_lshlrev_b32_e32 v144, 2, v128
	v_lshl_add_u64 v[178:179], s[26:27], 0, v[144:145]
	s_mov_b64 s[4:5], 0x2000
	v_add_co_u32_e32 v180, vcc, 0x2000, v178
	v_lshl_add_u64 v[132:133], v[178:179], 0, s[4:5]
	s_nop 0
	v_addc_co_u32_e32 v181, vcc, 0, v179, vcc
	global_load_dwordx4 v[128:131], v[180:181], off
	s_nop 0
	global_load_dwordx4 v[132:135], v[132:133], off offset:16
	s_nop 0
	global_load_dwordx4 v[164:167], v144, s[26:27] offset:16
	global_load_dwordx4 v[168:171], v144, s[26:27]
	s_mov_b64 s[4:5], 0x2200
	s_waitcnt vmcnt(0)
	v_sub_f32_e32 v128, v128, v168
	v_mul_f32_e32 v128, 0xbfb8aa3b, v128
	v_exp_f32_e32 v128, v128
	s_nop 0
	v_add_f32_e32 v128, 1.0, v128
	v_rcp_f32_e32 v177, v128
	v_sub_f32_e32 v128, v129, v169
	v_mul_f32_e32 v128, 0xbfb8aa3b, v128
	v_exp_f32_e32 v128, v128
	s_nop 0
	v_add_f32_e32 v128, 1.0, v128
	v_rcp_f32_e32 v176, v128
	v_sub_f32_e32 v128, v130, v170
	v_mul_f32_e32 v128, 0xbfb8aa3b, v128
	v_exp_f32_e32 v128, v128
	s_nop 0
	v_add_f32_e32 v128, 1.0, v128
	v_rcp_f32_e32 v175, v128
	v_sub_f32_e32 v128, v131, v171
	v_mul_f32_e32 v128, 0xbfb8aa3b, v128
	v_exp_f32_e32 v128, v128
	s_nop 0
	v_add_f32_e32 v128, 1.0, v128
	v_rcp_f32_e32 v174, v128
	v_sub_f32_e32 v128, v132, v164
	v_mul_f32_e32 v128, 0xbfb8aa3b, v128
	v_exp_f32_e32 v128, v128
	s_nop 0
	v_add_f32_e32 v128, 1.0, v128
	v_rcp_f32_e32 v172, v128
	v_sub_f32_e32 v128, v133, v165
	v_mul_f32_e32 v128, 0xbfb8aa3b, v128
	v_exp_f32_e32 v128, v128
	s_nop 0
	v_add_f32_e32 v128, 1.0, v128
	v_rcp_f32_e32 v171, v128
	v_sub_f32_e32 v128, v134, v166
	v_mul_f32_e32 v128, 0xbfb8aa3b, v128
	v_exp_f32_e32 v128, v128
	s_nop 0
	v_add_f32_e32 v128, 1.0, v128
	v_rcp_f32_e32 v170, v128
	v_sub_f32_e32 v128, v135, v167
	v_mul_f32_e32 v128, 0xbfb8aa3b, v128
	v_exp_f32_e32 v128, v128
	s_nop 0
	v_add_f32_e32 v128, 1.0, v128
	v_rcp_f32_e32 v169, v128
	v_lshl_add_u64 v[128:129], v[178:179], 0, s[4:5]
	global_load_dwordx4 v[178:181], v[180:181], off offset:512
	s_nop 0
	global_load_dwordx4 v[128:131], v[128:129], off offset:16
	s_nop 0
	global_load_dwordx4 v[132:135], v144, s[26:27] offset:528
	global_load_dwordx4 v[190:193], v144, s[26:27] offset:512
	s_waitcnt vmcnt(1)
	v_sub_f32_e32 v128, v128, v132
	v_mul_f32_e32 v128, 0xbfb8aa3b, v128
	v_exp_f32_e32 v128, v128
	s_waitcnt vmcnt(0)
	v_sub_f32_e32 v164, v179, v191
	v_mul_f32_e32 v164, 0xbfb8aa3b, v164
	v_exp_f32_e32 v164, v164
	v_add_f32_e32 v128, 1.0, v128
	v_rcp_f32_e32 v167, v128
	v_sub_f32_e32 v128, v129, v133
	v_mul_f32_e32 v128, 0xbfb8aa3b, v128
	v_exp_f32_e32 v128, v128
	v_add_f32_e32 v164, 1.0, v164
	v_rcp_f32_e32 v166, v164
	v_sub_f32_e32 v164, v180, v192
	v_add_f32_e32 v128, 1.0, v128
	v_rcp_f32_e32 v168, v128
	v_sub_f32_e32 v128, v130, v134
	v_mul_f32_e32 v164, 0xbfb8aa3b, v164
	v_mul_f32_e32 v128, 0xbfb8aa3b, v128
	v_exp_f32_e32 v164, v164
	v_exp_f32_e32 v128, v128
	v_sub_f32_e32 v144, v178, v190
	v_mul_f32_e32 v144, 0xbfb8aa3b, v144
	v_add_f32_e32 v164, 1.0, v164
	v_add_f32_e32 v128, 1.0, v128
	v_rcp_f32_e32 v165, v164
	v_sub_f32_e32 v164, v181, v193
	v_rcp_f32_e32 v173, v128
	v_sub_f32_e32 v128, v131, v135
	v_mul_f32_e32 v164, 0xbfb8aa3b, v164
	v_mul_f32_e32 v128, 0xbfb8aa3b, v128
	v_exp_f32_e32 v144, v144
	v_exp_f32_e32 v164, v164
	v_exp_f32_e32 v128, v128
	v_add_f32_e32 v144, 1.0, v144
	v_add_f32_e32 v164, 1.0, v164
	v_add_f32_e32 v128, 1.0, v128
	v_rcp_f32_e32 v144, v144
	v_rcp_f32_e32 v164, v164
	v_rcp_f32_e32 v178, v128

; #define PG8_STAGE(bufoff, gbase, voff) do { _Pragma("unroll") for (int _i = 0; _i < 2; ++_i) \
;         __builtin_amdgcn_global_load_lds((const unsigned*)((const char*)(gbase) + (voff)[_i]), (PG8_LAS unsigned*)(lds + (bufoff) + ldsw + _i * 8192), 16, 0, 0); } while (0)
; #define PG8_LDA(dst, b, h) do { _Pragma("unroll") for (int m = 0; m < 4; ++m) _Pragma("unroll") for (int k = 0; k < 2; ++k) dst[m][k] = *(const PG8_LAS bf16x8*)(lds + PG8_SA(b, h) + aoff + m * 2048 + k * 1024); } while (0)
; #define PG8_LDB(dst, b, h) do { _Pragma("unroll") for (int n = 0; n < 2; ++n) _Pragma("unroll") for (int k = 0; k < 2; ++k) dst[n][k] = *(const PG8_LAS bf16x8*)(lds + PG8_SB(b, h) + boff + n * 2048 + k * 1024); } while (0)
; #define PG8_WAIT_V(n) asm volatile("s_waitcnt vmcnt(" #n ")" ::: "memory")
; #define PG8_WAIT_L(n) asm volatile("s_waitcnt lgkmcnt(" #n ")" ::: "memory")
; #define PG8_BAR __builtin_amdgcn_s_barrier()
; template <class Epi, class Sched, bool ALIGN_EPI = false, bool SP2 = false>
; __device__ __forceinline__ void gemm_phase(PG8_LAS unsigned char* lds, const Gemm g, const Sched& S, const Epi& E) {
;     ...
;         const char* nA = has_next ? (const char*)g.A + (size_t)nxt.pm * tstepA + (size_t)nxt.z * g.azs + (size_t)(nxt.k0 >> 6) * kstA : cA; const char* nB = has_next ? (const char*)g.Bt + (size_t)nxt.pn * tstepB + (size_t)nxt.z * g.bzs + (size_t)nxt.k0 * 2 : cB;
;         const int nt = cur.nt;
;         for (int t = 0; t < nt; t += 2) {
;             const bool last = (t == nt - 2);
;             const char* a1 = cA + (size_t)(t + 1) * kstA;
;             const char* a2 = last ? nA : cA + (size_t)(t + 2) * kstA; const char* b2 = last ? nB : cB + (size_t)(t + 2) * kstep;
;             const char* a3 = a2 + kstA; const char* b3 = b2 + kstep;
;             if (last && has_next) S.a_ready(nxt);
;             if constexpr (SP2) {
;             PG8_LDB(B0, 0, 0); PG8_LDB(B1, 0, 1); PG8_SCHED; PG8_LDA(At, 0, 0); PG8_STAGE(PG8_SA(1, 1), a1 + hstepA, voffA);
;             PG8_WAIT_V(8); PG8_WAIT_L(0); PG8_BAR; PG8_MMA(0, 0, At, B0); PG8_MMA(0, 1, At, B1); PG8_BAR; PG8_SCHED;
;             PG8_LDA(At, 0, 1); PG8_STAGE(PG8_SB(0, 0), b2, voffB); PG8_STAGE(PG8_SB(0, 1), b2 + hstepB, voffB); PG8_STAGE(PG8_SA(0, 0), a2, voffA);
;             PG8_WAIT_V(8); PG8_WAIT_L(0); PG8_BAR; PG8_MMA(1, 0, At, B0); PG8_MMA(1, 1, At, B1); PG8_BAR; PG8_SCHED;
.LBB0_3057:
	s_ashr_i32 s23, s22, 31
	s_lshl_b64 s[4:5], s[22:23], 20
	v_readlane_b32 s12, v254, 41
	v_readlane_b32 s13, v254, 42
	s_add_u32 s24, s12, s4
	s_addc_u32 s25, s13, s5
	s_and_b64 s[4:5], s[36:37], exec
	s_cselect_b32 s4, s25, s41
	s_cselect_b32 s5, s24, s40
	s_ashr_i32 s21, s20, 31
	s_lshl_b64 s[12:13], s[20:21], 20
	s_add_u32 s30, s3, s12
	s_addc_u32 s31, s6, s13
	s_and_b64 s[12:13], s[36:37], exec
	s_cselect_b32 s12, s31, s43
	s_cselect_b32 s13, s30, s42
	s_add_u32 s40, s40, 0x80080
	s_addc_u32 s41, s41, 0
	s_add_u32 s21, s42, 0x100
	s_addc_u32 s23, s43, 0
	s_mov_b32 s35, -2
	ds_read_b128 v[156:159], v152
	ds_read_b128 v[160:163], v152 offset:1024
	ds_read_b128 v[164:167], v152 offset:2048
	ds_read_b128 v[168:171], v152 offset:3072
	ds_read_b128 v[172:175], v153
	ds_read_b128 v[176:179], v153 offset:1024
	ds_read_b128 v[180:183], v153 offset:2048
	ds_read_b128 v[190:193], v153 offset:3072
	s_add_u32 s42, s40, 0xfff80080
	s_addc_u32 s43, s41, -1
	s_cmp_eq_u32 s35, 28
	s_cselect_b32 s45, s4, s43
	s_cselect_b32 s44, s5, s42
	s_cselect_b32 s43, s12, s23
	s_cselect_b32 s42, s13, s21
	v_lshl_add_u64 v[226:227], s[40:41], 0, v[142:143]
	s_add_i32 m0, s8, 0xc000
	ds_read_b128 v[194:197], v154
	ds_read_b128 v[198:201], v154 offset:1024
	ds_read_b128 v[202:205], v154 offset:2048
	ds_read_b128 v[206:209], v154 offset:3072
	ds_read_b128 v[210:213], v154 offset:4096
	ds_read_b128 v[214:217], v154 offset:5120
	ds_read_b128 v[218:221], v154 offset:6144
	ds_read_b128 v[222:225], v154 offset:7168
	global_load_lds_dwordx4 v[226:227], off
	v_lshl_add_u64 v[226:227], s[40:41], 0, v[144:145]
	s_add_i32 m0, s8, 0xe000
	s_nop 0
	global_load_lds_dwordx4 v[226:227], off
	s_waitcnt vmcnt(8)
	s_waitcnt lgkmcnt(0)
	s_setprio 1
	s_barrier
	v_mfma_f32_16x16x32_bf16 v[124:127], v[156:159], v[194:197], 0
	v_mfma_f32_16x16x32_bf16 v[120:123], v[164:167], v[194:197], 0
	v_mfma_f32_16x16x32_bf16 v[108:111], v[156:159], v[202:205], 0
	v_mfma_f32_16x16x32_bf16 v[104:107], v[164:167], v[202:205], 0
	v_mfma_f32_16x16x32_bf16 v[92:95], v[156:159], v[210:213], 0
	v_mfma_f32_16x16x32_bf16 v[88:91], v[164:167], v[210:213], 0
	v_mfma_f32_16x16x32_bf16 v[76:79], v[156:159], v[218:221], 0
	v_mfma_f32_16x16x32_bf16 v[72:75], v[164:167], v[218:221], 0
	v_mfma_f32_16x16x32_bf16 v[124:127], v[160:163], v[198:201], v[124:127]
	v_mfma_f32_16x16x32_bf16 v[120:123], v[168:171], v[198:201], v[120:123]
	v_mfma_f32_16x16x32_bf16 v[108:111], v[160:163], v[206:209], v[108:111]
	v_mfma_f32_16x16x32_bf16 v[104:107], v[168:171], v[206:209], v[104:107]
	v_mfma_f32_16x16x32_bf16 v[92:95], v[160:163], v[214:217], v[92:95]
	v_mfma_f32_16x16x32_bf16 v[88:91], v[168:171], v[214:217], v[88:91]
	v_mfma_f32_16x16x32_bf16 v[76:79], v[160:163], v[222:225], v[76:79]
	v_mfma_f32_16x16x32_bf16 v[72:75], v[168:171], v[222:225], v[72:75]
	s_setprio 0
	s_setprio 1
	v_mfma_f32_16x16x32_bf16 v[116:119], v[172:175], v[194:197], 0
	v_mfma_f32_16x16x32_bf16 v[112:115], v[180:183], v[194:197], 0
	v_mfma_f32_16x16x32_bf16 v[100:103], v[172:175], v[202:205], 0
	v_mfma_f32_16x16x32_bf16 v[96:99], v[180:183], v[202:205], 0
	v_mfma_f32_16x16x32_bf16 v[84:87], v[172:175], v[210:213], 0
	v_mfma_f32_16x16x32_bf16 v[80:83], v[180:183], v[210:213], 0
	v_mfma_f32_16x16x32_bf16 v[68:71], v[172:175], v[218:221], 0
	v_mfma_f32_16x16x32_bf16 v[64:67], v[180:183], v[218:221], 0
	v_mfma_f32_16x16x32_bf16 v[116:119], v[176:179], v[198:201], v[116:119]
	v_mfma_f32_16x16x32_bf16 v[112:115], v[190:193], v[198:201], v[112:115]
	v_mfma_f32_16x16x32_bf16 v[100:103], v[176:179], v[206:209], v[100:103]
	v_mfma_f32_16x16x32_bf16 v[96:99], v[190:193], v[206:209], v[96:99]
	v_mfma_f32_16x16x32_bf16 v[84:87], v[176:179], v[214:217], v[84:87]
	v_mfma_f32_16x16x32_bf16 v[80:83], v[190:193], v[214:217], v[80:83]
	v_mfma_f32_16x16x32_bf16 v[68:71], v[176:179], v[222:225], v[68:71]
	v_mfma_f32_16x16x32_bf16 v[64:67], v[190:193], v[222:225], v[64:67]
	s_barrier
	s_setprio 0
	s_add_i32 s53, s50, s7
	v_lshl_add_u64 v[226:227], s[42:43], 0, v[130:131]
	s_mov_b32 m0, s53
	ds_read_b128 v[194:197], v154 offset:16384
	ds_read_b128 v[198:201], v154 offset:17408
	ds_read_b128 v[202:205], v154 offset:18432
	ds_read_b128 v[206:209], v154 offset:19456
	ds_read_b128 v[210:213], v154 offset:20480
	ds_read_b128 v[214:217], v154 offset:21504
	ds_read_b128 v[218:221], v154 offset:22528
	ds_read_b128 v[222:225], v154 offset:23552
	global_load_lds_dwordx4 v[226:227], off
	s_add_i32 m0, s53, 0x2000
	s_add_u32 s54, s42, 0x80000
	v_lshl_add_u64 v[228:229], s[42:43], 0, v[134:135]
	s_addc_u32 s55, s43, 0
	s_add_i32 s53, s51, s7
	global_load_lds_dwordx4 v[228:229], off
	v_lshl_add_u64 v[230:231], s[54:55], 0, v[130:131]
	s_mov_b32 m0, s53
	v_lshl_add_u64 v[232:233], s[44:45], 0, v[132:133]
	global_load_lds_dwordx4 v[230:231], off
	v_lshl_add_u64 v[230:231], s[54:55], 0, v[134:135]
	s_add_i32 m0, s53, 0x2000
	s_nop 0
	global_load_lds_dwordx4 v[230:231], off
	v_lshl_add_u64 v[230:231], s[44:45], 0, v[128:129]
	s_mov_b32 m0, s8
	s_nop 0
	global_load_lds_dwordx4 v[230:231], off
	s_mov_b32 m0, s9
	s_nop 0
	global_load_lds_dwordx4 v[232:233], off
	s_waitcnt vmcnt(8)
	s_waitcnt lgkmcnt(0)
	s_setprio 1
	s_barrier
; #define PG8_STAGE(bufoff, gbase, voff) do { _Pragma("unroll") for (int _i = 0; _i < 2; ++_i) \
;         __builtin_amdgcn_global_load_lds((const unsigned*)((const char*)(gbase) + (voff)[_i]), (PG8_LAS unsigned*)(lds + (bufoff) + ldsw + _i * 8192), 16, 0, 0); } while (0)
; #define PG8_LDA(dst, b, h) do { _Pragma("unroll") for (int m = 0; m < 4; ++m) _Pragma("unroll") for (int k = 0; k < 2; ++k) dst[m][k] = *(const PG8_LAS bf16x8*)(lds + PG8_SA(b, h) + aoff + m * 2048 + k * 1024); } while (0)
; #define PG8_LDB(dst, b, h) do { _Pragma("unroll") for (int n = 0; n < 2; ++n) _Pragma("unroll") for (int k = 0; k < 2; ++k) dst[n][k] = *(const PG8_LAS bf16x8*)(lds + PG8_SB(b, h) + boff + n * 2048 + k * 1024); } while (0)
; #define PG8_MMA(ai, bj, At, Bt) do { __builtin_amdgcn_s_setprio(1); _Pragma("unroll") for (int m = 0; m < 4; ++m) _Pragma("unroll") for (int n = 0; n < 2; ++n) _Pragma("unroll") for (int k = 0; k < 2; ++k) \
;         acc[ai][bj][m][n] = __builtin_amdgcn_mfma_f32_16x16x32_bf16(Bt[n][k], At[m][k], acc[ai][bj][m][n], 0, 0, 0); __builtin_amdgcn_s_setprio(0); } while (0)
; #define PG8_WAIT_V(n) asm volatile("s_waitcnt vmcnt(" #n ")" ::: "memory")
; #define PG8_WAIT_L(n) asm volatile("s_waitcnt lgkmcnt(" #n ")" ::: "memory")
; #define PG8_BAR __builtin_amdgcn_s_barrier()
; #define PG8_SCHED __builtin_amdgcn_sched_barrier(0)
; template <class Epi, class Sched, bool ALIGN_EPI = false, bool SP2 = false>
; __device__ __forceinline__ void gemm_phase(PG8_LAS unsigned char* lds, const Gemm g, const Sched& S, const Epi& E) {
;     ...
;             PG8_WAIT_V(8); PG8_WAIT_L(0); PG8_BAR; PG8_MMA(1, 0, At, B0); PG8_MMA(1, 1, At, B1); PG8_BAR; PG8_SCHED;
;             PG8_LDB(B0, 1, 0); PG8_LDB(B1, 1, 1); PG8_SCHED; PG8_LDA(At, 1, 0); PG8_STAGE(PG8_SA(0, 1), a2 + hstepA, voffA);
;             PG8_WAIT_V(8); PG8_WAIT_L(0); PG8_BAR; PG8_MMA(0, 0, At, B0); PG8_MMA(0, 1, At, B1); PG8_BAR; PG8_SCHED;
	v_mfma_f32_16x16x32_bf16 v[60:63], v[156:159], v[194:197], 0
	v_mfma_f32_16x16x32_bf16 v[56:59], v[164:167], v[194:197], 0
	v_mfma_f32_16x16x32_bf16 v[44:47], v[156:159], v[202:205], 0
	v_mfma_f32_16x16x32_bf16 v[40:43], v[164:167], v[202:205], 0
	v_mfma_f32_16x16x32_bf16 v[28:31], v[156:159], v[210:213], 0
	v_mfma_f32_16x16x32_bf16 v[24:27], v[164:167], v[210:213], 0
	v_mfma_f32_16x16x32_bf16 v[12:15], v[156:159], v[218:221], 0
	v_mfma_f32_16x16x32_bf16 v[8:11], v[164:167], v[218:221], 0
	v_mfma_f32_16x16x32_bf16 v[60:63], v[160:163], v[198:201], v[60:63]
	v_mfma_f32_16x16x32_bf16 v[56:59], v[168:171], v[198:201], v[56:59]
	v_mfma_f32_16x16x32_bf16 v[44:47], v[160:163], v[206:209], v[44:47]
	v_mfma_f32_16x16x32_bf16 v[40:43], v[168:171], v[206:209], v[40:43]
	v_mfma_f32_16x16x32_bf16 v[28:31], v[160:163], v[214:217], v[28:31]
	v_mfma_f32_16x16x32_bf16 v[24:27], v[168:171], v[214:217], v[24:27]
	v_mfma_f32_16x16x32_bf16 v[12:15], v[160:163], v[222:225], v[12:15]
	v_mfma_f32_16x16x32_bf16 v[8:11], v[168:171], v[222:225], v[8:11]
	s_setprio 0
	s_setprio 1
	v_mfma_f32_16x16x32_bf16 v[52:55], v[172:175], v[194:197], 0
	v_mfma_f32_16x16x32_bf16 v[48:51], v[180:183], v[194:197], 0
	v_mfma_f32_16x16x32_bf16 v[36:39], v[172:175], v[202:205], 0
	v_mfma_f32_16x16x32_bf16 v[32:35], v[180:183], v[202:205], 0
	v_mfma_f32_16x16x32_bf16 v[20:23], v[172:175], v[210:213], 0
	v_mfma_f32_16x16x32_bf16 v[16:19], v[180:183], v[210:213], 0
	v_mfma_f32_16x16x32_bf16 v[4:7], v[172:175], v[218:221], 0
	v_mfma_f32_16x16x32_bf16 v[0:3], v[180:183], v[218:221], 0
	v_mfma_f32_16x16x32_bf16 v[52:55], v[176:179], v[198:201], v[52:55]
	v_mfma_f32_16x16x32_bf16 v[48:51], v[190:193], v[198:201], v[48:51]
	v_mfma_f32_16x16x32_bf16 v[36:39], v[176:179], v[206:209], v[36:39]
	v_mfma_f32_16x16x32_bf16 v[32:35], v[190:193], v[206:209], v[32:35]
	v_mfma_f32_16x16x32_bf16 v[20:23], v[176:179], v[214:217], v[20:23]
	v_mfma_f32_16x16x32_bf16 v[16:19], v[190:193], v[214:217], v[16:19]
	v_mfma_f32_16x16x32_bf16 v[4:7], v[176:179], v[222:225], v[4:7]
	v_mfma_f32_16x16x32_bf16 v[0:3], v[190:193], v[222:225], v[0:3]
	s_barrier
	s_setprio 0
	s_add_i32 s53, 0, 0x18000
	v_add_u32_e32 v155, s53, v150
	s_add_i32 s54, 0, 0x1c000
	ds_read_b128 v[156:159], v155
	ds_read_b128 v[160:163], v155 offset:1024
	ds_read_b128 v[164:167], v155 offset:2048
	ds_read_b128 v[168:171], v155 offset:3072
	v_add_u32_e32 v155, s54, v150
	ds_read_b128 v[172:175], v155
	ds_read_b128 v[176:179], v155 offset:1024
	ds_read_b128 v[180:183], v155 offset:2048
	ds_read_b128 v[190:193], v155 offset:3072
	s_add_u32 s44, s44, 0x80000
	s_addc_u32 s45, s45, 0
	s_mov_b32 m0, s10
	v_lshl_add_u64 v[234:235], s[44:45], 0, v[128:129]
	ds_read_b128 v[194:197], v154 offset:32768
	ds_read_b128 v[198:201], v154 offset:33792
	ds_read_b128 v[202:205], v154 offset:34816
	ds_read_b128 v[206:209], v154 offset:35840
	ds_read_b128 v[210:213], v154 offset:36864
	ds_read_b128 v[214:217], v154 offset:37888
	ds_read_b128 v[218:221], v154 offset:38912
	ds_read_b128 v[222:225], v154 offset:39936
	global_load_lds_dwordx4 v[234:235], off
	v_lshl_add_u64 v[234:235], s[44:45], 0, v[132:133]
	s_mov_b32 m0, s11
	s_nop 0
	global_load_lds_dwordx4 v[234:235], off
	s_waitcnt vmcnt(8)
	s_waitcnt lgkmcnt(0)
	s_setprio 1
	s_barrier
	v_mfma_f32_16x16x32_bf16 v[124:127], v[156:159], v[194:197], v[124:127]
	v_mfma_f32_16x16x32_bf16 v[120:123], v[164:167], v[194:197], v[120:123]
	v_mfma_f32_16x16x32_bf16 v[108:111], v[156:159], v[202:205], v[108:111]
	v_mfma_f32_16x16x32_bf16 v[104:107], v[164:167], v[202:205], v[104:107]
	v_mfma_f32_16x16x32_bf16 v[92:95], v[156:159], v[210:213], v[92:95]
	v_mfma_f32_16x16x32_bf16 v[88:91], v[164:167], v[210:213], v[88:91]
	v_mfma_f32_16x16x32_bf16 v[76:79], v[156:159], v[218:221], v[76:79]
	v_mfma_f32_16x16x32_bf16 v[72:75], v[164:167], v[218:221], v[72:75]
	v_mfma_f32_16x16x32_bf16 v[124:127], v[160:163], v[198:201], v[124:127]
	v_mfma_f32_16x16x32_bf16 v[120:123], v[168:171], v[198:201], v[120:123]
	v_mfma_f32_16x16x32_bf16 v[108:111], v[160:163], v[206:209], v[108:111]
	v_mfma_f32_16x16x32_bf16 v[104:107], v[168:171], v[206:209], v[104:107]
	v_mfma_f32_16x16x32_bf16 v[92:95], v[160:163], v[214:217], v[92:95]
	v_mfma_f32_16x16x32_bf16 v[88:91], v[168:171], v[214:217], v[88:91]
	v_mfma_f32_16x16x32_bf16 v[76:79], v[160:163], v[222:225], v[76:79]
	v_mfma_f32_16x16x32_bf16 v[72:75], v[168:171], v[222:225], v[72:75]
	s_setprio 0
	s_setprio 1
	v_mfma_f32_16x16x32_bf16 v[116:119], v[172:175], v[194:197], v[116:119]
	v_mfma_f32_16x16x32_bf16 v[112:115], v[180:183], v[194:197], v[112:115]
	v_mfma_f32_16x16x32_bf16 v[100:103], v[172:175], v[202:205], v[100:103]
	v_mfma_f32_16x16x32_bf16 v[96:99], v[180:183], v[202:205], v[96:99]
	v_mfma_f32_16x16x32_bf16 v[84:87], v[172:175], v[210:213], v[84:87]
	v_mfma_f32_16x16x32_bf16 v[80:83], v[180:183], v[210:213], v[80:83]
	v_mfma_f32_16x16x32_bf16 v[68:71], v[172:175], v[218:221], v[68:71]
	v_mfma_f32_16x16x32_bf16 v[64:67], v[180:183], v[218:221], v[64:67]
	v_mfma_f32_16x16x32_bf16 v[116:119], v[176:179], v[198:201], v[116:119]
	v_mfma_f32_16x16x32_bf16 v[112:115], v[190:193], v[198:201], v[112:115]
	v_mfma_f32_16x16x32_bf16 v[100:103], v[176:179], v[206:209], v[100:103]
	v_mfma_f32_16x16x32_bf16 v[96:99], v[190:193], v[206:209], v[96:99]
	v_mfma_f32_16x16x32_bf16 v[84:87], v[176:179], v[214:217], v[84:87]
	v_mfma_f32_16x16x32_bf16 v[80:83], v[190:193], v[214:217], v[80:83]
	v_mfma_f32_16x16x32_bf16 v[68:71], v[176:179], v[222:225], v[68:71]
	v_mfma_f32_16x16x32_bf16 v[64:67], v[190:193], v[222:225], v[64:67]
	s_barrier
; #define PG8_STAGE(bufoff, gbase, voff) do { _Pragma("unroll") for (int _i = 0; _i < 2; ++_i) \
;         __builtin_amdgcn_global_load_lds((const unsigned*)((const char*)(gbase) + (voff)[_i]), (PG8_LAS unsigned*)(lds + (bufoff) + ldsw + _i * 8192), 16, 0, 0); } while (0)
; #define PG8_LDA(dst, b, h) do { _Pragma("unroll") for (int m = 0; m < 4; ++m) _Pragma("unroll") for (int k = 0; k < 2; ++k) dst[m][k] = *(const PG8_LAS bf16x8*)(lds + PG8_SA(b, h) + aoff + m * 2048 + k * 1024); } while (0)
; #define PG8_MMA(ai, bj, At, Bt) do { __builtin_amdgcn_s_setprio(1); _Pragma("unroll") for (int m = 0; m < 4; ++m) _Pragma("unroll") for (int n = 0; n < 2; ++n) _Pragma("unroll") for (int k = 0; k < 2; ++k) \
;         acc[ai][bj][m][n] = __builtin_amdgcn_mfma_f32_16x16x32_bf16(Bt[n][k], At[m][k], acc[ai][bj][m][n], 0, 0, 0); __builtin_amdgcn_s_setprio(0); } while (0)
; #define PG8_WAIT_V(n) asm volatile("s_waitcnt vmcnt(" #n ")" ::: "memory")
; #define PG8_WAIT_L(n) asm volatile("s_waitcnt lgkmcnt(" #n ")" ::: "memory")
; #define PG8_BAR __builtin_amdgcn_s_barrier()
; #define PG8_SCHED __builtin_amdgcn_sched_barrier(0)
; template <class Epi, class Sched, bool ALIGN_EPI = false, bool SP2 = false>
; __device__ __forceinline__ void gemm_phase(PG8_LAS unsigned char* lds, const Gemm g, const Sched& S, const Epi& E) {
;     ...
;             PG8_LDA(At, 1, 1); PG8_STAGE(PG8_SB(1, 0), b3, voffB); PG8_STAGE(PG8_SB(1, 1), b3 + hstepB, voffB); PG8_STAGE(PG8_SA(1, 0), a3, voffA);
;             PG8_WAIT_V(8); PG8_WAIT_L(0); PG8_BAR; PG8_MMA(1, 0, At, B0); PG8_MMA(1, 1, At, B1); PG8_BAR; PG8_SCHED;
	s_setprio 0
	s_add_i32 s44, s53, s7
	v_lshl_add_u64 v[226:227], v[226:227], 0, s[16:17]
	s_mov_b32 m0, s44
	ds_read_b128 v[194:197], v154 offset:49152
	ds_read_b128 v[198:201], v154 offset:50176
	ds_read_b128 v[202:205], v154 offset:51200
	ds_read_b128 v[206:209], v154 offset:52224
	ds_read_b128 v[210:213], v154 offset:53248
	ds_read_b128 v[214:217], v154 offset:54272
	ds_read_b128 v[218:221], v154 offset:55296
	ds_read_b128 v[222:225], v154 offset:56320
	global_load_lds_dwordx4 v[226:227], off
	s_add_i32 m0, s44, 0x2000
	s_add_u32 s42, s42, 0x80080
	v_lshl_add_u64 v[226:227], v[228:229], 0, s[16:17]
	s_addc_u32 s43, s43, 0
	s_add_i32 s44, s54, s7
	global_load_lds_dwordx4 v[226:227], off
	v_lshl_add_u64 v[226:227], s[42:43], 0, v[130:131]
	s_mov_b32 m0, s44
	s_nop 0
	global_load_lds_dwordx4 v[226:227], off
	v_lshl_add_u64 v[226:227], s[42:43], 0, v[134:135]
	s_add_i32 m0, s44, 0x2000
	s_nop 0
	global_load_lds_dwordx4 v[226:227], off
	v_lshl_add_u64 v[226:227], v[230:231], 0, s[16:17]
	s_mov_b32 m0, s48
	s_nop 0
	global_load_lds_dwordx4 v[226:227], off
	v_lshl_add_u64 v[226:227], v[232:233], 0, s[16:17]
	s_mov_b32 m0, s49
	s_nop 0
	global_load_lds_dwordx4 v[226:227], off
	s_waitcnt vmcnt(8)
	s_waitcnt lgkmcnt(0)
	s_setprio 1
	s_barrier
	v_mfma_f32_16x16x32_bf16 v[60:63], v[156:159], v[194:197], v[60:63]
	v_mfma_f32_16x16x32_bf16 v[56:59], v[164:167], v[194:197], v[56:59]
	v_mfma_f32_16x16x32_bf16 v[44:47], v[156:159], v[202:205], v[44:47]
	v_mfma_f32_16x16x32_bf16 v[40:43], v[164:167], v[202:205], v[40:43]
	v_mfma_f32_16x16x32_bf16 v[28:31], v[156:159], v[210:213], v[28:31]
	v_mfma_f32_16x16x32_bf16 v[24:27], v[164:167], v[210:213], v[24:27]
	v_mfma_f32_16x16x32_bf16 v[12:15], v[156:159], v[218:221], v[12:15]
	v_mfma_f32_16x16x32_bf16 v[8:11], v[164:167], v[218:221], v[8:11]
	v_mfma_f32_16x16x32_bf16 v[60:63], v[160:163], v[198:201], v[60:63]
	v_mfma_f32_16x16x32_bf16 v[56:59], v[168:171], v[198:201], v[56:59]
	v_mfma_f32_16x16x32_bf16 v[44:47], v[160:163], v[206:209], v[44:47]
	v_mfma_f32_16x16x32_bf16 v[40:43], v[168:171], v[206:209], v[40:43]
	v_mfma_f32_16x16x32_bf16 v[28:31], v[160:163], v[214:217], v[28:31]
	v_mfma_f32_16x16x32_bf16 v[24:27], v[168:171], v[214:217], v[24:27]
	v_mfma_f32_16x16x32_bf16 v[12:15], v[160:163], v[222:225], v[12:15]
	v_mfma_f32_16x16x32_bf16 v[8:11], v[168:171], v[222:225], v[8:11]
	s_setprio 0
	s_setprio 1
	v_mfma_f32_16x16x32_bf16 v[52:55], v[172:175], v[194:197], v[52:55]
	v_mfma_f32_16x16x32_bf16 v[48:51], v[180:183], v[194:197], v[48:51]
	v_mfma_f32_16x16x32_bf16 v[36:39], v[172:175], v[202:205], v[36:39]
	v_mfma_f32_16x16x32_bf16 v[32:35], v[180:183], v[202:205], v[32:35]
	v_mfma_f32_16x16x32_bf16 v[20:23], v[172:175], v[210:213], v[20:23]
	v_mfma_f32_16x16x32_bf16 v[16:19], v[180:183], v[210:213], v[16:19]
	v_mfma_f32_16x16x32_bf16 v[4:7], v[172:175], v[218:221], v[4:7]
	v_mfma_f32_16x16x32_bf16 v[0:3], v[180:183], v[218:221], v[0:3]
	v_mfma_f32_16x16x32_bf16 v[52:55], v[176:179], v[198:201], v[52:55]
	v_mfma_f32_16x16x32_bf16 v[48:51], v[190:193], v[198:201], v[48:51]
	v_mfma_f32_16x16x32_bf16 v[36:39], v[176:179], v[206:209], v[36:39]
	v_mfma_f32_16x16x32_bf16 v[32:35], v[190:193], v[206:209], v[32:35]
	v_mfma_f32_16x16x32_bf16 v[20:23], v[176:179], v[214:217], v[20:23]
	v_mfma_f32_16x16x32_bf16 v[16:19], v[190:193], v[214:217], v[16:19]
	v_mfma_f32_16x16x32_bf16 v[4:7], v[176:179], v[222:225], v[4:7]
	v_mfma_f32_16x16x32_bf16 v[0:3], v[190:193], v[222:225], v[0:3]
	s_barrier
	s_setprio 0
	s_add_i32 s35, s35, 2
	s_add_u32 s40, s40, 0x100
	s_addc_u32 s41, s41, 0
	s_add_u32 s21, s21, 0x100
	s_addc_u32 s23, s23, 0
	s_cmp_gt_u32 s35, 29
	s_cbranch_scc1 .Lmy_peel_11_exit

; #define PG8_BAR __builtin_amdgcn_s_barrier()
; template <class Epi, class Sched, bool ALIGN_EPI = false, bool SP2 = false>
; __device__ __forceinline__ void gemm_phase(PG8_LAS unsigned char* lds, const Gemm g, const Sched& S, const Epi& E) {
;     ...
;         if constexpr (ALIGN_EPI) { if (wr == 0) PG8_BAR; }
.Lmy_peel_11_exit:
	s_and_b64 vcc, exec, s[18:19]
	s_cbranch_vccz .LBB0_3061
	s_barrier
